# v72 plus nt hint on the pool phase's A_g stores
# baseline (speedup 1.0000x reference)
; __device__ __forceinline__ f32x2 ldx2(const bf16_t* p) { const unsigned w = *(const unsigned*)p; return (f32x2){__builtin_bit_cast(float, w << 16), __builtin_bit_cast(float, w & 0xffff0000u)}; }
; template <int W> __device__ __forceinline__ void pool_unit(const bf16_t* x, const LAS float* rs, f32x2 gn, bf16_t* Ag, size_t rb, int t0, int c, int g) {
;     ...
;     for (int bt = 0; bt < 4; ++bt) {
; #pragma unroll
;         for (int i = 0; i < 16; ++i) hn_[i] = ldx2(x + (rb + t0 + bt * 16 + i) * 1024 + c) * rs[16 + bt * 16 + i] * gn;
; #pragma unroll
.LBB0_1171:
	s_or_b32 s38, s16, s48
	s_mov_b32 s39, s49
	s_lshl_b64 s[50:51], s[38:39], 11
	v_lshl_add_u64 v[14:15], v[6:7], 0, s[50:51]
	s_movk_i32 s45, 0x1000
	v_add_co_u32_e32 v16, vcc, s45, v14
	global_load_dword v5, v[14:15], off
	global_load_dword v39, v[14:15], off offset:2048
	v_addc_co_u32_e32 v17, vcc, 0, v15, vcc
	v_add_co_u32_e32 v18, vcc, s23, v14
	s_movk_i32 s45, 0x3000
	s_nop 0
	v_addc_co_u32_e32 v19, vcc, 0, v15, vcc
	global_load_dword v44, v[18:19], off offset:-4096
	global_load_dword v45, v[16:17], off offset:2048
	v_add_co_u32_e32 v16, vcc, s31, v14
	v_pk_add_f32 v[36:37], v[20:21], 0 op_sel_hi:[1,0]
	s_nop 0
	v_addc_co_u32_e32 v17, vcc, 0, v15, vcc
	global_load_dword v47, v[18:19], off
	global_load_dword v49, v[18:19], off offset:2048
	global_load_dword v51, v[16:17], off offset:-4096
	v_add_co_u32_e32 v18, vcc, s45, v14
	s_movk_i32 s45, 0x5000
	s_nop 0
	v_addc_co_u32_e32 v19, vcc, 0, v15, vcc
	global_load_dword v53, v[18:19], off offset:2048
	global_load_dword v66, v[16:17], off
	global_load_dword v70, v[16:17], off offset:2048
	v_add_co_u32_e32 v16, vcc, s33, v14
	s_waitcnt vmcnt(9)
	v_lshlrev_b32_e32 v40, 16, v5
	v_addc_co_u32_e32 v17, vcc, 0, v15, vcc
	v_add_co_u32_e32 v18, vcc, s45, v14
	global_load_dword v72, v[16:17], off offset:-4096
	s_nop 0
	v_addc_co_u32_e32 v19, vcc, 0, v15, vcc
	v_add_co_u32_e32 v22, vcc, s19, v14
	s_movk_i32 s45, 0x7000
	s_nop 0
	v_addc_co_u32_e32 v23, vcc, 0, v15, vcc
	global_load_dword v76, v[18:19], off offset:2048
	global_load_dword v78, v[16:17], off
	global_load_dword v82, v[16:17], off offset:2048
	v_add_co_u32_e32 v16, vcc, s45, v14
	global_load_dword v84, v[22:23], off offset:-4096
	s_nop 0
	v_addc_co_u32_e32 v17, vcc, 0, v15, vcc
	global_load_dword v86, v[16:17], off offset:2048
	ds_read_b128 v[16:19], v175 offset:64
	ds_read_b128 v[24:27], v175 offset:80
	ds_read_b128 v[28:31], v175 offset:96
	ds_read_b128 v[32:35], v175 offset:112
	v_and_b32_e32 v41, 0xffff0000, v5
	s_waitcnt vmcnt(14)
	v_lshlrev_b32_e32 v42, 16, v39
	v_and_b32_e32 v43, 0xffff0000, v39
	s_waitcnt lgkmcnt(3)
	v_pk_mul_f32 v[40:41], v[16:17], v[40:41] op_sel_hi:[0,1]
	v_pk_mul_f32 v[42:43], v[16:17], v[42:43] op_sel:[1,0]
	s_waitcnt vmcnt(13)
	v_lshlrev_b32_e32 v16, 16, v44
	v_and_b32_e32 v17, 0xffff0000, v44
	v_mov_b32_e32 v38, v19
	s_waitcnt vmcnt(12)
	v_lshlrev_b32_e32 v44, 16, v45
	v_and_b32_e32 v45, 0xffff0000, v45
	s_waitcnt vmcnt(11)
	v_lshlrev_b32_e32 v46, 16, v47
	v_and_b32_e32 v47, 0xffff0000, v47
	s_waitcnt vmcnt(9)
	v_lshlrev_b32_e32 v50, 16, v51
	v_and_b32_e32 v51, 0xffff0000, v51
	s_waitcnt vmcnt(8)
	v_lshlrev_b32_e32 v52, 16, v53
	v_pk_mul_f32 v[58:59], v[18:19], v[16:17] op_sel_hi:[0,1]
	v_and_b32_e32 v53, 0xffff0000, v53
	s_waitcnt lgkmcnt(2)
	v_mov_b32_e32 v16, v27
	v_pk_mul_f32 v[38:39], v[38:39], v[44:45] op_sel_hi:[0,1]
	v_pk_mul_f32 v[44:45], v[24:25], v[46:47] op_sel_hi:[0,1]
	v_pk_mul_f32 v[46:47], v[26:27], v[50:51] op_sel_hi:[0,1]
	v_pk_mul_f32 v[26:27], v[16:17], v[52:53] op_sel_hi:[0,1]
	s_waitcnt vmcnt(7)
	v_lshlrev_b32_e32 v16, 16, v66
	v_and_b32_e32 v17, 0xffff0000, v66
	s_waitcnt lgkmcnt(1)
	v_pk_mul_f32 v[66:67], v[28:29], v[16:17] op_sel_hi:[0,1]
	s_waitcnt vmcnt(6)
	v_lshlrev_b32_e32 v16, 16, v70
	v_and_b32_e32 v17, 0xffff0000, v70
	v_pk_mul_f32 v[28:29], v[28:29], v[16:17] op_sel:[1,0]
	v_mov_b32_e32 v18, v31
	v_div_scale_f32 v5, s[50:51], s44, s44, 1.0
	v_pk_mul_f32 v[54:55], v[2:3], v[40:41]
	v_pk_fma_f32 v[36:37], v[2:3], v[40:41], v[36:37]
	v_pk_mul_f32 v[56:57], v[2:3], v[42:43]
	v_pk_add_f32 v[20:21], v[36:37], v[20:21] neg_lo:[0,1] neg_hi:[0,1]
	v_lshlrev_b32_e32 v48, 16, v49
	v_pk_fma_f32 v[20:21], v[2:3], v[42:43], v[20:21]
	v_and_b32_e32 v49, 0xffff0000, v49
	v_pk_mul_f32 v[24:25], v[24:25], v[48:49] op_sel:[1,0]
	v_pk_mul_f32 v[48:49], v[2:3], v[58:59]
	v_pk_mul_f32 v[50:51], v[2:3], v[38:39]
	v_pk_mul_f32 v[60:61], v[2:3], v[44:45]
	v_pk_mul_f32 v[62:63], v[2:3], v[24:25]
	v_pk_mul_f32 v[64:65], v[2:3], v[46:47]
	v_pk_mul_f32 v[52:53], v[2:3], v[26:27]
	v_pk_mul_f32 v[68:69], v[2:3], v[66:67]
	v_pk_mul_f32 v[70:71], v[2:3], v[28:29]
	s_waitcnt vmcnt(5)
	v_lshlrev_b32_e32 v16, 16, v72
	v_and_b32_e32 v17, 0xffff0000, v72
	v_pk_mul_f32 v[72:73], v[30:31], v[16:17] op_sel_hi:[0,1]
	v_pk_mul_f32 v[74:75], v[2:3], v[72:73]
	s_waitcnt vmcnt(4)
	v_lshlrev_b32_e32 v16, 16, v76
	v_and_b32_e32 v17, 0xffff0000, v76
	v_pk_mul_f32 v[30:31], v[18:19], v[16:17] op_sel_hi:[0,1]
	s_waitcnt vmcnt(3)
	v_lshlrev_b32_e32 v16, 16, v78
	v_and_b32_e32 v17, 0xffff0000, v78
	s_waitcnt lgkmcnt(0)
	v_pk_mul_f32 v[78:79], v[32:33], v[16:17] op_sel_hi:[0,1]
	s_waitcnt vmcnt(2)
	v_lshlrev_b32_e32 v16, 16, v82
	v_and_b32_e32 v17, 0xffff0000, v82
	v_pk_mul_f32 v[32:33], v[32:33], v[16:17] op_sel:[1,0]
	s_waitcnt vmcnt(1)
	v_lshlrev_b32_e32 v16, 16, v84
	v_and_b32_e32 v17, 0xffff0000, v84
	v_pk_mul_f32 v[18:19], v[34:35], v[16:17] op_sel_hi:[0,1]
	s_waitcnt vmcnt(0)
; __device__ __forceinline__ unsigned pk2(float lo, float hi) { f32x2 v = {lo, hi}; bf16x2_t b = __builtin_convertvector(v, bf16x2_t); return __builtin_bit_cast(unsigned, b); }
; template <int W> __device__ __forceinline__ void pool_unit(const bf16_t* x, const LAS float* rs, f32x2 gn, bf16_t* Ag, size_t rb, int t0, int c, int g) {
;     ...
;         for (int i = 0; i < 16; ++i) { const int t = t0 + bt * 16 + i;
;             win += hn_[i]; const float inv = 1.f / (float)((t + 1) < W ? (t + 1) : W);
;             const f32x2 a = win * inv - hn_[i];
;             *(unsigned*)(Ag + ((size_t)g * MT + rb + t) * 256 + (c & 255)) = pk2(a.x, a.y);
;             win -= (i - W + 1 >= 0) ? hn_[(i - W + 1 >= 0) ? (i - W + 1) : 0] : ring[(i - W + 17) & 15]; }
	v_lshlrev_b32_e32 v16, 16, v86
	v_and_b32_e32 v17, 0xffff0000, v86
	v_rcp_f32_e32 v86, v5
	v_pk_mul_f32 v[76:77], v[2:3], v[30:31]
	v_pk_mul_f32 v[80:81], v[2:3], v[78:79]
	v_pk_mul_f32 v[82:83], v[2:3], v[32:33]
	v_fma_f32 v87, -v5, v86, 1.0
	v_fmac_f32_e32 v86, v87, v86
	v_div_scale_f32 v87, vcc, 1.0, s44, 1.0
	v_mul_f32_e32 v88, v87, v86
	v_fma_f32 v89, -v5, v88, v87
	v_fmac_f32_e32 v88, v89, v86
	v_fma_f32 v5, -v5, v88, v87
	v_div_fmas_f32 v5, v5, v86, v88
	v_div_fixup_f32 v86, v5, s44, 1.0
	v_pk_fma_f32 v[54:55], v[86:87], v[36:37], v[54:55] op_sel_hi:[0,1,1] neg_lo:[0,0,1] neg_hi:[0,0,1]
	s_lshl_b64 s[44:45], s[38:39], 9
	v_cvt_pk_bf16_f32 v5, v54, v55
	v_lshl_add_u64 v[54:55], v[12:13], 0, s[44:45]
	s_or_b32 s44, s38, 1
	s_mov_b32 s45, s49
	v_pk_fma_f32 v[36:37], v[20:21], 0.5, v[56:57] op_sel_hi:[1,0,1] neg_lo:[0,0,1] neg_hi:[0,0,1]
	s_lshl_b64 s[44:45], s[44:45], 9
	v_pk_fma_f32 v[20:21], v[2:3], v[40:41], v[20:21] neg_lo:[1,0,0] neg_hi:[1,0,0]
	global_store_dword v[54:55], v5, off nt
	v_cvt_pk_bf16_f32 v5, v36, v37
	v_lshl_add_u64 v[36:37], v[12:13], 0, s[44:45]
	v_pk_fma_f32 v[20:21], v[2:3], v[58:59], v[20:21]
	s_or_b32 s44, s38, 2
	s_mov_b32 s45, s49
	global_store_dword v[36:37], v5, off nt
	v_pk_fma_f32 v[36:37], v[20:21], 0.5, v[48:49] op_sel_hi:[1,0,1] neg_lo:[0,0,1] neg_hi:[0,0,1]
	s_lshl_b64 s[44:45], s[44:45], 9
	v_pk_fma_f32 v[20:21], v[2:3], v[42:43], v[20:21] neg_lo:[1,0,0] neg_hi:[1,0,0]
	v_cvt_pk_bf16_f32 v5, v36, v37
	v_lshl_add_u64 v[36:37], v[12:13], 0, s[44:45]
	v_pk_fma_f32 v[20:21], v[2:3], v[38:39], v[20:21]
	s_or_b32 s44, s38, 3
	s_mov_b32 s45, s49
	global_store_dword v[36:37], v5, off nt
	v_pk_fma_f32 v[36:37], v[20:21], 0.5, v[50:51] op_sel_hi:[1,0,1] neg_lo:[0,0,1] neg_hi:[0,0,1]
	s_lshl_b64 s[44:45], s[44:45], 9
	v_pk_fma_f32 v[20:21], v[2:3], v[58:59], v[20:21] neg_lo:[1,0,0] neg_hi:[1,0,0]
	v_cvt_pk_bf16_f32 v5, v36, v37
	v_lshl_add_u64 v[36:37], v[12:13], 0, s[44:45]
	v_pk_fma_f32 v[20:21], v[2:3], v[44:45], v[20:21]
	s_or_b32 s44, s38, 4
	s_mov_b32 s45, s49
	global_store_dword v[36:37], v5, off nt
	v_pk_fma_f32 v[36:37], v[20:21], 0.5, v[60:61] op_sel_hi:[1,0,1] neg_lo:[0,0,1] neg_hi:[0,0,1]
	s_lshl_b64 s[44:45], s[44:45], 9
	v_pk_fma_f32 v[20:21], v[2:3], v[38:39], v[20:21] neg_lo:[1,0,0] neg_hi:[1,0,0]
	v_cvt_pk_bf16_f32 v5, v36, v37
	v_lshl_add_u64 v[36:37], v[12:13], 0, s[44:45]
	v_pk_fma_f32 v[20:21], v[2:3], v[24:25], v[20:21]
	s_or_b32 s44, s38, 5
	s_mov_b32 s45, s49
	global_store_dword v[36:37], v5, off nt
	v_pk_fma_f32 v[36:37], v[20:21], 0.5, v[62:63] op_sel_hi:[1,0,1] neg_lo:[0,0,1] neg_hi:[0,0,1]
	s_lshl_b64 s[44:45], s[44:45], 9
	v_pk_fma_f32 v[20:21], v[2:3], v[44:45], v[20:21] neg_lo:[1,0,0] neg_hi:[1,0,0]
	v_cvt_pk_bf16_f32 v5, v36, v37
	v_lshl_add_u64 v[36:37], v[12:13], 0, s[44:45]
	v_pk_fma_f32 v[20:21], v[2:3], v[46:47], v[20:21]
	s_or_b32 s44, s38, 6
	s_mov_b32 s45, s49
	global_store_dword v[36:37], v5, off nt
	v_pk_fma_f32 v[36:37], v[20:21], 0.5, v[64:65] op_sel_hi:[1,0,1] neg_lo:[0,0,1] neg_hi:[0,0,1]
	s_lshl_b64 s[44:45], s[44:45], 9
	v_pk_fma_f32 v[20:21], v[2:3], v[24:25], v[20:21] neg_lo:[1,0,0] neg_hi:[1,0,0]
	v_cvt_pk_bf16_f32 v5, v36, v37
	v_lshl_add_u64 v[36:37], v[12:13], 0, s[44:45]
	v_pk_fma_f32 v[20:21], v[2:3], v[26:27], v[20:21]
	s_or_b32 s44, s38, 7
	s_mov_b32 s45, s49
	v_pk_fma_f32 v[24:25], v[20:21], 0.5, v[52:53] op_sel_hi:[1,0,1] neg_lo:[0,0,1] neg_hi:[0,0,1]
	s_lshl_b64 s[44:45], s[44:45], 9
	v_pk_fma_f32 v[20:21], v[2:3], v[46:47], v[20:21] neg_lo:[1,0,0] neg_hi:[1,0,0]
	global_store_dword v[36:37], v5, off nt
	v_cvt_pk_bf16_f32 v5, v24, v25
	v_lshl_add_u64 v[24:25], v[12:13], 0, s[44:45]
	v_pk_fma_f32 v[20:21], v[2:3], v[66:67], v[20:21]
	s_or_b32 s44, s38, 8
	s_mov_b32 s45, s49
	global_store_dword v[24:25], v5, off nt
	v_pk_fma_f32 v[24:25], v[20:21], 0.5, v[68:69] op_sel_hi:[1,0,1] neg_lo:[0,0,1] neg_hi:[0,0,1]
	s_lshl_b64 s[44:45], s[44:45], 9
	v_pk_fma_f32 v[20:21], v[2:3], v[26:27], v[20:21] neg_lo:[1,0,0] neg_hi:[1,0,0]
	v_cvt_pk_bf16_f32 v5, v24, v25
	v_lshl_add_u64 v[24:25], v[12:13], 0, s[44:45]
	v_pk_fma_f32 v[20:21], v[2:3], v[28:29], v[20:21]
	s_or_b32 s44, s38, 9
	s_mov_b32 s45, s49
	global_store_dword v[24:25], v5, off nt
	v_pk_fma_f32 v[24:25], v[20:21], 0.5, v[70:71] op_sel_hi:[1,0,1] neg_lo:[0,0,1] neg_hi:[0,0,1]
	s_lshl_b64 s[44:45], s[44:45], 9
	v_pk_fma_f32 v[20:21], v[2:3], v[66:67], v[20:21] neg_lo:[1,0,0] neg_hi:[1,0,0]
	v_cvt_pk_bf16_f32 v5, v24, v25
	v_lshl_add_u64 v[24:25], v[12:13], 0, s[44:45]
	v_pk_fma_f32 v[20:21], v[2:3], v[72:73], v[20:21]
	s_or_b32 s44, s38, 10
	s_mov_b32 s45, s49
	global_store_dword v[24:25], v5, off nt
	v_pk_fma_f32 v[24:25], v[20:21], 0.5, v[74:75] op_sel_hi:[1,0,1] neg_lo:[0,0,1] neg_hi:[0,0,1]
	s_lshl_b64 s[44:45], s[44:45], 9
	v_pk_fma_f32 v[20:21], v[2:3], v[28:29], v[20:21] neg_lo:[1,0,0] neg_hi:[1,0,0]
	v_cvt_pk_bf16_f32 v5, v24, v25
	v_lshl_add_u64 v[24:25], v[12:13], 0, s[44:45]
	v_pk_fma_f32 v[20:21], v[2:3], v[30:31], v[20:21]
	s_or_b32 s44, s38, 11
	s_mov_b32 s45, s49
	global_store_dword v[24:25], v5, off nt
	v_pk_fma_f32 v[24:25], v[20:21], 0.5, v[76:77] op_sel_hi:[1,0,1] neg_lo:[0,0,1] neg_hi:[0,0,1]
	s_lshl_b64 s[44:45], s[44:45], 9
	v_pk_fma_f32 v[20:21], v[2:3], v[72:73], v[20:21] neg_lo:[1,0,0] neg_hi:[1,0,0]
	v_cvt_pk_bf16_f32 v5, v24, v25
	v_lshl_add_u64 v[24:25], v[12:13], 0, s[44:45]
	v_pk_fma_f32 v[20:21], v[2:3], v[78:79], v[20:21]
	s_or_b32 s44, s38, 12
	s_mov_b32 s45, s49
	global_store_dword v[24:25], v5, off nt
	v_pk_fma_f32 v[24:25], v[20:21], 0.5, v[80:81] op_sel_hi:[1,0,1] neg_lo:[0,0,1] neg_hi:[0,0,1]
	s_lshl_b64 s[44:45], s[44:45], 9
; __device__ __forceinline__ unsigned pk2(float lo, float hi) { f32x2 v = {lo, hi}; bf16x2_t b = __builtin_convertvector(v, bf16x2_t); return __builtin_bit_cast(unsigned, b); }
; __device__ __forceinline__ f32x2 ldx2(const bf16_t* p) { const unsigned w = *(const unsigned*)p; return (f32x2){__builtin_bit_cast(float, w << 16), __builtin_bit_cast(float, w & 0xffff0000u)}; }
; template <int W> __device__ __forceinline__ void pool_unit(const bf16_t* x, const LAS float* rs, f32x2 gn, bf16_t* Ag, size_t rb, int t0, int c, int g) {
;     ...
;     for (int bt = 0; bt < 4; ++bt) {
; #pragma unroll
;         for (int i = 0; i < 16; ++i) hn_[i] = ldx2(x + (rb + t0 + bt * 16 + i) * 1024 + c) * rs[16 + bt * 16 + i] * gn;
; #pragma unroll
;         for (int i = 0; i < 16; ++i) { const int t = t0 + bt * 16 + i;
;             win += hn_[i]; const float inv = 1.f / (float)((t + 1) < W ? (t + 1) : W);
;             const f32x2 a = win * inv - hn_[i];
;             *(unsigned*)(Ag + ((size_t)g * MT + rb + t) * 256 + (c & 255)) = pk2(a.x, a.y);
;             win -= (i - W + 1 >= 0) ? hn_[(i - W + 1 >= 0) ? (i - W + 1) : 0] : ring[(i - W + 17) & 15]; }
; #pragma unroll
	v_pk_fma_f32 v[20:21], v[2:3], v[30:31], v[20:21] neg_lo:[1,0,0] neg_hi:[1,0,0]
	v_cvt_pk_bf16_f32 v5, v24, v25
	v_lshl_add_u64 v[24:25], v[12:13], 0, s[44:45]
	v_pk_fma_f32 v[20:21], v[2:3], v[32:33], v[20:21]
	s_or_b32 s44, s38, 13
	s_mov_b32 s45, s49
	global_store_dword v[24:25], v5, off nt
	v_pk_fma_f32 v[24:25], v[20:21], 0.5, v[82:83] op_sel_hi:[1,0,1] neg_lo:[0,0,1] neg_hi:[0,0,1]
	s_lshl_b64 s[44:45], s[44:45], 9
	v_pk_fma_f32 v[20:21], v[2:3], v[78:79], v[20:21] neg_lo:[1,0,0] neg_hi:[1,0,0]
	v_pk_mul_f32 v[84:85], v[2:3], v[18:19]
	v_mov_b32_e32 v34, v35
	v_cvt_pk_bf16_f32 v5, v24, v25
	v_lshl_add_u64 v[24:25], v[12:13], 0, s[44:45]
	v_pk_fma_f32 v[20:21], v[2:3], v[18:19], v[20:21]
	s_or_b32 s44, s38, 14
	s_mov_b32 s45, s49
	v_pk_mul_f32 v[16:17], v[34:35], v[16:17] op_sel_hi:[0,1]
	global_store_dword v[24:25], v5, off nt
	v_pk_fma_f32 v[24:25], v[20:21], 0.5, v[84:85] op_sel_hi:[1,0,1] neg_lo:[0,0,1] neg_hi:[0,0,1]
	s_lshl_b64 s[44:45], s[44:45], 9
	v_pk_fma_f32 v[20:21], v[2:3], v[32:33], v[20:21] neg_lo:[1,0,0] neg_hi:[1,0,0]
	v_pk_mul_f32 v[34:35], v[2:3], v[16:17]
	v_cvt_pk_bf16_f32 v5, v24, v25
	v_lshl_add_u64 v[24:25], v[12:13], 0, s[44:45]
	v_pk_fma_f32 v[20:21], v[2:3], v[16:17], v[20:21]
	s_or_b32 s44, s38, 15
	s_mov_b32 s45, s49
	global_store_dword v[24:25], v5, off nt
	v_pk_fma_f32 v[24:25], v[20:21], 0.5, v[34:35] op_sel_hi:[1,0,1] neg_lo:[0,0,1] neg_hi:[0,0,1]
	s_lshl_b64 s[44:45], s[44:45], 9
	v_cvt_pk_bf16_f32 v5, v24, v25
	v_lshl_add_u64 v[24:25], v[12:13], 0, s[44:45]
	global_store_dword v[24:25], v5, off nt
	global_load_dword v5, v[22:23], off
	s_nop 0
	global_load_dword v43, v[22:23], off offset:2048
	v_add_co_u32_e32 v22, vcc, s92, v14
	s_mov_b32 s39, 0x9000
	s_nop 0
	v_addc_co_u32_e32 v23, vcc, 0, v15, vcc
	global_load_dword v46, v[22:23], off offset:-4096
	v_add_co_u32_e32 v24, vcc, s39, v14
	s_mov_b32 s39, 0xb000
	s_nop 0
	v_addc_co_u32_e32 v25, vcc, 0, v15, vcc
	global_load_dword v50, v[24:25], off offset:2048
	global_load_dword v54, v[22:23], off
	global_load_dword v58, v[22:23], off offset:2048
	v_add_co_u32_e32 v22, vcc, s12, v14
	v_pk_fma_f32 v[36:37], v[2:3], v[18:19], v[20:21] neg_lo:[1,0,0] neg_hi:[1,0,0]
	s_nop 0
	v_addc_co_u32_e32 v23, vcc, 0, v15, vcc
	global_load_dword v60, v[22:23], off offset:-4096
	v_add_co_u32_e32 v24, vcc, s39, v14
	s_mov_b32 s39, 0xe000
	s_nop 0
	v_addc_co_u32_e32 v25, vcc, 0, v15, vcc
	global_load_dword v64, v[24:25], off offset:2048
	global_load_dword v66, v[22:23], off
	global_load_dword v70, v[22:23], off offset:2048
	v_add_co_u32_e32 v22, vcc, s39, v14
	s_mov_b32 s39, 0xd000
	s_nop 0
	v_addc_co_u32_e32 v23, vcc, 0, v15, vcc
	global_load_dword v72, v[22:23], off offset:-4096
	v_add_co_u32_e32 v24, vcc, s39, v14
	s_mov_b32 s39, 0xf000
	s_nop 0
	v_addc_co_u32_e32 v25, vcc, 0, v15, vcc
	global_load_dword v76, v[24:25], off offset:2048
	global_load_dword v78, v[22:23], off
	global_load_dword v82, v[22:23], off offset:2048
	v_add_co_u32_e32 v22, vcc, s63, v14
	ds_read_b128 v[18:21], v175 offset:128
	s_nop 0
	v_addc_co_u32_e32 v23, vcc, 0, v15, vcc
	global_load_dword v84, v[22:23], off offset:-4096
	v_add_co_u32_e32 v24, vcc, s39, v14
	s_or_b32 s44, s38, 16
	s_nop 0
	v_addc_co_u32_e32 v25, vcc, 0, v15, vcc
	global_load_dword v86, v[24:25], off offset:2048
	s_mov_b32 s45, s49
	s_lshl_b64 s[44:45], s[44:45], 9
	ds_read_b128 v[24:27], v175 offset:144
	ds_read_b128 v[28:31], v175 offset:160
	ds_read_b128 v[32:35], v175 offset:176
	s_mov_b32 s39, 0x12000
	s_waitcnt vmcnt(15)
	v_lshlrev_b32_e32 v38, 16, v5
	v_and_b32_e32 v39, 0xffff0000, v5
	s_waitcnt lgkmcnt(3)
	v_pk_mul_f32 v[38:39], v[18:19], v[38:39] op_sel_hi:[0,1]
	v_pk_mul_f32 v[40:41], v[2:3], v[38:39]
	s_waitcnt vmcnt(14)
	v_lshlrev_b32_e32 v42, 16, v43
	v_and_b32_e32 v43, 0xffff0000, v43
	v_pk_fma_f32 v[36:37], v[2:3], v[38:39], v[36:37]
	v_pk_mul_f32 v[42:43], v[18:19], v[42:43] op_sel:[1,0]
	v_pk_fma_f32 v[40:41], v[36:37], 0.5, v[40:41] op_sel_hi:[1,0,1] neg_lo:[0,0,1] neg_hi:[0,0,1]
	v_pk_fma_f32 v[16:17], v[2:3], v[16:17], v[36:37] neg_lo:[1,0,0] neg_hi:[1,0,0]
	v_pk_mul_f32 v[44:45], v[2:3], v[42:43]
	s_waitcnt vmcnt(13)
	v_lshlrev_b32_e32 v18, 16, v46
	v_and_b32_e32 v19, 0xffff0000, v46
	v_cvt_pk_bf16_f32 v5, v40, v41
	v_lshl_add_u64 v[40:41], v[12:13], 0, s[44:45]
	v_pk_fma_f32 v[16:17], v[2:3], v[42:43], v[16:17]
	s_or_b32 s44, s38, 17
	s_mov_b32 s45, s49
	v_pk_mul_f32 v[46:47], v[20:21], v[18:19] op_sel_hi:[0,1]
	v_pk_fma_f32 v[36:37], v[16:17], 0.5, v[44:45] op_sel_hi:[1,0,1] neg_lo:[0,0,1] neg_hi:[0,0,1]
	s_lshl_b64 s[44:45], s[44:45], 9
	v_pk_fma_f32 v[16:17], v[2:3], v[38:39], v[16:17] neg_lo:[1,0,0] neg_hi:[1,0,0]
	v_pk_mul_f32 v[48:49], v[2:3], v[46:47]
	s_waitcnt vmcnt(12)
	v_lshlrev_b32_e32 v18, 16, v50
	v_and_b32_e32 v19, 0xffff0000, v50
	v_mov_b32_e32 v20, v21
	global_store_dword v[40:41], v5, off nt
	v_cvt_pk_bf16_f32 v5, v36, v37
	v_lshl_add_u64 v[36:37], v[12:13], 0, s[44:45]
	v_pk_fma_f32 v[16:17], v[2:3], v[46:47], v[16:17]
	s_or_b32 s44, s38, 18
	s_mov_b32 s45, s49
	v_pk_mul_f32 v[50:51], v[20:21], v[18:19] op_sel_hi:[0,1]
	global_store_dword v[36:37], v5, off nt
	v_pk_fma_f32 v[36:37], v[16:17], 0.5, v[48:49] op_sel_hi:[1,0,1] neg_lo:[0,0,1] neg_hi:[0,0,1]
	s_lshl_b64 s[44:45], s[44:45], 9
	v_pk_fma_f32 v[16:17], v[2:3], v[42:43], v[16:17] neg_lo:[1,0,0] neg_hi:[1,0,0]
	v_pk_mul_f32 v[52:53], v[2:3], v[50:51]
	s_waitcnt vmcnt(13)
	v_lshlrev_b32_e32 v18, 16, v54
	v_and_b32_e32 v19, 0xffff0000, v54
	v_cvt_pk_bf16_f32 v5, v36, v37
	v_lshl_add_u64 v[36:37], v[12:13], 0, s[44:45]
	v_pk_fma_f32 v[16:17], v[2:3], v[50:51], v[16:17]
	s_or_b32 s44, s38, 19
	s_mov_b32 s45, s49
	s_waitcnt lgkmcnt(2)
; __device__ __forceinline__ unsigned pk2(float lo, float hi) { f32x2 v = {lo, hi}; bf16x2_t b = __builtin_convertvector(v, bf16x2_t); return __builtin_bit_cast(unsigned, b); }
; __device__ __forceinline__ f32x2 ldx2(const bf16_t* p) { const unsigned w = *(const unsigned*)p; return (f32x2){__builtin_bit_cast(float, w << 16), __builtin_bit_cast(float, w & 0xffff0000u)}; }
; template <int W> __device__ __forceinline__ void pool_unit(const bf16_t* x, const LAS float* rs, f32x2 gn, bf16_t* Ag, size_t rb, int t0, int c, int g) {
;     ...
;     for (int bt = 0; bt < 4; ++bt) {
; #pragma unroll
;         for (int i = 0; i < 16; ++i) hn_[i] = ldx2(x + (rb + t0 + bt * 16 + i) * 1024 + c) * rs[16 + bt * 16 + i] * gn;
; #pragma unroll
;         for (int i = 0; i < 16; ++i) { const int t = t0 + bt * 16 + i;
;             win += hn_[i]; const float inv = 1.f / (float)((t + 1) < W ? (t + 1) : W);
;             const f32x2 a = win * inv - hn_[i];
;             *(unsigned*)(Ag + ((size_t)g * MT + rb + t) * 256 + (c & 255)) = pk2(a.x, a.y);
;             win -= (i - W + 1 >= 0) ? hn_[(i - W + 1 >= 0) ? (i - W + 1) : 0] : ring[(i - W + 17) & 15]; }
; #pragma unroll
	v_pk_mul_f32 v[54:55], v[24:25], v[18:19] op_sel_hi:[0,1]
	global_store_dword v[36:37], v5, off nt
	v_pk_fma_f32 v[36:37], v[16:17], 0.5, v[52:53] op_sel_hi:[1,0,1] neg_lo:[0,0,1] neg_hi:[0,0,1]
	s_lshl_b64 s[44:45], s[44:45], 9
	v_pk_fma_f32 v[16:17], v[2:3], v[46:47], v[16:17] neg_lo:[1,0,0] neg_hi:[1,0,0]
	v_pk_mul_f32 v[56:57], v[2:3], v[54:55]
	s_waitcnt vmcnt(13)
	v_lshlrev_b32_e32 v18, 16, v58
	v_and_b32_e32 v19, 0xffff0000, v58
	v_cvt_pk_bf16_f32 v5, v36, v37
	v_lshl_add_u64 v[36:37], v[12:13], 0, s[44:45]
	v_pk_fma_f32 v[16:17], v[2:3], v[54:55], v[16:17]
	s_or_b32 s44, s38, 20
	s_mov_b32 s45, s49
	v_pk_mul_f32 v[24:25], v[24:25], v[18:19] op_sel:[1,0]
	global_store_dword v[36:37], v5, off nt
	v_pk_fma_f32 v[36:37], v[16:17], 0.5, v[56:57] op_sel_hi:[1,0,1] neg_lo:[0,0,1] neg_hi:[0,0,1]
	s_lshl_b64 s[44:45], s[44:45], 9
	v_pk_fma_f32 v[16:17], v[2:3], v[50:51], v[16:17] neg_lo:[1,0,0] neg_hi:[1,0,0]
	v_pk_mul_f32 v[58:59], v[2:3], v[24:25]
	s_waitcnt vmcnt(13)
	v_lshlrev_b32_e32 v18, 16, v60
	v_and_b32_e32 v19, 0xffff0000, v60
	v_cvt_pk_bf16_f32 v5, v36, v37
	v_lshl_add_u64 v[36:37], v[12:13], 0, s[44:45]
	v_pk_fma_f32 v[16:17], v[2:3], v[24:25], v[16:17]
	s_or_b32 s44, s38, 21
	s_mov_b32 s45, s49
	v_pk_mul_f32 v[60:61], v[26:27], v[18:19] op_sel_hi:[0,1]
	global_store_dword v[36:37], v5, off nt
	v_pk_fma_f32 v[36:37], v[16:17], 0.5, v[58:59] op_sel_hi:[1,0,1] neg_lo:[0,0,1] neg_hi:[0,0,1]
	s_lshl_b64 s[44:45], s[44:45], 9
	v_pk_fma_f32 v[16:17], v[2:3], v[54:55], v[16:17] neg_lo:[1,0,0] neg_hi:[1,0,0]
	v_pk_mul_f32 v[62:63], v[2:3], v[60:61]
	s_waitcnt vmcnt(13)
	v_lshlrev_b32_e32 v18, 16, v64
	v_and_b32_e32 v19, 0xffff0000, v64
	v_mov_b32_e32 v20, v27
	v_cvt_pk_bf16_f32 v5, v36, v37
	v_lshl_add_u64 v[36:37], v[12:13], 0, s[44:45]
	v_pk_fma_f32 v[16:17], v[2:3], v[60:61], v[16:17]
	s_or_b32 s44, s38, 22
	s_mov_b32 s45, s49
	v_pk_mul_f32 v[26:27], v[20:21], v[18:19] op_sel_hi:[0,1]
	global_store_dword v[36:37], v5, off nt
	v_pk_fma_f32 v[36:37], v[16:17], 0.5, v[62:63] op_sel_hi:[1,0,1] neg_lo:[0,0,1] neg_hi:[0,0,1]
	s_lshl_b64 s[44:45], s[44:45], 9
	v_pk_fma_f32 v[16:17], v[2:3], v[24:25], v[16:17] neg_lo:[1,0,0] neg_hi:[1,0,0]
	v_pk_mul_f32 v[64:65], v[2:3], v[26:27]
	s_waitcnt vmcnt(13)
	v_lshlrev_b32_e32 v18, 16, v66
	v_and_b32_e32 v19, 0xffff0000, v66
	v_cvt_pk_bf16_f32 v5, v36, v37
	v_lshl_add_u64 v[36:37], v[12:13], 0, s[44:45]
	v_pk_fma_f32 v[16:17], v[2:3], v[26:27], v[16:17]
	s_or_b32 s44, s38, 23
	s_mov_b32 s45, s49
	s_waitcnt lgkmcnt(1)
	v_pk_mul_f32 v[66:67], v[28:29], v[18:19] op_sel_hi:[0,1]
	v_pk_fma_f32 v[24:25], v[16:17], 0.5, v[64:65] op_sel_hi:[1,0,1] neg_lo:[0,0,1] neg_hi:[0,0,1]
	s_lshl_b64 s[44:45], s[44:45], 9
	v_pk_fma_f32 v[16:17], v[2:3], v[60:61], v[16:17] neg_lo:[1,0,0] neg_hi:[1,0,0]
	v_pk_mul_f32 v[68:69], v[2:3], v[66:67]
	s_waitcnt vmcnt(12)
	v_lshlrev_b32_e32 v18, 16, v70
	v_and_b32_e32 v19, 0xffff0000, v70
	global_store_dword v[36:37], v5, off nt
	v_cvt_pk_bf16_f32 v5, v24, v25
	v_lshl_add_u64 v[24:25], v[12:13], 0, s[44:45]
	v_pk_fma_f32 v[16:17], v[2:3], v[66:67], v[16:17]
	s_or_b32 s44, s38, 24
	s_mov_b32 s45, s49
	v_pk_mul_f32 v[28:29], v[28:29], v[18:19] op_sel:[1,0]
	global_store_dword v[24:25], v5, off nt
	v_pk_fma_f32 v[24:25], v[16:17], 0.5, v[68:69] op_sel_hi:[1,0,1] neg_lo:[0,0,1] neg_hi:[0,0,1]
	s_lshl_b64 s[44:45], s[44:45], 9
	v_pk_fma_f32 v[16:17], v[2:3], v[26:27], v[16:17] neg_lo:[1,0,0] neg_hi:[1,0,0]
	v_pk_mul_f32 v[70:71], v[2:3], v[28:29]
	s_waitcnt vmcnt(13)
	v_lshlrev_b32_e32 v18, 16, v72
	v_and_b32_e32 v19, 0xffff0000, v72
	v_cvt_pk_bf16_f32 v5, v24, v25
	v_lshl_add_u64 v[24:25], v[12:13], 0, s[44:45]
	v_pk_fma_f32 v[16:17], v[2:3], v[28:29], v[16:17]
	s_or_b32 s44, s38, 25
	s_mov_b32 s45, s49
	v_pk_mul_f32 v[72:73], v[30:31], v[18:19] op_sel_hi:[0,1]
	global_store_dword v[24:25], v5, off nt
	v_pk_fma_f32 v[24:25], v[16:17], 0.5, v[70:71] op_sel_hi:[1,0,1] neg_lo:[0,0,1] neg_hi:[0,0,1]
	s_lshl_b64 s[44:45], s[44:45], 9
	v_pk_fma_f32 v[16:17], v[2:3], v[66:67], v[16:17] neg_lo:[1,0,0] neg_hi:[1,0,0]
	v_pk_mul_f32 v[74:75], v[2:3], v[72:73]
	s_waitcnt vmcnt(13)
	v_lshlrev_b32_e32 v18, 16, v76
	v_and_b32_e32 v19, 0xffff0000, v76
	v_mov_b32_e32 v20, v31
	v_cvt_pk_bf16_f32 v5, v24, v25
	v_lshl_add_u64 v[24:25], v[12:13], 0, s[44:45]
	v_pk_fma_f32 v[16:17], v[2:3], v[72:73], v[16:17]
	s_or_b32 s44, s38, 26
	s_mov_b32 s45, s49
	v_pk_mul_f32 v[30:31], v[20:21], v[18:19] op_sel_hi:[0,1]
	global_store_dword v[24:25], v5, off nt
	v_pk_fma_f32 v[24:25], v[16:17], 0.5, v[74:75] op_sel_hi:[1,0,1] neg_lo:[0,0,1] neg_hi:[0,0,1]
	s_lshl_b64 s[44:45], s[44:45], 9
	v_pk_fma_f32 v[16:17], v[2:3], v[28:29], v[16:17] neg_lo:[1,0,0] neg_hi:[1,0,0]
	v_pk_mul_f32 v[76:77], v[2:3], v[30:31]
	s_waitcnt vmcnt(13)
	v_lshlrev_b32_e32 v18, 16, v78
	v_and_b32_e32 v19, 0xffff0000, v78
	v_cvt_pk_bf16_f32 v5, v24, v25
	v_lshl_add_u64 v[24:25], v[12:13], 0, s[44:45]
	v_pk_fma_f32 v[16:17], v[2:3], v[30:31], v[16:17]
	s_or_b32 s44, s38, 27
	s_mov_b32 s45, s49
	s_waitcnt lgkmcnt(0)
	v_pk_mul_f32 v[78:79], v[32:33], v[18:19] op_sel_hi:[0,1]
	global_store_dword v[24:25], v5, off nt
	v_pk_fma_f32 v[24:25], v[16:17], 0.5, v[76:77] op_sel_hi:[1,0,1] neg_lo:[0,0,1] neg_hi:[0,0,1]
	s_lshl_b64 s[44:45], s[44:45], 9
	v_pk_fma_f32 v[16:17], v[2:3], v[72:73], v[16:17] neg_lo:[1,0,0] neg_hi:[1,0,0]
	v_pk_mul_f32 v[80:81], v[2:3], v[78:79]
	s_waitcnt vmcnt(13)
; __device__ __forceinline__ unsigned pk2(float lo, float hi) { f32x2 v = {lo, hi}; bf16x2_t b = __builtin_convertvector(v, bf16x2_t); return __builtin_bit_cast(unsigned, b); }
; __device__ __forceinline__ f32x2 ldx2(const bf16_t* p) { const unsigned w = *(const unsigned*)p; return (f32x2){__builtin_bit_cast(float, w << 16), __builtin_bit_cast(float, w & 0xffff0000u)}; }
; template <int W> __device__ __forceinline__ void pool_unit(const bf16_t* x, const LAS float* rs, f32x2 gn, bf16_t* Ag, size_t rb, int t0, int c, int g) {
;     ...
;     for (int bt = 0; bt < 4; ++bt) {
; #pragma unroll
;         for (int i = 0; i < 16; ++i) hn_[i] = ldx2(x + (rb + t0 + bt * 16 + i) * 1024 + c) * rs[16 + bt * 16 + i] * gn;
; #pragma unroll
;         for (int i = 0; i < 16; ++i) { const int t = t0 + bt * 16 + i;
;             win += hn_[i]; const float inv = 1.f / (float)((t + 1) < W ? (t + 1) : W);
;             const f32x2 a = win * inv - hn_[i];
;             *(unsigned*)(Ag + ((size_t)g * MT + rb + t) * 256 + (c & 255)) = pk2(a.x, a.y);
;             win -= (i - W + 1 >= 0) ? hn_[(i - W + 1 >= 0) ? (i - W + 1) : 0] : ring[(i - W + 17) & 15]; }
; #pragma unroll
;         for (int i = 0; i < 16; ++i) ring[i] = hn_[i];
	v_lshlrev_b32_e32 v18, 16, v82
	v_and_b32_e32 v19, 0xffff0000, v82
	v_cvt_pk_bf16_f32 v5, v24, v25
	v_lshl_add_u64 v[24:25], v[12:13], 0, s[44:45]
	v_pk_fma_f32 v[16:17], v[2:3], v[78:79], v[16:17]
	s_or_b32 s44, s38, 28
	s_mov_b32 s45, s49
	v_pk_mul_f32 v[32:33], v[32:33], v[18:19] op_sel:[1,0]
	global_store_dword v[24:25], v5, off nt
	v_pk_fma_f32 v[24:25], v[16:17], 0.5, v[80:81] op_sel_hi:[1,0,1] neg_lo:[0,0,1] neg_hi:[0,0,1]
	s_lshl_b64 s[44:45], s[44:45], 9
	v_pk_fma_f32 v[16:17], v[2:3], v[30:31], v[16:17] neg_lo:[1,0,0] neg_hi:[1,0,0]
	v_pk_mul_f32 v[82:83], v[2:3], v[32:33]
	s_waitcnt vmcnt(13)
	v_lshlrev_b32_e32 v18, 16, v84
	v_and_b32_e32 v19, 0xffff0000, v84
	v_cvt_pk_bf16_f32 v5, v24, v25
	v_lshl_add_u64 v[24:25], v[12:13], 0, s[44:45]
	v_pk_fma_f32 v[16:17], v[2:3], v[32:33], v[16:17]
	s_or_b32 s44, s38, 29
	s_mov_b32 s45, s49
	v_pk_mul_f32 v[20:21], v[34:35], v[18:19] op_sel_hi:[0,1]
	global_store_dword v[24:25], v5, off nt
	v_pk_fma_f32 v[24:25], v[16:17], 0.5, v[82:83] op_sel_hi:[1,0,1] neg_lo:[0,0,1] neg_hi:[0,0,1]
	s_lshl_b64 s[44:45], s[44:45], 9
	v_pk_fma_f32 v[16:17], v[2:3], v[78:79], v[16:17] neg_lo:[1,0,0] neg_hi:[1,0,0]
	v_pk_mul_f32 v[84:85], v[2:3], v[20:21]
	s_waitcnt vmcnt(13)
	v_lshlrev_b32_e32 v18, 16, v86
	v_and_b32_e32 v19, 0xffff0000, v86
	v_mov_b32_e32 v34, v35
	v_cvt_pk_bf16_f32 v5, v24, v25
	v_lshl_add_u64 v[24:25], v[12:13], 0, s[44:45]
	v_pk_fma_f32 v[16:17], v[2:3], v[20:21], v[16:17]
	s_or_b32 s44, s38, 30
	s_mov_b32 s45, s49
	v_pk_mul_f32 v[18:19], v[34:35], v[18:19] op_sel_hi:[0,1]
	global_store_dword v[24:25], v5, off nt
	v_pk_fma_f32 v[24:25], v[16:17], 0.5, v[84:85] op_sel_hi:[1,0,1] neg_lo:[0,0,1] neg_hi:[0,0,1]
	s_lshl_b64 s[44:45], s[44:45], 9
	v_pk_fma_f32 v[16:17], v[2:3], v[32:33], v[16:17] neg_lo:[1,0,0] neg_hi:[1,0,0]
	v_pk_mul_f32 v[34:35], v[2:3], v[18:19]
	v_cvt_pk_bf16_f32 v5, v24, v25
	v_lshl_add_u64 v[24:25], v[12:13], 0, s[44:45]
	v_pk_fma_f32 v[16:17], v[2:3], v[18:19], v[16:17]
	s_or_b32 s44, s38, 31
	s_mov_b32 s45, s49
	global_store_dword v[24:25], v5, off nt
	v_pk_fma_f32 v[24:25], v[16:17], 0.5, v[34:35] op_sel_hi:[1,0,1] neg_lo:[0,0,1] neg_hi:[0,0,1]
	s_lshl_b64 s[44:45], s[44:45], 9
	v_cvt_pk_bf16_f32 v5, v24, v25
	v_lshl_add_u64 v[24:25], v[12:13], 0, s[44:45]
	global_store_dword v[24:25], v5, off nt
	global_load_dword v5, v[22:23], off
	s_nop 0
	global_load_dword v46, v[22:23], off offset:2048
	v_add_co_u32_e32 v22, vcc, s39, v14
	s_mov_b32 s39, 0x11000
	s_nop 0
	v_addc_co_u32_e32 v23, vcc, 0, v15, vcc
	global_load_dword v48, v[22:23], off offset:-4096
	v_add_co_u32_e32 v24, vcc, s39, v14
	s_mov_b32 s39, 0x14000
	s_nop 0
	v_addc_co_u32_e32 v25, vcc, 0, v15, vcc
	global_load_dword v52, v[24:25], off offset:2048
	global_load_dword v54, v[22:23], off
	global_load_dword v58, v[22:23], off offset:2048
	v_add_co_u32_e32 v22, vcc, s39, v14
	s_mov_b32 s39, 0x13000
	s_nop 0
	v_addc_co_u32_e32 v23, vcc, 0, v15, vcc
	global_load_dword v60, v[22:23], off offset:-4096
	v_add_co_u32_e32 v24, vcc, s39, v14
	s_mov_b32 s39, 0x16000
	s_nop 0
	v_addc_co_u32_e32 v25, vcc, 0, v15, vcc
	global_load_dword v64, v[24:25], off offset:2048
	global_load_dword v66, v[22:23], off
	global_load_dword v70, v[22:23], off offset:2048
	v_add_co_u32_e32 v22, vcc, s39, v14
	s_mov_b32 s39, 0x15000
	s_nop 0
	v_addc_co_u32_e32 v23, vcc, 0, v15, vcc
	global_load_dword v72, v[22:23], off offset:-4096
	v_add_co_u32_e32 v24, vcc, s39, v14
	s_mov_b32 s39, 0x18000
	s_nop 0
	v_addc_co_u32_e32 v25, vcc, 0, v15, vcc
	global_load_dword v76, v[24:25], off offset:2048
	global_load_dword v78, v[22:23], off
	global_load_dword v82, v[22:23], off offset:2048
	v_add_co_u32_e32 v22, vcc, s39, v14
	s_mov_b32 s39, 0x17000
	s_nop 0
	v_addc_co_u32_e32 v23, vcc, 0, v15, vcc
	global_load_dword v84, v[22:23], off offset:-4096
	v_add_co_u32_e32 v24, vcc, s39, v14
	v_pk_fma_f32 v[40:41], v[2:3], v[20:21], v[16:17] neg_lo:[1,0,0] neg_hi:[1,0,0]
	s_nop 0
	v_addc_co_u32_e32 v25, vcc, 0, v15, vcc
	global_load_dword v86, v[24:25], off offset:2048
	ds_read_b128 v[24:27], v175 offset:192
	s_or_b32 s44, s38, 32
	s_mov_b32 s45, s49
	s_lshl_b64 s[44:45], s[44:45], 9
	ds_read_b128 v[28:31], v175 offset:208
	ds_read_b128 v[32:35], v175 offset:224
	ds_read_b128 v[36:39], v175 offset:240
	s_waitcnt lgkmcnt(3)
	v_mov_b32_e32 v20, v27
	s_mov_b32 s39, 0x1a000
	s_waitcnt vmcnt(15)
	v_lshlrev_b32_e32 v16, 16, v5
	v_and_b32_e32 v17, 0xffff0000, v5
	v_pk_mul_f32 v[42:43], v[24:25], v[16:17] op_sel_hi:[0,1]
	v_pk_mul_f32 v[44:45], v[2:3], v[42:43]
	s_waitcnt vmcnt(14)
	v_lshlrev_b32_e32 v16, 16, v46
	v_and_b32_e32 v17, 0xffff0000, v46
	v_pk_fma_f32 v[40:41], v[2:3], v[42:43], v[40:41]
	v_pk_mul_f32 v[24:25], v[24:25], v[16:17] op_sel:[1,0]
	v_pk_fma_f32 v[44:45], v[40:41], 0.5, v[44:45] op_sel_hi:[1,0,1] neg_lo:[0,0,1] neg_hi:[0,0,1]
	v_pk_fma_f32 v[18:19], v[2:3], v[18:19], v[40:41] neg_lo:[1,0,0] neg_hi:[1,0,0]
	v_pk_mul_f32 v[46:47], v[2:3], v[24:25]
	s_waitcnt vmcnt(13)
	v_lshlrev_b32_e32 v16, 16, v48
	v_and_b32_e32 v17, 0xffff0000, v48
	v_cvt_pk_bf16_f32 v5, v44, v45
	v_lshl_add_u64 v[44:45], v[12:13], 0, s[44:45]
	v_pk_fma_f32 v[18:19], v[2:3], v[24:25], v[18:19]
	s_or_b32 s44, s38, 33
	s_mov_b32 s45, s49
	v_pk_mul_f32 v[48:49], v[26:27], v[16:17] op_sel_hi:[0,1]
	v_pk_fma_f32 v[40:41], v[18:19], 0.5, v[46:47] op_sel_hi:[1,0,1] neg_lo:[0,0,1] neg_hi:[0,0,1]
	s_lshl_b64 s[44:45], s[44:45], 9
	v_pk_fma_f32 v[18:19], v[2:3], v[42:43], v[18:19] neg_lo:[1,0,0] neg_hi:[1,0,0]
	v_pk_mul_f32 v[50:51], v[2:3], v[48:49]
	s_waitcnt vmcnt(12)
; __device__ __forceinline__ unsigned pk2(float lo, float hi) { f32x2 v = {lo, hi}; bf16x2_t b = __builtin_convertvector(v, bf16x2_t); return __builtin_bit_cast(unsigned, b); }
; __device__ __forceinline__ f32x2 ldx2(const bf16_t* p) { const unsigned w = *(const unsigned*)p; return (f32x2){__builtin_bit_cast(float, w << 16), __builtin_bit_cast(float, w & 0xffff0000u)}; }
; template <int W> __device__ __forceinline__ void pool_unit(const bf16_t* x, const LAS float* rs, f32x2 gn, bf16_t* Ag, size_t rb, int t0, int c, int g) {
;     ...
;     for (int bt = 0; bt < 4; ++bt) {
; #pragma unroll
;         for (int i = 0; i < 16; ++i) hn_[i] = ldx2(x + (rb + t0 + bt * 16 + i) * 1024 + c) * rs[16 + bt * 16 + i] * gn;
; #pragma unroll
;         for (int i = 0; i < 16; ++i) { const int t = t0 + bt * 16 + i;
;             win += hn_[i]; const float inv = 1.f / (float)((t + 1) < W ? (t + 1) : W);
;             const f32x2 a = win * inv - hn_[i];
;             *(unsigned*)(Ag + ((size_t)g * MT + rb + t) * 256 + (c & 255)) = pk2(a.x, a.y);
;             win -= (i - W + 1 >= 0) ? hn_[(i - W + 1 >= 0) ? (i - W + 1) : 0] : ring[(i - W + 17) & 15]; }
; #pragma unroll
	v_lshlrev_b32_e32 v16, 16, v52
	v_and_b32_e32 v17, 0xffff0000, v52
	global_store_dword v[44:45], v5, off nt
	v_cvt_pk_bf16_f32 v5, v40, v41
	v_lshl_add_u64 v[40:41], v[12:13], 0, s[44:45]
	v_pk_fma_f32 v[18:19], v[2:3], v[48:49], v[18:19]
	s_or_b32 s44, s38, 34
	s_mov_b32 s45, s49
	v_pk_mul_f32 v[26:27], v[20:21], v[16:17] op_sel_hi:[0,1]
	global_store_dword v[40:41], v5, off nt
	v_pk_fma_f32 v[40:41], v[18:19], 0.5, v[50:51] op_sel_hi:[1,0,1] neg_lo:[0,0,1] neg_hi:[0,0,1]
	s_lshl_b64 s[44:45], s[44:45], 9
	v_pk_fma_f32 v[18:19], v[2:3], v[24:25], v[18:19] neg_lo:[1,0,0] neg_hi:[1,0,0]
	v_pk_mul_f32 v[52:53], v[2:3], v[26:27]
	s_waitcnt vmcnt(13)
	v_lshlrev_b32_e32 v16, 16, v54
	v_and_b32_e32 v17, 0xffff0000, v54
	v_cvt_pk_bf16_f32 v5, v40, v41
	v_lshl_add_u64 v[40:41], v[12:13], 0, s[44:45]
	v_pk_fma_f32 v[18:19], v[2:3], v[26:27], v[18:19]
	s_or_b32 s44, s38, 35
	s_mov_b32 s45, s49
	s_waitcnt lgkmcnt(2)
	v_pk_mul_f32 v[54:55], v[28:29], v[16:17] op_sel_hi:[0,1]
	v_pk_fma_f32 v[24:25], v[18:19], 0.5, v[52:53] op_sel_hi:[1,0,1] neg_lo:[0,0,1] neg_hi:[0,0,1]
	s_lshl_b64 s[44:45], s[44:45], 9
	v_pk_fma_f32 v[18:19], v[2:3], v[48:49], v[18:19] neg_lo:[1,0,0] neg_hi:[1,0,0]
	v_pk_mul_f32 v[56:57], v[2:3], v[54:55]
	s_waitcnt vmcnt(12)
	v_lshlrev_b32_e32 v16, 16, v58
	v_and_b32_e32 v17, 0xffff0000, v58
	global_store_dword v[40:41], v5, off nt
	v_cvt_pk_bf16_f32 v5, v24, v25
	v_lshl_add_u64 v[24:25], v[12:13], 0, s[44:45]
	v_pk_fma_f32 v[18:19], v[2:3], v[54:55], v[18:19]
	s_or_b32 s44, s38, 36
	s_mov_b32 s45, s49
	v_pk_mul_f32 v[28:29], v[28:29], v[16:17] op_sel:[1,0]
	global_store_dword v[24:25], v5, off nt
	v_pk_fma_f32 v[24:25], v[18:19], 0.5, v[56:57] op_sel_hi:[1,0,1] neg_lo:[0,0,1] neg_hi:[0,0,1]
	s_lshl_b64 s[44:45], s[44:45], 9
	v_pk_fma_f32 v[18:19], v[2:3], v[26:27], v[18:19] neg_lo:[1,0,0] neg_hi:[1,0,0]
	v_pk_mul_f32 v[58:59], v[2:3], v[28:29]
	s_waitcnt vmcnt(13)
	v_lshlrev_b32_e32 v16, 16, v60
	v_and_b32_e32 v17, 0xffff0000, v60
	v_cvt_pk_bf16_f32 v5, v24, v25
	v_lshl_add_u64 v[24:25], v[12:13], 0, s[44:45]
	v_pk_fma_f32 v[18:19], v[2:3], v[28:29], v[18:19]
	s_or_b32 s44, s38, 37
	s_mov_b32 s45, s49
	v_pk_mul_f32 v[60:61], v[30:31], v[16:17] op_sel_hi:[0,1]
	global_store_dword v[24:25], v5, off nt
	v_pk_fma_f32 v[24:25], v[18:19], 0.5, v[58:59] op_sel_hi:[1,0,1] neg_lo:[0,0,1] neg_hi:[0,0,1]
	s_lshl_b64 s[44:45], s[44:45], 9
	v_pk_fma_f32 v[18:19], v[2:3], v[54:55], v[18:19] neg_lo:[1,0,0] neg_hi:[1,0,0]
	v_pk_mul_f32 v[62:63], v[2:3], v[60:61]
	s_waitcnt vmcnt(13)
	v_lshlrev_b32_e32 v16, 16, v64
	v_and_b32_e32 v17, 0xffff0000, v64
	v_mov_b32_e32 v20, v31
	v_cvt_pk_bf16_f32 v5, v24, v25
	v_lshl_add_u64 v[24:25], v[12:13], 0, s[44:45]
	v_pk_fma_f32 v[18:19], v[2:3], v[60:61], v[18:19]
	s_or_b32 s44, s38, 38
	s_mov_b32 s45, s49
	v_pk_mul_f32 v[30:31], v[20:21], v[16:17] op_sel_hi:[0,1]
	global_store_dword v[24:25], v5, off nt
	v_pk_fma_f32 v[24:25], v[18:19], 0.5, v[62:63] op_sel_hi:[1,0,1] neg_lo:[0,0,1] neg_hi:[0,0,1]
	s_lshl_b64 s[44:45], s[44:45], 9
	v_pk_fma_f32 v[18:19], v[2:3], v[28:29], v[18:19] neg_lo:[1,0,0] neg_hi:[1,0,0]
	v_pk_mul_f32 v[64:65], v[2:3], v[30:31]
	s_waitcnt vmcnt(13)
	v_lshlrev_b32_e32 v16, 16, v66
	v_and_b32_e32 v17, 0xffff0000, v66
	v_cvt_pk_bf16_f32 v5, v24, v25
	v_lshl_add_u64 v[24:25], v[12:13], 0, s[44:45]
	v_pk_fma_f32 v[18:19], v[2:3], v[30:31], v[18:19]
	s_or_b32 s44, s38, 39
	s_mov_b32 s45, s49
	s_waitcnt lgkmcnt(1)
	v_pk_mul_f32 v[66:67], v[32:33], v[16:17] op_sel_hi:[0,1]
	global_store_dword v[24:25], v5, off nt
	v_pk_fma_f32 v[24:25], v[18:19], 0.5, v[64:65] op_sel_hi:[1,0,1] neg_lo:[0,0,1] neg_hi:[0,0,1]
	s_lshl_b64 s[44:45], s[44:45], 9
	v_pk_fma_f32 v[18:19], v[2:3], v[60:61], v[18:19] neg_lo:[1,0,0] neg_hi:[1,0,0]
	v_pk_mul_f32 v[68:69], v[2:3], v[66:67]
	s_waitcnt vmcnt(13)
	v_lshlrev_b32_e32 v16, 16, v70
	v_and_b32_e32 v17, 0xffff0000, v70
	v_cvt_pk_bf16_f32 v5, v24, v25
	v_lshl_add_u64 v[24:25], v[12:13], 0, s[44:45]
	v_pk_fma_f32 v[18:19], v[2:3], v[66:67], v[18:19]
	s_or_b32 s44, s38, 40
	s_mov_b32 s45, s49
	v_pk_mul_f32 v[32:33], v[32:33], v[16:17] op_sel:[1,0]
	global_store_dword v[24:25], v5, off nt
	v_pk_fma_f32 v[24:25], v[18:19], 0.5, v[68:69] op_sel_hi:[1,0,1] neg_lo:[0,0,1] neg_hi:[0,0,1]
	s_lshl_b64 s[44:45], s[44:45], 9
	v_pk_fma_f32 v[18:19], v[2:3], v[30:31], v[18:19] neg_lo:[1,0,0] neg_hi:[1,0,0]
	v_pk_mul_f32 v[70:71], v[2:3], v[32:33]
	s_waitcnt vmcnt(13)
	v_lshlrev_b32_e32 v16, 16, v72
	v_and_b32_e32 v17, 0xffff0000, v72
	v_cvt_pk_bf16_f32 v5, v24, v25
	v_lshl_add_u64 v[24:25], v[12:13], 0, s[44:45]
	v_pk_fma_f32 v[18:19], v[2:3], v[32:33], v[18:19]
	s_or_b32 s44, s38, 41
	s_mov_b32 s45, s49
	v_pk_mul_f32 v[72:73], v[34:35], v[16:17] op_sel_hi:[0,1]
	global_store_dword v[24:25], v5, off nt
	v_pk_fma_f32 v[24:25], v[18:19], 0.5, v[70:71] op_sel_hi:[1,0,1] neg_lo:[0,0,1] neg_hi:[0,0,1]
	s_lshl_b64 s[44:45], s[44:45], 9
	v_pk_fma_f32 v[18:19], v[2:3], v[66:67], v[18:19] neg_lo:[1,0,0] neg_hi:[1,0,0]
	v_pk_mul_f32 v[74:75], v[2:3], v[72:73]
	s_waitcnt vmcnt(13)
	v_lshlrev_b32_e32 v16, 16, v76
	v_and_b32_e32 v17, 0xffff0000, v76
	v_mov_b32_e32 v20, v35
	v_cvt_pk_bf16_f32 v5, v24, v25
	v_lshl_add_u64 v[24:25], v[12:13], 0, s[44:45]
	v_pk_fma_f32 v[18:19], v[2:3], v[72:73], v[18:19]
	s_or_b32 s44, s38, 42
	s_mov_b32 s45, s49
	v_pk_mul_f32 v[34:35], v[20:21], v[16:17] op_sel_hi:[0,1]
	global_store_dword v[24:25], v5, off nt
	v_pk_fma_f32 v[24:25], v[18:19], 0.5, v[74:75] op_sel_hi:[1,0,1] neg_lo:[0,0,1] neg_hi:[0,0,1]
	s_lshl_b64 s[44:45], s[44:45], 9
	v_pk_fma_f32 v[18:19], v[2:3], v[32:33], v[18:19] neg_lo:[1,0,0] neg_hi:[1,0,0]
	v_pk_mul_f32 v[76:77], v[2:3], v[34:35]
	s_waitcnt vmcnt(13)
; __device__ __forceinline__ unsigned pk2(float lo, float hi) { f32x2 v = {lo, hi}; bf16x2_t b = __builtin_convertvector(v, bf16x2_t); return __builtin_bit_cast(unsigned, b); }
; __device__ __forceinline__ f32x2 ldx2(const bf16_t* p) { const unsigned w = *(const unsigned*)p; return (f32x2){__builtin_bit_cast(float, w << 16), __builtin_bit_cast(float, w & 0xffff0000u)}; }
; template <int W> __device__ __forceinline__ void pool_unit(const bf16_t* x, const LAS float* rs, f32x2 gn, bf16_t* Ag, size_t rb, int t0, int c, int g) {
;     ...
;     for (int bt = 0; bt < 4; ++bt) {
; #pragma unroll
;         for (int i = 0; i < 16; ++i) hn_[i] = ldx2(x + (rb + t0 + bt * 16 + i) * 1024 + c) * rs[16 + bt * 16 + i] * gn;
; #pragma unroll
;         for (int i = 0; i < 16; ++i) { const int t = t0 + bt * 16 + i;
;             win += hn_[i]; const float inv = 1.f / (float)((t + 1) < W ? (t + 1) : W);
;             const f32x2 a = win * inv - hn_[i];
;             *(unsigned*)(Ag + ((size_t)g * MT + rb + t) * 256 + (c & 255)) = pk2(a.x, a.y);
;             win -= (i - W + 1 >= 0) ? hn_[(i - W + 1 >= 0) ? (i - W + 1) : 0] : ring[(i - W + 17) & 15]; }
; #pragma unroll
;         for (int i = 0; i < 16; ++i) ring[i] = hn_[i];
	v_lshlrev_b32_e32 v16, 16, v78
	v_and_b32_e32 v17, 0xffff0000, v78
	v_cvt_pk_bf16_f32 v5, v24, v25
	v_lshl_add_u64 v[24:25], v[12:13], 0, s[44:45]
	v_pk_fma_f32 v[18:19], v[2:3], v[34:35], v[18:19]
	s_or_b32 s44, s38, 43
	s_mov_b32 s45, s49
	s_waitcnt lgkmcnt(0)
	v_pk_mul_f32 v[78:79], v[36:37], v[16:17] op_sel_hi:[0,1]
	global_store_dword v[24:25], v5, off nt
	v_pk_fma_f32 v[24:25], v[18:19], 0.5, v[76:77] op_sel_hi:[1,0,1] neg_lo:[0,0,1] neg_hi:[0,0,1]
	s_lshl_b64 s[44:45], s[44:45], 9
	v_pk_fma_f32 v[18:19], v[2:3], v[72:73], v[18:19] neg_lo:[1,0,0] neg_hi:[1,0,0]
	v_pk_mul_f32 v[80:81], v[2:3], v[78:79]
	s_waitcnt vmcnt(13)
	v_lshlrev_b32_e32 v16, 16, v82
	v_and_b32_e32 v17, 0xffff0000, v82
	v_cvt_pk_bf16_f32 v5, v24, v25
	v_lshl_add_u64 v[24:25], v[12:13], 0, s[44:45]
	v_pk_fma_f32 v[18:19], v[2:3], v[78:79], v[18:19]
	s_or_b32 s44, s38, 44
	s_mov_b32 s45, s49
	v_pk_mul_f32 v[36:37], v[36:37], v[16:17] op_sel:[1,0]
	global_store_dword v[24:25], v5, off nt
	v_pk_fma_f32 v[24:25], v[18:19], 0.5, v[80:81] op_sel_hi:[1,0,1] neg_lo:[0,0,1] neg_hi:[0,0,1]
	s_lshl_b64 s[44:45], s[44:45], 9
	v_pk_fma_f32 v[18:19], v[2:3], v[34:35], v[18:19] neg_lo:[1,0,0] neg_hi:[1,0,0]
	v_pk_mul_f32 v[82:83], v[2:3], v[36:37]
	s_waitcnt vmcnt(13)
	v_lshlrev_b32_e32 v16, 16, v84
	v_and_b32_e32 v17, 0xffff0000, v84
	v_cvt_pk_bf16_f32 v5, v24, v25
	v_lshl_add_u64 v[24:25], v[12:13], 0, s[44:45]
	v_pk_fma_f32 v[18:19], v[2:3], v[36:37], v[18:19]
	s_or_b32 s44, s38, 45
	s_mov_b32 s45, s49
	v_pk_mul_f32 v[20:21], v[38:39], v[16:17] op_sel_hi:[0,1]
	global_store_dword v[24:25], v5, off nt
	v_pk_fma_f32 v[24:25], v[18:19], 0.5, v[82:83] op_sel_hi:[1,0,1] neg_lo:[0,0,1] neg_hi:[0,0,1]
	s_lshl_b64 s[44:45], s[44:45], 9
	v_pk_fma_f32 v[18:19], v[2:3], v[78:79], v[18:19] neg_lo:[1,0,0] neg_hi:[1,0,0]
	v_pk_mul_f32 v[84:85], v[2:3], v[20:21]
	s_waitcnt vmcnt(13)
	v_lshlrev_b32_e32 v16, 16, v86
	v_and_b32_e32 v17, 0xffff0000, v86
	v_mov_b32_e32 v38, v39
	v_cvt_pk_bf16_f32 v5, v24, v25
	v_lshl_add_u64 v[24:25], v[12:13], 0, s[44:45]
	v_pk_fma_f32 v[18:19], v[2:3], v[20:21], v[18:19]
	s_or_b32 s44, s38, 46
	s_mov_b32 s45, s49
	v_pk_mul_f32 v[16:17], v[38:39], v[16:17] op_sel_hi:[0,1]
	global_store_dword v[24:25], v5, off nt
	v_pk_fma_f32 v[24:25], v[18:19], 0.5, v[84:85] op_sel_hi:[1,0,1] neg_lo:[0,0,1] neg_hi:[0,0,1]
	s_lshl_b64 s[44:45], s[44:45], 9
	v_pk_fma_f32 v[18:19], v[2:3], v[36:37], v[18:19] neg_lo:[1,0,0] neg_hi:[1,0,0]
	v_pk_mul_f32 v[38:39], v[2:3], v[16:17]
	v_cvt_pk_bf16_f32 v5, v24, v25
	v_lshl_add_u64 v[24:25], v[12:13], 0, s[44:45]
	v_pk_fma_f32 v[18:19], v[2:3], v[16:17], v[18:19]
	s_or_b32 s44, s38, 47
	s_mov_b32 s45, s49
	global_store_dword v[24:25], v5, off nt
	v_pk_fma_f32 v[24:25], v[18:19], 0.5, v[38:39] op_sel_hi:[1,0,1] neg_lo:[0,0,1] neg_hi:[0,0,1]
	s_lshl_b64 s[44:45], s[44:45], 9
	v_cvt_pk_bf16_f32 v5, v24, v25
	v_lshl_add_u64 v[24:25], v[12:13], 0, s[44:45]
	global_store_dword v[24:25], v5, off nt
	global_load_dword v5, v[22:23], off
	s_nop 0
	global_load_dword v39, v[22:23], off offset:2048
	v_add_co_u32_e32 v22, vcc, s39, v14
	s_mov_b32 s39, 0x19000
	s_nop 0
	v_addc_co_u32_e32 v23, vcc, 0, v15, vcc
	global_load_dword v41, v[22:23], off offset:-4096
	v_add_co_u32_e32 v24, vcc, s39, v14
	s_mov_b32 s39, 0x1c000
	s_nop 0
	v_addc_co_u32_e32 v25, vcc, 0, v15, vcc
	global_load_dword v45, v[24:25], off offset:2048
	global_load_dword v47, v[22:23], off
	global_load_dword v51, v[22:23], off offset:2048
	v_add_co_u32_e32 v22, vcc, s39, v14
	s_mov_b32 s39, 0x1b000
	s_nop 0
	v_addc_co_u32_e32 v23, vcc, 0, v15, vcc
	global_load_dword v53, v[22:23], off offset:-4096
	v_add_co_u32_e32 v24, vcc, s39, v14
	s_mov_b32 s39, 0x1e000
	s_nop 0
	v_addc_co_u32_e32 v25, vcc, 0, v15, vcc
	global_load_dword v57, v[24:25], off offset:2048
	global_load_dword v59, v[22:23], off
	global_load_dword v63, v[22:23], off offset:2048
	v_add_co_u32_e32 v22, vcc, s39, v14
	s_mov_b32 s39, 0x1d000
	s_nop 0
	v_addc_co_u32_e32 v23, vcc, 0, v15, vcc
	global_load_dword v65, v[22:23], off offset:-4096
	v_add_co_u32_e32 v24, vcc, s39, v14
	s_mov_b32 s39, 0x1f000
	s_nop 0
	v_addc_co_u32_e32 v25, vcc, 0, v15, vcc
	global_load_dword v69, v[24:25], off offset:2048
	global_load_dword v71, v[22:23], off
	global_load_dword v75, v[22:23], off offset:2048
	v_add_co_u32_e32 v14, vcc, s39, v14
	s_or_b32 s44, s38, 48
	s_nop 0
	v_addc_co_u32_e32 v15, vcc, 0, v15, vcc
	global_load_dword v77, v[14:15], off
	global_load_dword v81, v[14:15], off offset:2048
	v_pk_fma_f32 v[14:15], v[2:3], v[20:21], v[18:19] neg_lo:[1,0,0] neg_hi:[1,0,0]
	ds_read_b128 v[18:21], v175 offset:256
	s_mov_b32 s45, s49
	s_lshl_b64 s[44:45], s[44:45], 9
	ds_read_b128 v[22:25], v175 offset:272
	ds_read_b128 v[26:29], v175 offset:288
	ds_read_b128 v[30:33], v175 offset:304
	s_mov_b32 s39, s49
	s_waitcnt vmcnt(15)
	v_lshlrev_b32_e32 v34, 16, v5
	v_and_b32_e32 v35, 0xffff0000, v5
	s_waitcnt lgkmcnt(3)
	v_pk_mul_f32 v[34:35], v[18:19], v[34:35] op_sel_hi:[0,1]
	v_pk_mul_f32 v[36:37], v[2:3], v[34:35]
	s_waitcnt vmcnt(14)
	v_lshlrev_b32_e32 v38, 16, v39
	v_and_b32_e32 v39, 0xffff0000, v39
	v_pk_fma_f32 v[14:15], v[2:3], v[34:35], v[14:15]
	v_pk_mul_f32 v[18:19], v[18:19], v[38:39] op_sel:[1,0]
	v_pk_fma_f32 v[36:37], v[14:15], 0.5, v[36:37] op_sel_hi:[1,0,1] neg_lo:[0,0,1] neg_hi:[0,0,1]
	v_pk_fma_f32 v[14:15], v[2:3], v[16:17], v[14:15] neg_lo:[1,0,0] neg_hi:[1,0,0]
	v_pk_mul_f32 v[38:39], v[2:3], v[18:19]
	s_waitcnt vmcnt(13)
; __device__ __forceinline__ unsigned pk2(float lo, float hi) { f32x2 v = {lo, hi}; bf16x2_t b = __builtin_convertvector(v, bf16x2_t); return __builtin_bit_cast(unsigned, b); }
; __device__ __forceinline__ f32x2 ldx2(const bf16_t* p) { const unsigned w = *(const unsigned*)p; return (f32x2){__builtin_bit_cast(float, w << 16), __builtin_bit_cast(float, w & 0xffff0000u)}; }
; template <int W> __device__ __forceinline__ void pool_unit(const bf16_t* x, const LAS float* rs, f32x2 gn, bf16_t* Ag, size_t rb, int t0, int c, int g) {
;     ...
;     for (int bt = 0; bt < 4; ++bt) {
; #pragma unroll
;         for (int i = 0; i < 16; ++i) hn_[i] = ldx2(x + (rb + t0 + bt * 16 + i) * 1024 + c) * rs[16 + bt * 16 + i] * gn;
; #pragma unroll
;         for (int i = 0; i < 16; ++i) { const int t = t0 + bt * 16 + i;
;             win += hn_[i]; const float inv = 1.f / (float)((t + 1) < W ? (t + 1) : W);
;             const f32x2 a = win * inv - hn_[i];
;             *(unsigned*)(Ag + ((size_t)g * MT + rb + t) * 256 + (c & 255)) = pk2(a.x, a.y);
;             win -= (i - W + 1 >= 0) ? hn_[(i - W + 1 >= 0) ? (i - W + 1) : 0] : ring[(i - W + 17) & 15]; }
; #pragma unroll
	v_lshlrev_b32_e32 v40, 16, v41
	v_and_b32_e32 v41, 0xffff0000, v41
	v_cvt_pk_bf16_f32 v5, v36, v37
	v_lshl_add_u64 v[36:37], v[12:13], 0, s[44:45]
	v_pk_fma_f32 v[14:15], v[2:3], v[18:19], v[14:15]
	s_or_b32 s44, s38, 49
	s_mov_b32 s45, s49
	v_pk_mul_f32 v[40:41], v[20:21], v[40:41] op_sel_hi:[0,1]
	v_pk_fma_f32 v[16:17], v[14:15], 0.5, v[38:39] op_sel_hi:[1,0,1] neg_lo:[0,0,1] neg_hi:[0,0,1]
	s_lshl_b64 s[44:45], s[44:45], 9
	v_pk_fma_f32 v[14:15], v[2:3], v[34:35], v[14:15] neg_lo:[1,0,0] neg_hi:[1,0,0]
	v_pk_mul_f32 v[42:43], v[2:3], v[40:41]
	s_waitcnt vmcnt(12)
	v_lshlrev_b32_e32 v44, 16, v45
	v_and_b32_e32 v45, 0xffff0000, v45
	v_mov_b32_e32 v20, v21
	global_store_dword v[36:37], v5, off nt
	v_cvt_pk_bf16_f32 v5, v16, v17
	v_lshl_add_u64 v[16:17], v[12:13], 0, s[44:45]
	v_pk_fma_f32 v[14:15], v[2:3], v[40:41], v[14:15]
	s_or_b32 s44, s38, 50
	s_mov_b32 s45, s49
	v_pk_mul_f32 v[20:21], v[20:21], v[44:45] op_sel_hi:[0,1]
	global_store_dword v[16:17], v5, off nt
	v_pk_fma_f32 v[16:17], v[14:15], 0.5, v[42:43] op_sel_hi:[1,0,1] neg_lo:[0,0,1] neg_hi:[0,0,1]
	s_lshl_b64 s[44:45], s[44:45], 9
	v_pk_fma_f32 v[14:15], v[2:3], v[18:19], v[14:15] neg_lo:[1,0,0] neg_hi:[1,0,0]
	v_pk_mul_f32 v[44:45], v[2:3], v[20:21]
	s_waitcnt vmcnt(13)
	v_lshlrev_b32_e32 v46, 16, v47
	v_and_b32_e32 v47, 0xffff0000, v47
	v_cvt_pk_bf16_f32 v5, v16, v17
	v_lshl_add_u64 v[16:17], v[12:13], 0, s[44:45]
	v_pk_fma_f32 v[14:15], v[2:3], v[20:21], v[14:15]
	s_or_b32 s44, s38, 51
	s_mov_b32 s45, s49
	s_waitcnt lgkmcnt(2)
	v_pk_mul_f32 v[46:47], v[22:23], v[46:47] op_sel_hi:[0,1]
	global_store_dword v[16:17], v5, off nt
	v_pk_fma_f32 v[16:17], v[14:15], 0.5, v[44:45] op_sel_hi:[1,0,1] neg_lo:[0,0,1] neg_hi:[0,0,1]
	s_lshl_b64 s[44:45], s[44:45], 9
	v_pk_fma_f32 v[14:15], v[2:3], v[40:41], v[14:15] neg_lo:[1,0,0] neg_hi:[1,0,0]
	v_pk_mul_f32 v[48:49], v[2:3], v[46:47]
	s_waitcnt vmcnt(13)
	v_lshlrev_b32_e32 v50, 16, v51
	v_and_b32_e32 v51, 0xffff0000, v51
	v_cvt_pk_bf16_f32 v5, v16, v17
	v_lshl_add_u64 v[16:17], v[12:13], 0, s[44:45]
	v_pk_fma_f32 v[14:15], v[2:3], v[46:47], v[14:15]
	s_or_b32 s44, s38, 52
	s_mov_b32 s45, s49
	v_pk_mul_f32 v[22:23], v[22:23], v[50:51] op_sel:[1,0]
	global_store_dword v[16:17], v5, off nt
	v_pk_fma_f32 v[16:17], v[14:15], 0.5, v[48:49] op_sel_hi:[1,0,1] neg_lo:[0,0,1] neg_hi:[0,0,1]
	s_lshl_b64 s[44:45], s[44:45], 9
	v_pk_fma_f32 v[14:15], v[2:3], v[20:21], v[14:15] neg_lo:[1,0,0] neg_hi:[1,0,0]
	v_pk_mul_f32 v[50:51], v[2:3], v[22:23]
	s_waitcnt vmcnt(13)
	v_lshlrev_b32_e32 v52, 16, v53
	v_and_b32_e32 v53, 0xffff0000, v53
	v_cvt_pk_bf16_f32 v5, v16, v17
	v_lshl_add_u64 v[16:17], v[12:13], 0, s[44:45]
	v_pk_fma_f32 v[14:15], v[2:3], v[22:23], v[14:15]
	s_or_b32 s44, s38, 53
	s_mov_b32 s45, s49
	v_pk_mul_f32 v[52:53], v[24:25], v[52:53] op_sel_hi:[0,1]
	global_store_dword v[16:17], v5, off nt
	v_pk_fma_f32 v[16:17], v[14:15], 0.5, v[50:51] op_sel_hi:[1,0,1] neg_lo:[0,0,1] neg_hi:[0,0,1]
	s_lshl_b64 s[44:45], s[44:45], 9
	v_pk_fma_f32 v[14:15], v[2:3], v[46:47], v[14:15] neg_lo:[1,0,0] neg_hi:[1,0,0]
	v_pk_mul_f32 v[54:55], v[2:3], v[52:53]
	s_waitcnt vmcnt(13)
	v_lshlrev_b32_e32 v56, 16, v57
	v_and_b32_e32 v57, 0xffff0000, v57
	v_mov_b32_e32 v24, v25
	v_cvt_pk_bf16_f32 v5, v16, v17
	v_lshl_add_u64 v[16:17], v[12:13], 0, s[44:45]
	v_pk_fma_f32 v[14:15], v[2:3], v[52:53], v[14:15]
	s_or_b32 s44, s38, 54
	s_mov_b32 s45, s49
	v_pk_mul_f32 v[24:25], v[24:25], v[56:57] op_sel_hi:[0,1]
	global_store_dword v[16:17], v5, off nt
	v_pk_fma_f32 v[16:17], v[14:15], 0.5, v[54:55] op_sel_hi:[1,0,1] neg_lo:[0,0,1] neg_hi:[0,0,1]
	s_lshl_b64 s[44:45], s[44:45], 9
	v_pk_fma_f32 v[14:15], v[2:3], v[22:23], v[14:15] neg_lo:[1,0,0] neg_hi:[1,0,0]
	v_pk_mul_f32 v[56:57], v[2:3], v[24:25]
	s_waitcnt vmcnt(13)
	v_lshlrev_b32_e32 v58, 16, v59
	v_and_b32_e32 v59, 0xffff0000, v59
	v_cvt_pk_bf16_f32 v5, v16, v17
	v_lshl_add_u64 v[16:17], v[12:13], 0, s[44:45]
	v_pk_fma_f32 v[14:15], v[2:3], v[24:25], v[14:15]
	s_or_b32 s44, s38, 55
	s_mov_b32 s45, s49
	s_waitcnt lgkmcnt(1)
	v_pk_mul_f32 v[58:59], v[26:27], v[58:59] op_sel_hi:[0,1]
	global_store_dword v[16:17], v5, off nt
	v_pk_fma_f32 v[16:17], v[14:15], 0.5, v[56:57] op_sel_hi:[1,0,1] neg_lo:[0,0,1] neg_hi:[0,0,1]
	s_lshl_b64 s[44:45], s[44:45], 9
	v_pk_fma_f32 v[14:15], v[2:3], v[52:53], v[14:15] neg_lo:[1,0,0] neg_hi:[1,0,0]
	v_pk_mul_f32 v[60:61], v[2:3], v[58:59]
	s_waitcnt vmcnt(13)
	v_lshlrev_b32_e32 v62, 16, v63
	v_and_b32_e32 v63, 0xffff0000, v63
	v_cvt_pk_bf16_f32 v5, v16, v17
	v_lshl_add_u64 v[16:17], v[12:13], 0, s[44:45]
	v_pk_fma_f32 v[14:15], v[2:3], v[58:59], v[14:15]
	s_or_b32 s44, s38, 56
	s_mov_b32 s45, s49
	v_pk_mul_f32 v[26:27], v[26:27], v[62:63] op_sel:[1,0]
	global_store_dword v[16:17], v5, off nt
	v_pk_fma_f32 v[16:17], v[14:15], 0.5, v[60:61] op_sel_hi:[1,0,1] neg_lo:[0,0,1] neg_hi:[0,0,1]
	s_lshl_b64 s[44:45], s[44:45], 9
	v_pk_fma_f32 v[14:15], v[2:3], v[24:25], v[14:15] neg_lo:[1,0,0] neg_hi:[1,0,0]
	v_pk_mul_f32 v[62:63], v[2:3], v[26:27]
	s_waitcnt vmcnt(13)
; __device__ __forceinline__ unsigned pk2(float lo, float hi) { f32x2 v = {lo, hi}; bf16x2_t b = __builtin_convertvector(v, bf16x2_t); return __builtin_bit_cast(unsigned, b); }
; template <int W> __device__ __forceinline__ void pool_unit(const bf16_t* x, const LAS float* rs, f32x2 gn, bf16_t* Ag, size_t rb, int t0, int c, int g) {
;     ...
;         for (int i = 0; i < 16; ++i) { const int t = t0 + bt * 16 + i;
;             win += hn_[i]; const float inv = 1.f / (float)((t + 1) < W ? (t + 1) : W);
;             const f32x2 a = win * inv - hn_[i];
;             *(unsigned*)(Ag + ((size_t)g * MT + rb + t) * 256 + (c & 255)) = pk2(a.x, a.y);
;             win -= (i - W + 1 >= 0) ? hn_[(i - W + 1 >= 0) ? (i - W + 1) : 0] : ring[(i - W + 17) & 15]; }
; #pragma unroll
;         for (int i = 0; i < 16; ++i) ring[i] = hn_[i];
; __device__ __forceinline__ void pool_phase(LAS unsigned char* lds, const bf16_t* x, const float* ssq, const float* gain, bf16_t* Ag, int G, int wg) {
;     ...
;     for (int u = wg; u < NB * 32; u += G) {
	v_lshlrev_b32_e32 v64, 16, v65
	v_and_b32_e32 v65, 0xffff0000, v65
	v_cvt_pk_bf16_f32 v5, v16, v17
	v_lshl_add_u64 v[16:17], v[12:13], 0, s[44:45]
	v_pk_fma_f32 v[14:15], v[2:3], v[26:27], v[14:15]
	s_or_b32 s44, s38, 57
	s_mov_b32 s45, s49
	v_pk_mul_f32 v[64:65], v[28:29], v[64:65] op_sel_hi:[0,1]
	global_store_dword v[16:17], v5, off nt
	v_pk_fma_f32 v[16:17], v[14:15], 0.5, v[62:63] op_sel_hi:[1,0,1] neg_lo:[0,0,1] neg_hi:[0,0,1]
	s_lshl_b64 s[44:45], s[44:45], 9
	v_pk_fma_f32 v[14:15], v[2:3], v[58:59], v[14:15] neg_lo:[1,0,0] neg_hi:[1,0,0]
	v_pk_mul_f32 v[66:67], v[2:3], v[64:65]
	s_waitcnt vmcnt(13)
	v_lshlrev_b32_e32 v68, 16, v69
	v_and_b32_e32 v69, 0xffff0000, v69
	v_mov_b32_e32 v28, v29
	v_cvt_pk_bf16_f32 v5, v16, v17
	v_lshl_add_u64 v[16:17], v[12:13], 0, s[44:45]
	v_pk_fma_f32 v[14:15], v[2:3], v[64:65], v[14:15]
	s_or_b32 s44, s38, 58
	s_mov_b32 s45, s49
	v_pk_mul_f32 v[28:29], v[28:29], v[68:69] op_sel_hi:[0,1]
	global_store_dword v[16:17], v5, off nt
	v_pk_fma_f32 v[16:17], v[14:15], 0.5, v[66:67] op_sel_hi:[1,0,1] neg_lo:[0,0,1] neg_hi:[0,0,1]
	s_lshl_b64 s[44:45], s[44:45], 9
	v_pk_fma_f32 v[14:15], v[2:3], v[26:27], v[14:15] neg_lo:[1,0,0] neg_hi:[1,0,0]
	v_pk_mul_f32 v[68:69], v[2:3], v[28:29]
	s_waitcnt vmcnt(13)
	v_lshlrev_b32_e32 v70, 16, v71
	v_and_b32_e32 v71, 0xffff0000, v71
	v_cvt_pk_bf16_f32 v5, v16, v17
	v_lshl_add_u64 v[16:17], v[12:13], 0, s[44:45]
	v_pk_fma_f32 v[14:15], v[2:3], v[28:29], v[14:15]
	s_or_b32 s44, s38, 59
	s_mov_b32 s45, s49
	s_waitcnt lgkmcnt(0)
	v_pk_mul_f32 v[70:71], v[30:31], v[70:71] op_sel_hi:[0,1]
	global_store_dword v[16:17], v5, off nt
	v_pk_fma_f32 v[16:17], v[14:15], 0.5, v[68:69] op_sel_hi:[1,0,1] neg_lo:[0,0,1] neg_hi:[0,0,1]
	s_lshl_b64 s[44:45], s[44:45], 9
	v_pk_fma_f32 v[14:15], v[2:3], v[64:65], v[14:15] neg_lo:[1,0,0] neg_hi:[1,0,0]
	v_pk_mul_f32 v[72:73], v[2:3], v[70:71]
	s_waitcnt vmcnt(13)
	v_lshlrev_b32_e32 v74, 16, v75
	v_and_b32_e32 v75, 0xffff0000, v75
	v_cvt_pk_bf16_f32 v5, v16, v17
	v_lshl_add_u64 v[16:17], v[12:13], 0, s[44:45]
	v_pk_fma_f32 v[14:15], v[2:3], v[70:71], v[14:15]
	s_or_b32 s44, s38, 60
	s_mov_b32 s45, s49
	v_pk_mul_f32 v[30:31], v[30:31], v[74:75] op_sel:[1,0]
	global_store_dword v[16:17], v5, off nt
	v_pk_fma_f32 v[16:17], v[14:15], 0.5, v[72:73] op_sel_hi:[1,0,1] neg_lo:[0,0,1] neg_hi:[0,0,1]
	s_lshl_b64 s[44:45], s[44:45], 9
	v_pk_fma_f32 v[14:15], v[2:3], v[28:29], v[14:15] neg_lo:[1,0,0] neg_hi:[1,0,0]
	v_pk_mul_f32 v[74:75], v[2:3], v[30:31]
	s_waitcnt vmcnt(13)
	v_lshlrev_b32_e32 v76, 16, v77
	v_and_b32_e32 v77, 0xffff0000, v77
	v_cvt_pk_bf16_f32 v5, v16, v17
	v_lshl_add_u64 v[16:17], v[12:13], 0, s[44:45]
	v_pk_fma_f32 v[14:15], v[2:3], v[30:31], v[14:15]
	s_or_b32 s44, s38, 61
	s_mov_b32 s45, s49
	v_pk_mul_f32 v[76:77], v[32:33], v[76:77] op_sel_hi:[0,1]
	global_store_dword v[16:17], v5, off nt
	v_pk_fma_f32 v[16:17], v[14:15], 0.5, v[74:75] op_sel_hi:[1,0,1] neg_lo:[0,0,1] neg_hi:[0,0,1]
	s_lshl_b64 s[44:45], s[44:45], 9
	v_pk_fma_f32 v[14:15], v[2:3], v[70:71], v[14:15] neg_lo:[1,0,0] neg_hi:[1,0,0]
	v_pk_mul_f32 v[78:79], v[2:3], v[76:77]
	s_waitcnt vmcnt(13)
	v_lshlrev_b32_e32 v80, 16, v81
	v_and_b32_e32 v81, 0xffff0000, v81
	v_mov_b32_e32 v32, v33
	v_cvt_pk_bf16_f32 v5, v16, v17
	v_lshl_add_u64 v[16:17], v[12:13], 0, s[44:45]
	v_pk_fma_f32 v[14:15], v[2:3], v[76:77], v[14:15]
	s_or_b32 s38, s38, 62
	v_pk_mul_f32 v[32:33], v[32:33], v[80:81] op_sel_hi:[0,1]
	global_store_dword v[16:17], v5, off nt
	v_pk_fma_f32 v[16:17], v[14:15], 0.5, v[78:79] op_sel_hi:[1,0,1] neg_lo:[0,0,1] neg_hi:[0,0,1]
	s_lshl_b64 s[38:39], s[38:39], 9
	v_pk_fma_f32 v[14:15], v[2:3], v[30:31], v[14:15] neg_lo:[1,0,0] neg_hi:[1,0,0]
	v_pk_mul_f32 v[80:81], v[2:3], v[32:33]
	v_cvt_pk_bf16_f32 v5, v16, v17
	v_lshl_add_u64 v[16:17], v[12:13], 0, s[38:39]
	v_pk_fma_f32 v[14:15], v[2:3], v[32:33], v[14:15]
	global_store_dword v[16:17], v5, off nt
	v_pk_fma_f32 v[16:17], v[14:15], 0.5, v[80:81] op_sel_hi:[1,0,1] neg_lo:[0,0,1] neg_hi:[0,0,1]
	v_mov_b64_e32 v[14:15], s[48:49]
	v_mov_b64_e32 v[18:19], v[0:1]
.LBB0_1172:
	s_or_b64 exec, exec, s[0:1]
	v_readlane_b32 s0, v252, 36
	s_or_b32 s16, s16, 63
	v_readlane_b32 s1, v252, 37
	v_lshl_add_u64 v[14:15], v[14:15], 0, s[16:17]
	v_lshlrev_b64 v[14:15], 9, v[14:15]
	v_lshl_add_u64 v[18:19], v[18:19], 1, s[0:1]
	s_add_i32 s9, s9, s28
	s_add_i32 s8, s8, s66
	v_cvt_pk_bf16_f32 v5, v16, v17
	v_lshl_add_u64 v[14:15], v[18:19], 0, v[14:15]
	s_cmpk_lt_i32 s9, 0x200
	global_store_dword v[14:15], v5, off nt
	s_cbranch_scc0 .LBB0_1245

; __device__ __forceinline__ unsigned pk2(float lo, float hi) { f32x2 v = {lo, hi}; bf16x2_t b = __builtin_convertvector(v, bf16x2_t); return __builtin_bit_cast(unsigned, b); }
; __device__ __forceinline__ f32x2 ldx2(const bf16_t* p) { const unsigned w = *(const unsigned*)p; return (f32x2){__builtin_bit_cast(float, w << 16), __builtin_bit_cast(float, w & 0xffff0000u)}; }
; template <int W> __device__ __forceinline__ void pool_unit(const bf16_t* x, const LAS float* rs, f32x2 gn, bf16_t* Ag, size_t rb, int t0, int c, int g) {
;     ...
;     for (int i = 16 - (W - 1); i < 16; ++i) win += ring[i];
; #pragma unroll
;     for (int bt = 0; bt < 4; ++bt) {
; #pragma unroll
;         for (int i = 0; i < 16; ++i) hn_[i] = ldx2(x + (rb + t0 + bt * 16 + i) * 1024 + c) * rs[16 + bt * 16 + i] * gn;
; #pragma unroll
;         for (int i = 0; i < 16; ++i) { const int t = t0 + bt * 16 + i;
;             win += hn_[i]; const float inv = 1.f / (float)((t + 1) < W ? (t + 1) : W);
;             const f32x2 a = win * inv - hn_[i];
;             *(unsigned*)(Ag + ((size_t)g * MT + rb + t) * 256 + (c & 255)) = pk2(a.x, a.y);
;             win -= (i - W + 1 >= 0) ? hn_[(i - W + 1 >= 0) ? (i - W + 1) : 0] : ring[(i - W + 17) & 15]; }
; #pragma unroll
.LBB0_1204:
	s_or_b32 s44, s48, s16
	s_mov_b32 s45, s49
	s_add_u32 s38, s48, 0x8000
	s_addc_u32 s39, s49, 0
	s_lshl_b64 s[44:45], s[44:45], 11
	v_lshl_add_u64 v[14:15], v[6:7], 0, s[44:45]
	s_movk_i32 s44, 0x1000
	v_add_co_u32_e32 v16, vcc, s44, v14
	global_load_dword v5, v[14:15], off
	global_load_dword v47, v[14:15], off offset:2048
	v_addc_co_u32_e32 v17, vcc, 0, v15, vcc
	v_add_co_u32_e32 v18, vcc, s23, v14
	s_movk_i32 s44, 0x3000
	s_nop 0
	v_addc_co_u32_e32 v19, vcc, 0, v15, vcc
	global_load_dword v50, v[18:19], off offset:-4096
	global_load_dword v51, v[16:17], off offset:2048
	global_load_dword v52, v[18:19], off
	global_load_dword v53, v[18:19], off offset:2048
	v_add_co_u32_e32 v16, vcc, s31, v14
	v_pk_add_f32 v[20:21], v[26:27], 0 op_sel_hi:[1,0]
	s_nop 0
	v_addc_co_u32_e32 v17, vcc, 0, v15, vcc
	v_add_co_u32_e32 v18, vcc, s44, v14
	global_load_dword v55, v[16:17], off offset:-4096
	s_nop 0
	v_addc_co_u32_e32 v19, vcc, 0, v15, vcc
	global_load_dword v72, v[18:19], off offset:2048
	global_load_dword v74, v[16:17], off
	global_load_dword v78, v[16:17], off offset:2048
	v_add_co_u32_e32 v16, vcc, s33, v14
	s_movk_i32 s44, 0x5000
	s_nop 0
	v_addc_co_u32_e32 v17, vcc, 0, v15, vcc
	v_add_co_u32_e32 v18, vcc, s44, v14
	s_movk_i32 s44, 0x7000
	s_nop 0
	v_addc_co_u32_e32 v19, vcc, 0, v15, vcc
	v_add_co_u32_e32 v30, vcc, s19, v14
	global_load_dword v80, v[16:17], off offset:-4096
	s_nop 0
	v_addc_co_u32_e32 v31, vcc, 0, v15, vcc
	global_load_dword v84, v[18:19], off offset:2048
	global_load_dword v86, v[16:17], off
	global_load_dword v88, v[16:17], off offset:2048
	v_add_co_u32_e32 v16, vcc, s44, v14
	global_load_dword v89, v[30:31], off offset:-4096
	s_nop 0
	v_addc_co_u32_e32 v17, vcc, 0, v15, vcc
	global_load_dword v90, v[16:17], off offset:2048
	ds_read_b128 v[16:19], v175 offset:64
	ds_read_b128 v[32:35], v175 offset:80
	ds_read_b128 v[36:39], v175 offset:96
	ds_read_b128 v[40:43], v175 offset:112
	s_min_u32 s44, s16, 3
	s_add_i32 s44, s44, 1
	v_pk_add_f32 v[20:21], v[20:21], v[22:23]
	s_waitcnt vmcnt(15)
	v_lshlrev_b32_e32 v24, 16, v5
	v_and_b32_e32 v25, 0xffff0000, v5
	s_waitcnt vmcnt(14)
	v_lshlrev_b32_e32 v46, 16, v47
	v_and_b32_e32 v47, 0xffff0000, v47
	s_waitcnt lgkmcnt(3)
	v_pk_mul_f32 v[48:49], v[16:17], v[24:25] op_sel_hi:[0,1]
	v_pk_mul_f32 v[46:47], v[16:17], v[46:47] op_sel:[1,0]
	s_waitcnt vmcnt(13)
	v_lshlrev_b32_e32 v16, 16, v50
	v_and_b32_e32 v17, 0xffff0000, v50
	v_pk_mul_f32 v[60:61], v[18:19], v[16:17] op_sel_hi:[0,1]
	s_waitcnt lgkmcnt(2)
	v_mov_b32_e32 v18, v35
	v_cvt_f32_ubyte0_e32 v5, s44
	v_pk_add_f32 v[44:45], v[20:21], v[28:29]
	v_mov_b32_e32 v20, v19
	v_pk_mul_f32 v[56:57], v[2:3], v[48:49]
	v_pk_fma_f32 v[44:45], v[2:3], v[48:49], v[44:45]
	v_pk_mul_f32 v[58:59], v[2:3], v[46:47]
	v_pk_add_f32 v[26:27], v[44:45], v[26:27] neg_lo:[0,1] neg_hi:[0,1]
	s_waitcnt vmcnt(9)
	v_lshlrev_b32_e32 v54, 16, v55
	v_and_b32_e32 v55, 0xffff0000, v55
	s_waitcnt vmcnt(8)
	v_lshlrev_b32_e32 v16, 16, v72
	v_and_b32_e32 v17, 0xffff0000, v72
	v_pk_mul_f32 v[54:55], v[34:35], v[54:55] op_sel_hi:[0,1]
	v_pk_mul_f32 v[34:35], v[18:19], v[16:17] op_sel_hi:[0,1]
	s_waitcnt vmcnt(7)
	v_lshlrev_b32_e32 v16, 16, v74
	v_and_b32_e32 v17, 0xffff0000, v74
	s_waitcnt lgkmcnt(1)
	v_pk_mul_f32 v[74:75], v[36:37], v[16:17] op_sel_hi:[0,1]
	s_waitcnt vmcnt(6)
	v_lshlrev_b32_e32 v16, 16, v78
	v_and_b32_e32 v17, 0xffff0000, v78
	v_pk_mul_f32 v[36:37], v[36:37], v[16:17] op_sel:[1,0]
	v_mov_b32_e32 v18, v39
	v_pk_fma_f32 v[26:27], v[2:3], v[46:47], v[26:27]
	v_lshlrev_b32_e32 v24, 16, v51
	v_pk_add_f32 v[22:23], v[26:27], v[22:23] neg_lo:[0,1] neg_hi:[0,1]
	s_waitcnt vmcnt(5)
	v_lshlrev_b32_e32 v16, 16, v80
	v_and_b32_e32 v17, 0xffff0000, v80
	v_pk_mul_f32 v[80:81], v[38:39], v[16:17] op_sel_hi:[0,1]
	s_waitcnt vmcnt(4)
	v_lshlrev_b32_e32 v16, 16, v84
	v_and_b32_e32 v17, 0xffff0000, v84
	v_pk_mul_f32 v[38:39], v[18:19], v[16:17] op_sel_hi:[0,1]
	v_and_b32_e32 v25, 0xffff0000, v51
	v_lshlrev_b32_e32 v50, 16, v52
	v_and_b32_e32 v51, 0xffff0000, v52
	s_waitcnt vmcnt(0)
	v_lshlrev_b32_e32 v18, 16, v90
	v_and_b32_e32 v19, 0xffff0000, v90
	v_div_scale_f32 v90, s[44:45], v5, v5, 1.0
	v_rcp_f32_e32 v91, v90
	s_or_b32 s44, s16, s38
	s_mov_b32 s45, s39
	s_lshl_b64 s[54:55], s[44:45], 9
	v_fma_f32 v92, -v90, v91, 1.0
	v_fmac_f32_e32 v91, v92, v91
	v_div_scale_f32 v92, vcc, 1.0, v5, 1.0
	v_mul_f32_e32 v93, v92, v91
	v_fma_f32 v94, -v90, v93, v92
	v_fmac_f32_e32 v93, v94, v91
	v_fma_f32 v90, -v90, v93, v92
	v_div_fmas_f32 v90, v90, v91, v93
	v_div_fixup_f32 v90, v90, v5, 1.0
	v_pk_fma_f32 v[56:57], v[90:91], v[44:45], v[56:57] op_sel_hi:[0,1,1] neg_lo:[0,0,1] neg_hi:[0,0,1]
	s_or_b32 s45, s16, 1
	v_cvt_pk_bf16_f32 v5, v56, v57
	v_lshl_add_u64 v[56:57], v[8:9], 0, s[54:55]
	s_min_u32 s54, s45, 3
	s_add_i32 s54, s54, 1
	v_cvt_f32_ubyte0_e32 v90, s54
	v_div_scale_f32 v91, s[54:55], v90, v90, 1.0
	v_rcp_f32_e32 v92, v91
	global_store_dword v[56:57], v5, off nt
	s_or_b32 s54, s38, s45
	s_mov_b32 s55, s39
	v_fma_f32 v5, -v91, v92, 1.0
	v_fmac_f32_e32 v92, v5, v92
	v_div_scale_f32 v5, vcc, 1.0, v90, 1.0
	v_mul_f32_e32 v44, v5, v92
	v_fma_f32 v45, -v91, v44, v5
	v_fmac_f32_e32 v44, v45, v92
	v_fma_f32 v5, -v91, v44, v5
	v_div_fmas_f32 v5, v5, v92, v44
	v_div_fixup_f32 v44, v5, v90, 1.0
	v_pk_fma_f32 v[44:45], v[44:45], v[26:27], v[58:59] op_sel_hi:[0,1,1] neg_lo:[0,0,1] neg_hi:[0,0,1]
	s_lshl_b64 s[54:55], s[54:55], 9
	s_or_b32 s45, s16, 2
	v_cvt_pk_bf16_f32 v5, v44, v45
	v_lshl_add_u64 v[44:45], v[8:9], 0, s[54:55]
	s_min_u32 s54, s45, 3
	s_add_i32 s54, s54, 1
	v_cvt_f32_ubyte0_e32 v56, s54
	v_div_scale_f32 v57, s[54:55], v56, v56, 1.0
	v_rcp_f32_e32 v58, v57
; __device__ __forceinline__ unsigned pk2(float lo, float hi) { f32x2 v = {lo, hi}; bf16x2_t b = __builtin_convertvector(v, bf16x2_t); return __builtin_bit_cast(unsigned, b); }
; __device__ __forceinline__ f32x2 ldx2(const bf16_t* p) { const unsigned w = *(const unsigned*)p; return (f32x2){__builtin_bit_cast(float, w << 16), __builtin_bit_cast(float, w & 0xffff0000u)}; }
; template <int W> __device__ __forceinline__ void pool_unit(const bf16_t* x, const LAS float* rs, f32x2 gn, bf16_t* Ag, size_t rb, int t0, int c, int g) {
;     ...
;     for (int bt = 0; bt < 4; ++bt) {
; #pragma unroll
;         for (int i = 0; i < 16; ++i) hn_[i] = ldx2(x + (rb + t0 + bt * 16 + i) * 1024 + c) * rs[16 + bt * 16 + i] * gn;
; #pragma unroll
;         for (int i = 0; i < 16; ++i) { const int t = t0 + bt * 16 + i;
;             win += hn_[i]; const float inv = 1.f / (float)((t + 1) < W ? (t + 1) : W);
;             const f32x2 a = win * inv - hn_[i];
;             *(unsigned*)(Ag + ((size_t)g * MT + rb + t) * 256 + (c & 255)) = pk2(a.x, a.y);
;             win -= (i - W + 1 >= 0) ? hn_[(i - W + 1 >= 0) ? (i - W + 1) : 0] : ring[(i - W + 17) & 15]; }
; #pragma unroll
	global_store_dword v[44:45], v5, off nt
	v_lshlrev_b32_e32 v52, 16, v53
	v_and_b32_e32 v53, 0xffff0000, v53
	v_fma_f32 v5, -v57, v58, 1.0
	v_fmac_f32_e32 v58, v5, v58
	v_div_scale_f32 v5, vcc, 1.0, v56, 1.0
	v_mul_f32_e32 v26, v5, v58
	v_fma_f32 v27, -v57, v26, v5
	v_fmac_f32_e32 v26, v27, v58
	v_fma_f32 v5, -v57, v26, v5
	v_div_fmas_f32 v5, v5, v58, v26
	v_pk_mul_f32 v[50:51], v[32:33], v[50:51] op_sel_hi:[0,1]
	v_pk_mul_f32 v[32:33], v[32:33], v[52:53] op_sel:[1,0]
	v_pk_mul_f32 v[52:53], v[2:3], v[60:61]
	v_pk_fma_f32 v[22:23], v[2:3], v[60:61], v[22:23]
	v_div_fixup_f32 v26, v5, v56, 1.0
	s_or_b32 s54, s38, s45
	s_mov_b32 s55, s39
	v_pk_mul_f32 v[62:63], v[20:21], v[24:25] op_sel_hi:[0,1]
	v_pk_fma_f32 v[26:27], v[26:27], v[22:23], v[52:53] op_sel_hi:[0,1,1] neg_lo:[0,0,1] neg_hi:[0,0,1]
	s_lshl_b64 s[54:55], s[54:55], 9
	v_pk_add_f32 v[22:23], v[22:23], v[28:29] neg_lo:[0,1] neg_hi:[0,1]
	v_pk_mul_f32 v[64:65], v[2:3], v[62:63]
	v_cvt_pk_bf16_f32 v5, v26, v27
	v_lshl_add_u64 v[26:27], v[8:9], 0, s[54:55]
	v_pk_fma_f32 v[22:23], v[2:3], v[62:63], v[22:23]
	s_or_b32 s54, s44, 3
	s_mov_b32 s55, s39
	global_store_dword v[26:27], v5, off nt
	v_pk_fma_f32 v[26:27], v[22:23], s[34:35], v[64:65] op_sel_hi:[1,0,1] neg_lo:[0,0,1] neg_hi:[0,0,1]
	s_lshl_b64 s[54:55], s[54:55], 9
	v_pk_fma_f32 v[22:23], v[2:3], v[48:49], v[22:23] neg_lo:[1,0,0] neg_hi:[1,0,0]
	v_pk_mul_f32 v[66:67], v[2:3], v[50:51]
	v_cvt_pk_bf16_f32 v5, v26, v27
	v_lshl_add_u64 v[26:27], v[8:9], 0, s[54:55]
	v_pk_fma_f32 v[22:23], v[2:3], v[50:51], v[22:23]
	s_or_b32 s54, s44, 4
	s_mov_b32 s55, s39
	global_store_dword v[26:27], v5, off nt
	v_pk_fma_f32 v[26:27], v[22:23], s[34:35], v[66:67] op_sel_hi:[1,0,1] neg_lo:[0,0,1] neg_hi:[0,0,1]
	s_lshl_b64 s[54:55], s[54:55], 9
	v_pk_fma_f32 v[22:23], v[2:3], v[46:47], v[22:23] neg_lo:[1,0,0] neg_hi:[1,0,0]
	v_pk_mul_f32 v[68:69], v[2:3], v[32:33]
	v_cvt_pk_bf16_f32 v5, v26, v27
	v_lshl_add_u64 v[26:27], v[8:9], 0, s[54:55]
	v_pk_fma_f32 v[22:23], v[2:3], v[32:33], v[22:23]
	s_or_b32 s54, s44, 5
	s_mov_b32 s55, s39
	global_store_dword v[26:27], v5, off nt
	v_pk_fma_f32 v[26:27], v[22:23], s[34:35], v[68:69] op_sel_hi:[1,0,1] neg_lo:[0,0,1] neg_hi:[0,0,1]
	s_lshl_b64 s[54:55], s[54:55], 9
	v_pk_fma_f32 v[22:23], v[2:3], v[60:61], v[22:23] neg_lo:[1,0,0] neg_hi:[1,0,0]
	v_pk_mul_f32 v[70:71], v[2:3], v[54:55]
	v_cvt_pk_bf16_f32 v5, v26, v27
	v_lshl_add_u64 v[26:27], v[8:9], 0, s[54:55]
	v_pk_fma_f32 v[22:23], v[2:3], v[54:55], v[22:23]
	s_or_b32 s54, s44, 6
	s_mov_b32 s55, s39
	global_store_dword v[26:27], v5, off nt
	v_pk_fma_f32 v[26:27], v[22:23], s[34:35], v[70:71] op_sel_hi:[1,0,1] neg_lo:[0,0,1] neg_hi:[0,0,1]
	s_lshl_b64 s[54:55], s[54:55], 9
	v_pk_fma_f32 v[22:23], v[2:3], v[62:63], v[22:23] neg_lo:[1,0,0] neg_hi:[1,0,0]
	v_pk_mul_f32 v[72:73], v[2:3], v[34:35]
	v_cvt_pk_bf16_f32 v5, v26, v27
	v_lshl_add_u64 v[26:27], v[8:9], 0, s[54:55]
	v_pk_fma_f32 v[22:23], v[2:3], v[34:35], v[22:23]
	s_or_b32 s54, s44, 7
	s_mov_b32 s55, s39
	global_store_dword v[26:27], v5, off nt
	v_pk_fma_f32 v[26:27], v[22:23], s[34:35], v[72:73] op_sel_hi:[1,0,1] neg_lo:[0,0,1] neg_hi:[0,0,1]
	s_lshl_b64 s[54:55], s[54:55], 9
	v_pk_fma_f32 v[22:23], v[2:3], v[50:51], v[22:23] neg_lo:[1,0,0] neg_hi:[1,0,0]
	v_pk_mul_f32 v[76:77], v[2:3], v[74:75]
	v_cvt_pk_bf16_f32 v5, v26, v27
	v_lshl_add_u64 v[26:27], v[8:9], 0, s[54:55]
	v_pk_fma_f32 v[22:23], v[2:3], v[74:75], v[22:23]
	s_or_b32 s54, s44, 8
	s_mov_b32 s55, s39
	global_store_dword v[26:27], v5, off nt
	v_pk_fma_f32 v[26:27], v[22:23], s[34:35], v[76:77] op_sel_hi:[1,0,1] neg_lo:[0,0,1] neg_hi:[0,0,1]
	s_lshl_b64 s[54:55], s[54:55], 9
	v_pk_fma_f32 v[22:23], v[2:3], v[32:33], v[22:23] neg_lo:[1,0,0] neg_hi:[1,0,0]
	v_pk_mul_f32 v[78:79], v[2:3], v[36:37]
	v_cvt_pk_bf16_f32 v5, v26, v27
	v_lshl_add_u64 v[26:27], v[8:9], 0, s[54:55]
	v_pk_fma_f32 v[22:23], v[2:3], v[36:37], v[22:23]
	s_or_b32 s54, s44, 9
	s_mov_b32 s55, s39
	global_store_dword v[26:27], v5, off nt
	v_pk_fma_f32 v[26:27], v[22:23], s[34:35], v[78:79] op_sel_hi:[1,0,1] neg_lo:[0,0,1] neg_hi:[0,0,1]
	s_lshl_b64 s[54:55], s[54:55], 9
	v_pk_fma_f32 v[22:23], v[2:3], v[54:55], v[22:23] neg_lo:[1,0,0] neg_hi:[1,0,0]
	v_pk_mul_f32 v[82:83], v[2:3], v[80:81]
	v_cvt_pk_bf16_f32 v5, v26, v27
	v_lshl_add_u64 v[26:27], v[8:9], 0, s[54:55]
	v_pk_fma_f32 v[22:23], v[2:3], v[80:81], v[22:23]
	s_or_b32 s54, s44, 10
	s_mov_b32 s55, s39
	global_store_dword v[26:27], v5, off nt
	v_pk_fma_f32 v[26:27], v[22:23], s[34:35], v[82:83] op_sel_hi:[1,0,1] neg_lo:[0,0,1] neg_hi:[0,0,1]
	s_lshl_b64 s[54:55], s[54:55], 9
	v_pk_fma_f32 v[22:23], v[2:3], v[34:35], v[22:23] neg_lo:[1,0,0] neg_hi:[1,0,0]
	v_pk_mul_f32 v[84:85], v[2:3], v[38:39]
	v_lshlrev_b32_e32 v16, 16, v86
	v_and_b32_e32 v17, 0xffff0000, v86
	v_cvt_pk_bf16_f32 v5, v26, v27
	v_lshl_add_u64 v[26:27], v[8:9], 0, s[54:55]
	v_pk_fma_f32 v[22:23], v[2:3], v[38:39], v[22:23]
	s_or_b32 s54, s44, 11
	s_mov_b32 s55, s39
	s_waitcnt lgkmcnt(0)
; __device__ __forceinline__ unsigned pk2(float lo, float hi) { f32x2 v = {lo, hi}; bf16x2_t b = __builtin_convertvector(v, bf16x2_t); return __builtin_bit_cast(unsigned, b); }
; __device__ __forceinline__ f32x2 ldx2(const bf16_t* p) { const unsigned w = *(const unsigned*)p; return (f32x2){__builtin_bit_cast(float, w << 16), __builtin_bit_cast(float, w & 0xffff0000u)}; }
; template <int W> __device__ __forceinline__ void pool_unit(const bf16_t* x, const LAS float* rs, f32x2 gn, bf16_t* Ag, size_t rb, int t0, int c, int g) {
;     ...
;     for (int bt = 0; bt < 4; ++bt) {
; #pragma unroll
;         for (int i = 0; i < 16; ++i) hn_[i] = ldx2(x + (rb + t0 + bt * 16 + i) * 1024 + c) * rs[16 + bt * 16 + i] * gn;
; #pragma unroll
;         for (int i = 0; i < 16; ++i) { const int t = t0 + bt * 16 + i;
;             win += hn_[i]; const float inv = 1.f / (float)((t + 1) < W ? (t + 1) : W);
;             const f32x2 a = win * inv - hn_[i];
;             *(unsigned*)(Ag + ((size_t)g * MT + rb + t) * 256 + (c & 255)) = pk2(a.x, a.y);
;             win -= (i - W + 1 >= 0) ? hn_[(i - W + 1 >= 0) ? (i - W + 1) : 0] : ring[(i - W + 17) & 15]; }
; #pragma unroll
;         for (int i = 0; i < 16; ++i) ring[i] = hn_[i];
	v_pk_mul_f32 v[24:25], v[40:41], v[16:17] op_sel_hi:[0,1]
	global_store_dword v[26:27], v5, off nt
	v_pk_fma_f32 v[26:27], v[22:23], s[34:35], v[84:85] op_sel_hi:[1,0,1] neg_lo:[0,0,1] neg_hi:[0,0,1]
	s_lshl_b64 s[54:55], s[54:55], 9
	v_pk_fma_f32 v[22:23], v[2:3], v[74:75], v[22:23] neg_lo:[1,0,0] neg_hi:[1,0,0]
	v_pk_mul_f32 v[86:87], v[2:3], v[24:25]
	v_lshlrev_b32_e32 v16, 16, v88
	v_and_b32_e32 v17, 0xffff0000, v88
	v_cvt_pk_bf16_f32 v5, v26, v27
	v_lshl_add_u64 v[26:27], v[8:9], 0, s[54:55]
	v_pk_fma_f32 v[22:23], v[2:3], v[24:25], v[22:23]
	s_or_b32 s54, s44, 12
	s_mov_b32 s55, s39
	v_pk_mul_f32 v[20:21], v[40:41], v[16:17] op_sel:[1,0]
	global_store_dword v[26:27], v5, off nt
	v_pk_fma_f32 v[26:27], v[22:23], s[34:35], v[86:87] op_sel_hi:[1,0,1] neg_lo:[0,0,1] neg_hi:[0,0,1]
	s_lshl_b64 s[54:55], s[54:55], 9
	v_pk_fma_f32 v[22:23], v[2:3], v[36:37], v[22:23] neg_lo:[1,0,0] neg_hi:[1,0,0]
	v_pk_mul_f32 v[40:41], v[2:3], v[20:21]
	v_lshlrev_b32_e32 v16, 16, v89
	v_and_b32_e32 v17, 0xffff0000, v89
	v_cvt_pk_bf16_f32 v5, v26, v27
	v_lshl_add_u64 v[26:27], v[8:9], 0, s[54:55]
	v_pk_fma_f32 v[22:23], v[2:3], v[20:21], v[22:23]
	s_or_b32 s54, s44, 13
	s_mov_b32 s55, s39
	v_pk_mul_f32 v[16:17], v[42:43], v[16:17] op_sel_hi:[0,1]
	global_store_dword v[26:27], v5, off nt
	v_pk_fma_f32 v[26:27], v[22:23], s[34:35], v[40:41] op_sel_hi:[1,0,1] neg_lo:[0,0,1] neg_hi:[0,0,1]
	s_lshl_b64 s[54:55], s[54:55], 9
	v_pk_fma_f32 v[22:23], v[2:3], v[80:81], v[22:23] neg_lo:[1,0,0] neg_hi:[1,0,0]
	v_pk_mul_f32 v[88:89], v[2:3], v[16:17]
	v_mov_b32_e32 v42, v43
	v_cvt_pk_bf16_f32 v5, v26, v27
	v_lshl_add_u64 v[26:27], v[8:9], 0, s[54:55]
	v_pk_fma_f32 v[22:23], v[2:3], v[16:17], v[22:23]
	s_or_b32 s54, s44, 14
	s_mov_b32 s55, s39
	v_pk_mul_f32 v[18:19], v[42:43], v[18:19] op_sel_hi:[0,1]
	global_store_dword v[26:27], v5, off nt
	v_pk_fma_f32 v[26:27], v[22:23], s[34:35], v[88:89] op_sel_hi:[1,0,1] neg_lo:[0,0,1] neg_hi:[0,0,1]
	s_lshl_b64 s[54:55], s[54:55], 9
	v_pk_fma_f32 v[22:23], v[2:3], v[38:39], v[22:23] neg_lo:[1,0,0] neg_hi:[1,0,0]
	v_pk_mul_f32 v[42:43], v[2:3], v[18:19]
	v_cvt_pk_bf16_f32 v5, v26, v27
	v_lshl_add_u64 v[26:27], v[8:9], 0, s[54:55]
	v_pk_fma_f32 v[22:23], v[2:3], v[18:19], v[22:23]
	s_or_b32 s54, s44, 15
	s_mov_b32 s55, s39
	global_store_dword v[26:27], v5, off nt
	v_pk_fma_f32 v[26:27], v[22:23], s[34:35], v[42:43] op_sel_hi:[1,0,1] neg_lo:[0,0,1] neg_hi:[0,0,1]
	s_lshl_b64 s[54:55], s[54:55], 9
	v_cvt_pk_bf16_f32 v5, v26, v27
	v_lshl_add_u64 v[26:27], v[8:9], 0, s[54:55]
	global_store_dword v[26:27], v5, off nt
	global_load_dword v5, v[30:31], off
	s_nop 0
	global_load_dword v47, v[30:31], off offset:2048
	v_add_co_u32_e32 v26, vcc, s92, v14
	s_mov_b32 s45, 0x9000
	s_nop 0
	v_addc_co_u32_e32 v27, vcc, 0, v15, vcc
	global_load_dword v50, v[26:27], off offset:-4096
	v_add_co_u32_e32 v28, vcc, s45, v14
	s_mov_b32 s45, 0xb000
	s_nop 0
	v_addc_co_u32_e32 v29, vcc, 0, v15, vcc
	global_load_dword v54, v[28:29], off offset:2048
	global_load_dword v58, v[26:27], off
	global_load_dword v62, v[26:27], off offset:2048
	v_add_co_u32_e32 v26, vcc, s12, v14
	v_pk_fma_f32 v[40:41], v[2:3], v[24:25], v[22:23] neg_lo:[1,0,0] neg_hi:[1,0,0]
	s_nop 0
	v_addc_co_u32_e32 v27, vcc, 0, v15, vcc
	global_load_dword v66, v[26:27], off offset:-4096
	v_add_co_u32_e32 v28, vcc, s45, v14
	s_mov_b32 s45, 0xe000
	s_nop 0
	v_addc_co_u32_e32 v29, vcc, 0, v15, vcc
	global_load_dword v70, v[28:29], off offset:2048
	global_load_dword v74, v[26:27], off
	global_load_dword v78, v[26:27], off offset:2048
	v_add_co_u32_e32 v26, vcc, s45, v14
	s_mov_b32 s45, 0xd000
	s_nop 0
	v_addc_co_u32_e32 v27, vcc, 0, v15, vcc
	global_load_dword v80, v[26:27], off offset:-4096
	v_add_co_u32_e32 v28, vcc, s45, v14
	s_mov_b32 s45, 0xf000
	s_nop 0
	v_addc_co_u32_e32 v29, vcc, 0, v15, vcc
	global_load_dword v84, v[28:29], off offset:2048
	global_load_dword v86, v[26:27], off
	global_load_dword v88, v[26:27], off offset:2048
	v_add_co_u32_e32 v30, vcc, s63, v14
	ds_read_b128 v[22:25], v175 offset:128
	s_nop 0
	v_addc_co_u32_e32 v31, vcc, 0, v15, vcc
	global_load_dword v89, v[30:31], off offset:-4096
	v_add_co_u32_e32 v26, vcc, s45, v14
	s_or_b32 s54, s44, 16
	s_nop 0
	v_addc_co_u32_e32 v27, vcc, 0, v15, vcc
	global_load_dword v90, v[26:27], off offset:2048
	s_mov_b32 s55, s39
	s_lshl_b64 s[54:55], s[54:55], 9
	ds_read_b128 v[26:29], v175 offset:144
	ds_read_b128 v[32:35], v175 offset:160
	ds_read_b128 v[36:39], v175 offset:176
	s_mov_b32 s45, 0x12000
	s_waitcnt vmcnt(15)
	v_lshlrev_b32_e32 v42, 16, v5
	v_and_b32_e32 v43, 0xffff0000, v5
	s_waitcnt lgkmcnt(3)
	v_pk_mul_f32 v[42:43], v[22:23], v[42:43] op_sel_hi:[0,1]
	v_pk_mul_f32 v[44:45], v[2:3], v[42:43]
	s_waitcnt vmcnt(14)
	v_lshlrev_b32_e32 v46, 16, v47
	v_and_b32_e32 v47, 0xffff0000, v47
	v_pk_fma_f32 v[40:41], v[2:3], v[42:43], v[40:41]
	v_pk_mul_f32 v[46:47], v[22:23], v[46:47] op_sel:[1,0]
	v_pk_fma_f32 v[44:45], v[40:41], s[34:35], v[44:45] op_sel_hi:[1,0,1] neg_lo:[0,0,1] neg_hi:[0,0,1]
	v_pk_fma_f32 v[20:21], v[2:3], v[20:21], v[40:41] neg_lo:[1,0,0] neg_hi:[1,0,0]
	v_pk_mul_f32 v[48:49], v[2:3], v[46:47]
	s_waitcnt vmcnt(13)
	v_lshlrev_b32_e32 v22, 16, v50
	v_and_b32_e32 v23, 0xffff0000, v50
	v_cvt_pk_bf16_f32 v5, v44, v45
	v_lshl_add_u64 v[44:45], v[8:9], 0, s[54:55]
	v_pk_fma_f32 v[20:21], v[2:3], v[46:47], v[20:21]
	s_or_b32 s54, s44, 17
	s_mov_b32 s55, s39
	v_pk_mul_f32 v[50:51], v[24:25], v[22:23] op_sel_hi:[0,1]
	v_pk_fma_f32 v[40:41], v[20:21], s[34:35], v[48:49] op_sel_hi:[1,0,1] neg_lo:[0,0,1] neg_hi:[0,0,1]
	s_lshl_b64 s[54:55], s[54:55], 9
	v_pk_fma_f32 v[16:17], v[2:3], v[16:17], v[20:21] neg_lo:[1,0,0] neg_hi:[1,0,0]
	v_pk_mul_f32 v[52:53], v[2:3], v[50:51]
	s_waitcnt vmcnt(12)
; __device__ __forceinline__ unsigned pk2(float lo, float hi) { f32x2 v = {lo, hi}; bf16x2_t b = __builtin_convertvector(v, bf16x2_t); return __builtin_bit_cast(unsigned, b); }
; __device__ __forceinline__ f32x2 ldx2(const bf16_t* p) { const unsigned w = *(const unsigned*)p; return (f32x2){__builtin_bit_cast(float, w << 16), __builtin_bit_cast(float, w & 0xffff0000u)}; }
; template <int W> __device__ __forceinline__ void pool_unit(const bf16_t* x, const LAS float* rs, f32x2 gn, bf16_t* Ag, size_t rb, int t0, int c, int g) {
;     ...
;     for (int bt = 0; bt < 4; ++bt) {
; #pragma unroll
;         for (int i = 0; i < 16; ++i) hn_[i] = ldx2(x + (rb + t0 + bt * 16 + i) * 1024 + c) * rs[16 + bt * 16 + i] * gn;
; #pragma unroll
;         for (int i = 0; i < 16; ++i) { const int t = t0 + bt * 16 + i;
;             win += hn_[i]; const float inv = 1.f / (float)((t + 1) < W ? (t + 1) : W);
;             const f32x2 a = win * inv - hn_[i];
;             *(unsigned*)(Ag + ((size_t)g * MT + rb + t) * 256 + (c & 255)) = pk2(a.x, a.y);
;             win -= (i - W + 1 >= 0) ? hn_[(i - W + 1 >= 0) ? (i - W + 1) : 0] : ring[(i - W + 17) & 15]; }
; #pragma unroll
	v_lshlrev_b32_e32 v22, 16, v54
	v_and_b32_e32 v23, 0xffff0000, v54
	v_mov_b32_e32 v24, v25
	global_store_dword v[44:45], v5, off nt
	v_cvt_pk_bf16_f32 v5, v40, v41
	v_lshl_add_u64 v[40:41], v[8:9], 0, s[54:55]
	v_pk_fma_f32 v[16:17], v[2:3], v[50:51], v[16:17]
	s_or_b32 s54, s44, 18
	s_mov_b32 s55, s39
	v_pk_mul_f32 v[54:55], v[24:25], v[22:23] op_sel_hi:[0,1]
	v_pk_fma_f32 v[20:21], v[16:17], s[34:35], v[52:53] op_sel_hi:[1,0,1] neg_lo:[0,0,1] neg_hi:[0,0,1]
	s_lshl_b64 s[54:55], s[54:55], 9
	v_pk_fma_f32 v[16:17], v[2:3], v[18:19], v[16:17] neg_lo:[1,0,0] neg_hi:[1,0,0]
	v_pk_mul_f32 v[56:57], v[2:3], v[54:55]
	s_waitcnt vmcnt(12)
	v_lshlrev_b32_e32 v22, 16, v58
	v_and_b32_e32 v23, 0xffff0000, v58
	global_store_dword v[40:41], v5, off nt
	v_cvt_pk_bf16_f32 v5, v20, v21
	v_lshl_add_u64 v[20:21], v[8:9], 0, s[54:55]
	v_pk_fma_f32 v[16:17], v[2:3], v[54:55], v[16:17]
	s_or_b32 s54, s44, 19
	s_mov_b32 s55, s39
	s_waitcnt lgkmcnt(2)
	v_pk_mul_f32 v[58:59], v[26:27], v[22:23] op_sel_hi:[0,1]
	v_pk_fma_f32 v[18:19], v[16:17], s[34:35], v[56:57] op_sel_hi:[1,0,1] neg_lo:[0,0,1] neg_hi:[0,0,1]
	s_lshl_b64 s[54:55], s[54:55], 9
	v_pk_fma_f32 v[16:17], v[2:3], v[42:43], v[16:17] neg_lo:[1,0,0] neg_hi:[1,0,0]
	v_pk_mul_f32 v[60:61], v[2:3], v[58:59]
	s_waitcnt vmcnt(12)
	v_lshlrev_b32_e32 v22, 16, v62
	v_and_b32_e32 v23, 0xffff0000, v62
	global_store_dword v[20:21], v5, off nt
	v_cvt_pk_bf16_f32 v5, v18, v19
	v_lshl_add_u64 v[18:19], v[8:9], 0, s[54:55]
	v_pk_fma_f32 v[16:17], v[2:3], v[58:59], v[16:17]
	s_or_b32 s54, s44, 20
	s_mov_b32 s55, s39
	v_pk_mul_f32 v[62:63], v[26:27], v[22:23] op_sel:[1,0]
	global_store_dword v[18:19], v5, off nt
	v_pk_fma_f32 v[18:19], v[16:17], s[34:35], v[60:61] op_sel_hi:[1,0,1] neg_lo:[0,0,1] neg_hi:[0,0,1]
	s_lshl_b64 s[54:55], s[54:55], 9
	v_pk_fma_f32 v[16:17], v[2:3], v[46:47], v[16:17] neg_lo:[1,0,0] neg_hi:[1,0,0]
	v_pk_mul_f32 v[64:65], v[2:3], v[62:63]
	s_waitcnt vmcnt(13)
	v_lshlrev_b32_e32 v22, 16, v66
	v_and_b32_e32 v23, 0xffff0000, v66
	v_cvt_pk_bf16_f32 v5, v18, v19
	v_lshl_add_u64 v[18:19], v[8:9], 0, s[54:55]
	v_pk_fma_f32 v[16:17], v[2:3], v[62:63], v[16:17]
	s_or_b32 s54, s44, 21
	s_mov_b32 s55, s39
	v_pk_mul_f32 v[66:67], v[28:29], v[22:23] op_sel_hi:[0,1]
	global_store_dword v[18:19], v5, off nt
	v_pk_fma_f32 v[18:19], v[16:17], s[34:35], v[64:65] op_sel_hi:[1,0,1] neg_lo:[0,0,1] neg_hi:[0,0,1]
	s_lshl_b64 s[54:55], s[54:55], 9
	v_pk_fma_f32 v[16:17], v[2:3], v[50:51], v[16:17] neg_lo:[1,0,0] neg_hi:[1,0,0]
	v_pk_mul_f32 v[68:69], v[2:3], v[66:67]
	s_waitcnt vmcnt(13)
	v_lshlrev_b32_e32 v22, 16, v70
	v_and_b32_e32 v23, 0xffff0000, v70
	v_mov_b32_e32 v24, v29
	v_cvt_pk_bf16_f32 v5, v18, v19
	v_lshl_add_u64 v[18:19], v[8:9], 0, s[54:55]
	v_pk_fma_f32 v[16:17], v[2:3], v[66:67], v[16:17]
	s_or_b32 s54, s44, 22
	s_mov_b32 s55, s39
	v_pk_mul_f32 v[70:71], v[24:25], v[22:23] op_sel_hi:[0,1]
	global_store_dword v[18:19], v5, off nt
	v_pk_fma_f32 v[18:19], v[16:17], s[34:35], v[68:69] op_sel_hi:[1,0,1] neg_lo:[0,0,1] neg_hi:[0,0,1]
	s_lshl_b64 s[54:55], s[54:55], 9
	v_pk_fma_f32 v[16:17], v[2:3], v[54:55], v[16:17] neg_lo:[1,0,0] neg_hi:[1,0,0]
	v_pk_mul_f32 v[72:73], v[2:3], v[70:71]
	s_waitcnt vmcnt(13)
	v_lshlrev_b32_e32 v22, 16, v74
	v_and_b32_e32 v23, 0xffff0000, v74
	v_cvt_pk_bf16_f32 v5, v18, v19
	v_lshl_add_u64 v[18:19], v[8:9], 0, s[54:55]
	v_pk_fma_f32 v[16:17], v[2:3], v[70:71], v[16:17]
	s_or_b32 s54, s44, 23
	s_mov_b32 s55, s39
	s_waitcnt lgkmcnt(1)
	v_pk_mul_f32 v[74:75], v[32:33], v[22:23] op_sel_hi:[0,1]
	global_store_dword v[18:19], v5, off nt
	v_pk_fma_f32 v[18:19], v[16:17], s[34:35], v[72:73] op_sel_hi:[1,0,1] neg_lo:[0,0,1] neg_hi:[0,0,1]
	s_lshl_b64 s[54:55], s[54:55], 9
	v_pk_fma_f32 v[16:17], v[2:3], v[58:59], v[16:17] neg_lo:[1,0,0] neg_hi:[1,0,0]
	v_pk_mul_f32 v[76:77], v[2:3], v[74:75]
	s_waitcnt vmcnt(13)
	v_lshlrev_b32_e32 v22, 16, v78
	v_and_b32_e32 v23, 0xffff0000, v78
	v_cvt_pk_bf16_f32 v5, v18, v19
	v_lshl_add_u64 v[18:19], v[8:9], 0, s[54:55]
	v_pk_fma_f32 v[16:17], v[2:3], v[74:75], v[16:17]
	s_or_b32 s54, s44, 24
	s_mov_b32 s55, s39
	v_pk_mul_f32 v[32:33], v[32:33], v[22:23] op_sel:[1,0]
	global_store_dword v[18:19], v5, off nt
	v_pk_fma_f32 v[18:19], v[16:17], s[34:35], v[76:77] op_sel_hi:[1,0,1] neg_lo:[0,0,1] neg_hi:[0,0,1]
	s_lshl_b64 s[54:55], s[54:55], 9
	v_pk_fma_f32 v[16:17], v[2:3], v[62:63], v[16:17] neg_lo:[1,0,0] neg_hi:[1,0,0]
	v_pk_mul_f32 v[78:79], v[2:3], v[32:33]
	s_waitcnt vmcnt(13)
	v_lshlrev_b32_e32 v22, 16, v80
	v_and_b32_e32 v23, 0xffff0000, v80
	v_cvt_pk_bf16_f32 v5, v18, v19
	v_lshl_add_u64 v[18:19], v[8:9], 0, s[54:55]
	v_pk_fma_f32 v[16:17], v[2:3], v[32:33], v[16:17]
	s_or_b32 s54, s44, 25
	s_mov_b32 s55, s39
	v_pk_mul_f32 v[80:81], v[34:35], v[22:23] op_sel_hi:[0,1]
	global_store_dword v[18:19], v5, off nt
	v_pk_fma_f32 v[18:19], v[16:17], s[34:35], v[78:79] op_sel_hi:[1,0,1] neg_lo:[0,0,1] neg_hi:[0,0,1]
	s_lshl_b64 s[54:55], s[54:55], 9
	v_pk_fma_f32 v[16:17], v[2:3], v[66:67], v[16:17] neg_lo:[1,0,0] neg_hi:[1,0,0]
	v_pk_mul_f32 v[82:83], v[2:3], v[80:81]
	s_waitcnt vmcnt(13)
	v_lshlrev_b32_e32 v22, 16, v84
	v_and_b32_e32 v23, 0xffff0000, v84
	v_mov_b32_e32 v24, v35
	v_cvt_pk_bf16_f32 v5, v18, v19
	v_lshl_add_u64 v[18:19], v[8:9], 0, s[54:55]
	v_pk_fma_f32 v[16:17], v[2:3], v[80:81], v[16:17]
	s_or_b32 s54, s44, 26
	s_mov_b32 s55, s39
	v_pk_mul_f32 v[34:35], v[24:25], v[22:23] op_sel_hi:[0,1]
	global_store_dword v[18:19], v5, off nt
	v_pk_fma_f32 v[18:19], v[16:17], s[34:35], v[82:83] op_sel_hi:[1,0,1] neg_lo:[0,0,1] neg_hi:[0,0,1]
	s_lshl_b64 s[54:55], s[54:55], 9
	v_pk_fma_f32 v[16:17], v[2:3], v[70:71], v[16:17] neg_lo:[1,0,0] neg_hi:[1,0,0]
	v_pk_mul_f32 v[84:85], v[2:3], v[34:35]
	s_waitcnt vmcnt(13)
; __device__ __forceinline__ unsigned pk2(float lo, float hi) { f32x2 v = {lo, hi}; bf16x2_t b = __builtin_convertvector(v, bf16x2_t); return __builtin_bit_cast(unsigned, b); }
; __device__ __forceinline__ f32x2 ldx2(const bf16_t* p) { const unsigned w = *(const unsigned*)p; return (f32x2){__builtin_bit_cast(float, w << 16), __builtin_bit_cast(float, w & 0xffff0000u)}; }
; template <int W> __device__ __forceinline__ void pool_unit(const bf16_t* x, const LAS float* rs, f32x2 gn, bf16_t* Ag, size_t rb, int t0, int c, int g) {
;     ...
;     for (int bt = 0; bt < 4; ++bt) {
; #pragma unroll
;         for (int i = 0; i < 16; ++i) hn_[i] = ldx2(x + (rb + t0 + bt * 16 + i) * 1024 + c) * rs[16 + bt * 16 + i] * gn;
; #pragma unroll
;         for (int i = 0; i < 16; ++i) { const int t = t0 + bt * 16 + i;
;             win += hn_[i]; const float inv = 1.f / (float)((t + 1) < W ? (t + 1) : W);
;             const f32x2 a = win * inv - hn_[i];
;             *(unsigned*)(Ag + ((size_t)g * MT + rb + t) * 256 + (c & 255)) = pk2(a.x, a.y);
;             win -= (i - W + 1 >= 0) ? hn_[(i - W + 1 >= 0) ? (i - W + 1) : 0] : ring[(i - W + 17) & 15]; }
; #pragma unroll
;         for (int i = 0; i < 16; ++i) ring[i] = hn_[i];
	v_lshlrev_b32_e32 v22, 16, v86
	v_and_b32_e32 v23, 0xffff0000, v86
	v_cvt_pk_bf16_f32 v5, v18, v19
	v_lshl_add_u64 v[18:19], v[8:9], 0, s[54:55]
	v_pk_fma_f32 v[16:17], v[2:3], v[34:35], v[16:17]
	s_or_b32 s54, s44, 27
	s_mov_b32 s55, s39
	s_waitcnt lgkmcnt(0)
	v_pk_mul_f32 v[28:29], v[36:37], v[22:23] op_sel_hi:[0,1]
	global_store_dword v[18:19], v5, off nt
	v_pk_fma_f32 v[18:19], v[16:17], s[34:35], v[84:85] op_sel_hi:[1,0,1] neg_lo:[0,0,1] neg_hi:[0,0,1]
	s_lshl_b64 s[54:55], s[54:55], 9
	v_pk_fma_f32 v[16:17], v[2:3], v[74:75], v[16:17] neg_lo:[1,0,0] neg_hi:[1,0,0]
	v_pk_mul_f32 v[86:87], v[2:3], v[28:29]
	s_waitcnt vmcnt(13)
	v_lshlrev_b32_e32 v22, 16, v88
	v_and_b32_e32 v23, 0xffff0000, v88
	v_cvt_pk_bf16_f32 v5, v18, v19
	v_lshl_add_u64 v[18:19], v[8:9], 0, s[54:55]
	v_pk_fma_f32 v[16:17], v[2:3], v[28:29], v[16:17]
	s_or_b32 s54, s44, 28
	s_mov_b32 s55, s39
	v_pk_mul_f32 v[26:27], v[36:37], v[22:23] op_sel:[1,0]
	global_store_dword v[18:19], v5, off nt
	v_pk_fma_f32 v[18:19], v[16:17], s[34:35], v[86:87] op_sel_hi:[1,0,1] neg_lo:[0,0,1] neg_hi:[0,0,1]
	s_lshl_b64 s[54:55], s[54:55], 9
	v_pk_fma_f32 v[16:17], v[2:3], v[32:33], v[16:17] neg_lo:[1,0,0] neg_hi:[1,0,0]
	v_pk_mul_f32 v[36:37], v[2:3], v[26:27]
	s_waitcnt vmcnt(13)
	v_lshlrev_b32_e32 v22, 16, v89
	v_and_b32_e32 v23, 0xffff0000, v89
	v_cvt_pk_bf16_f32 v5, v18, v19
	v_lshl_add_u64 v[18:19], v[8:9], 0, s[54:55]
	v_pk_fma_f32 v[16:17], v[2:3], v[26:27], v[16:17]
	s_or_b32 s54, s44, 29
	s_mov_b32 s55, s39
	v_pk_mul_f32 v[24:25], v[38:39], v[22:23] op_sel_hi:[0,1]
	global_store_dword v[18:19], v5, off nt
	v_pk_fma_f32 v[18:19], v[16:17], s[34:35], v[36:37] op_sel_hi:[1,0,1] neg_lo:[0,0,1] neg_hi:[0,0,1]
	s_lshl_b64 s[54:55], s[54:55], 9
	v_pk_fma_f32 v[16:17], v[2:3], v[80:81], v[16:17] neg_lo:[1,0,0] neg_hi:[1,0,0]
	v_pk_mul_f32 v[88:89], v[2:3], v[24:25]
	s_waitcnt vmcnt(13)
	v_lshlrev_b32_e32 v22, 16, v90
	v_and_b32_e32 v23, 0xffff0000, v90
	v_mov_b32_e32 v38, v39
	v_cvt_pk_bf16_f32 v5, v18, v19
	v_lshl_add_u64 v[18:19], v[8:9], 0, s[54:55]
	v_pk_fma_f32 v[16:17], v[2:3], v[24:25], v[16:17]
	s_or_b32 s54, s44, 30
	s_mov_b32 s55, s39
	v_pk_mul_f32 v[22:23], v[38:39], v[22:23] op_sel_hi:[0,1]
	global_store_dword v[18:19], v5, off nt
	v_pk_fma_f32 v[18:19], v[16:17], s[34:35], v[88:89] op_sel_hi:[1,0,1] neg_lo:[0,0,1] neg_hi:[0,0,1]
	s_lshl_b64 s[54:55], s[54:55], 9
	v_pk_fma_f32 v[16:17], v[2:3], v[34:35], v[16:17] neg_lo:[1,0,0] neg_hi:[1,0,0]
	v_pk_mul_f32 v[38:39], v[2:3], v[22:23]
	v_cvt_pk_bf16_f32 v5, v18, v19
	v_lshl_add_u64 v[18:19], v[8:9], 0, s[54:55]
	v_pk_fma_f32 v[16:17], v[2:3], v[22:23], v[16:17]
	s_or_b32 s54, s44, 31
	s_mov_b32 s55, s39
	global_store_dword v[18:19], v5, off nt
	v_pk_fma_f32 v[18:19], v[16:17], s[34:35], v[38:39] op_sel_hi:[1,0,1] neg_lo:[0,0,1] neg_hi:[0,0,1]
	s_lshl_b64 s[54:55], s[54:55], 9
	v_cvt_pk_bf16_f32 v5, v18, v19
	v_lshl_add_u64 v[18:19], v[8:9], 0, s[54:55]
	global_store_dword v[18:19], v5, off nt
	global_load_dword v5, v[30:31], off
	s_nop 0
	global_load_dword v50, v[30:31], off offset:2048
	v_add_co_u32_e32 v18, vcc, s45, v14
	s_mov_b32 s45, 0x11000
	s_nop 0
	v_addc_co_u32_e32 v19, vcc, 0, v15, vcc
	global_load_dword v54, v[18:19], off offset:-4096
	v_add_co_u32_e32 v20, vcc, s45, v14
	s_mov_b32 s45, 0x14000
	s_nop 0
	v_addc_co_u32_e32 v21, vcc, 0, v15, vcc
	global_load_dword v58, v[20:21], off offset:2048
	global_load_dword v62, v[18:19], off
	global_load_dword v66, v[18:19], off offset:2048
	v_add_co_u32_e32 v18, vcc, s45, v14
	s_mov_b32 s45, 0x13000
	s_nop 0
	v_addc_co_u32_e32 v19, vcc, 0, v15, vcc
	global_load_dword v68, v[18:19], off offset:-4096
	v_add_co_u32_e32 v20, vcc, s45, v14
	s_mov_b32 s45, 0x16000
	s_nop 0
	v_addc_co_u32_e32 v21, vcc, 0, v15, vcc
	global_load_dword v72, v[20:21], off offset:2048
	global_load_dword v74, v[18:19], off
	global_load_dword v78, v[18:19], off offset:2048
	v_add_co_u32_e32 v18, vcc, s45, v14
	s_mov_b32 s45, 0x15000
	s_nop 0
	v_addc_co_u32_e32 v19, vcc, 0, v15, vcc
	global_load_dword v80, v[18:19], off offset:-4096
	v_add_co_u32_e32 v20, vcc, s45, v14
	s_mov_b32 s45, 0x18000
	s_nop 0
	v_addc_co_u32_e32 v21, vcc, 0, v15, vcc
	global_load_dword v84, v[20:21], off offset:2048
	global_load_dword v86, v[18:19], off
	global_load_dword v88, v[18:19], off offset:2048
	v_add_co_u32_e32 v30, vcc, s45, v14
	s_mov_b32 s45, 0x17000
	s_nop 0
	v_addc_co_u32_e32 v31, vcc, 0, v15, vcc
	global_load_dword v89, v[30:31], off offset:-4096
	v_add_co_u32_e32 v18, vcc, s45, v14
	v_pk_fma_f32 v[44:45], v[2:3], v[28:29], v[16:17] neg_lo:[1,0,0] neg_hi:[1,0,0]
	s_nop 0
	v_addc_co_u32_e32 v19, vcc, 0, v15, vcc
	global_load_dword v90, v[18:19], off offset:2048
	ds_read_b128 v[16:19], v175 offset:192
	s_or_b32 s54, s44, 32
	s_mov_b32 s55, s39
	s_lshl_b64 s[54:55], s[54:55], 9
	ds_read_b128 v[32:35], v175 offset:208
	ds_read_b128 v[36:39], v175 offset:224
	ds_read_b128 v[40:43], v175 offset:240
	s_mov_b32 s45, 0x1a000
	s_waitcnt vmcnt(15)
	v_lshlrev_b32_e32 v20, 16, v5
	v_and_b32_e32 v21, 0xffff0000, v5
	s_waitcnt lgkmcnt(3)
	v_pk_mul_f32 v[46:47], v[16:17], v[20:21] op_sel_hi:[0,1]
	v_pk_mul_f32 v[48:49], v[2:3], v[46:47]
	s_waitcnt vmcnt(14)
	v_lshlrev_b32_e32 v20, 16, v50
	v_and_b32_e32 v21, 0xffff0000, v50
	v_pk_fma_f32 v[44:45], v[2:3], v[46:47], v[44:45]
	v_pk_mul_f32 v[50:51], v[16:17], v[20:21] op_sel:[1,0]
	v_pk_fma_f32 v[48:49], v[44:45], s[34:35], v[48:49] op_sel_hi:[1,0,1] neg_lo:[0,0,1] neg_hi:[0,0,1]
	v_pk_fma_f32 v[26:27], v[2:3], v[26:27], v[44:45] neg_lo:[1,0,0] neg_hi:[1,0,0]
	v_pk_mul_f32 v[52:53], v[2:3], v[50:51]
	s_waitcnt vmcnt(13)
; __device__ __forceinline__ unsigned pk2(float lo, float hi) { f32x2 v = {lo, hi}; bf16x2_t b = __builtin_convertvector(v, bf16x2_t); return __builtin_bit_cast(unsigned, b); }
; __device__ __forceinline__ f32x2 ldx2(const bf16_t* p) { const unsigned w = *(const unsigned*)p; return (f32x2){__builtin_bit_cast(float, w << 16), __builtin_bit_cast(float, w & 0xffff0000u)}; }
; template <int W> __device__ __forceinline__ void pool_unit(const bf16_t* x, const LAS float* rs, f32x2 gn, bf16_t* Ag, size_t rb, int t0, int c, int g) {
;     ...
;     for (int bt = 0; bt < 4; ++bt) {
; #pragma unroll
;         for (int i = 0; i < 16; ++i) hn_[i] = ldx2(x + (rb + t0 + bt * 16 + i) * 1024 + c) * rs[16 + bt * 16 + i] * gn;
; #pragma unroll
;         for (int i = 0; i < 16; ++i) { const int t = t0 + bt * 16 + i;
;             win += hn_[i]; const float inv = 1.f / (float)((t + 1) < W ? (t + 1) : W);
;             const f32x2 a = win * inv - hn_[i];
;             *(unsigned*)(Ag + ((size_t)g * MT + rb + t) * 256 + (c & 255)) = pk2(a.x, a.y);
;             win -= (i - W + 1 >= 0) ? hn_[(i - W + 1 >= 0) ? (i - W + 1) : 0] : ring[(i - W + 17) & 15]; }
; #pragma unroll
	v_lshlrev_b32_e32 v16, 16, v54
	v_and_b32_e32 v17, 0xffff0000, v54
	v_cvt_pk_bf16_f32 v5, v48, v49
	v_lshl_add_u64 v[48:49], v[8:9], 0, s[54:55]
	v_pk_fma_f32 v[26:27], v[2:3], v[50:51], v[26:27]
	s_or_b32 s54, s44, 33
	s_mov_b32 s55, s39
	v_pk_mul_f32 v[54:55], v[18:19], v[16:17] op_sel_hi:[0,1]
	v_pk_fma_f32 v[44:45], v[26:27], s[34:35], v[52:53] op_sel_hi:[1,0,1] neg_lo:[0,0,1] neg_hi:[0,0,1]
	s_lshl_b64 s[54:55], s[54:55], 9
	v_pk_fma_f32 v[24:25], v[2:3], v[24:25], v[26:27] neg_lo:[1,0,0] neg_hi:[1,0,0]
	v_pk_mul_f32 v[56:57], v[2:3], v[54:55]
	s_waitcnt vmcnt(12)
	v_lshlrev_b32_e32 v16, 16, v58
	v_and_b32_e32 v17, 0xffff0000, v58
	v_mov_b32_e32 v18, v19
	global_store_dword v[48:49], v5, off nt
	v_cvt_pk_bf16_f32 v5, v44, v45
	v_lshl_add_u64 v[44:45], v[8:9], 0, s[54:55]
	v_pk_fma_f32 v[24:25], v[2:3], v[54:55], v[24:25]
	s_or_b32 s54, s44, 34
	s_mov_b32 s55, s39
	v_pk_mul_f32 v[58:59], v[18:19], v[16:17] op_sel_hi:[0,1]
	v_pk_fma_f32 v[26:27], v[24:25], s[34:35], v[56:57] op_sel_hi:[1,0,1] neg_lo:[0,0,1] neg_hi:[0,0,1]
	s_lshl_b64 s[54:55], s[54:55], 9
	v_pk_fma_f32 v[22:23], v[2:3], v[22:23], v[24:25] neg_lo:[1,0,0] neg_hi:[1,0,0]
	v_pk_mul_f32 v[60:61], v[2:3], v[58:59]
	s_waitcnt vmcnt(12)
	v_lshlrev_b32_e32 v16, 16, v62
	v_and_b32_e32 v17, 0xffff0000, v62
	global_store_dword v[44:45], v5, off nt
	v_cvt_pk_bf16_f32 v5, v26, v27
	v_lshl_add_u64 v[26:27], v[8:9], 0, s[54:55]
	v_pk_fma_f32 v[22:23], v[2:3], v[58:59], v[22:23]
	s_or_b32 s54, s44, 35
	s_mov_b32 s55, s39
	s_waitcnt lgkmcnt(2)
	v_pk_mul_f32 v[62:63], v[32:33], v[16:17] op_sel_hi:[0,1]
	v_pk_fma_f32 v[24:25], v[22:23], s[34:35], v[60:61] op_sel_hi:[1,0,1] neg_lo:[0,0,1] neg_hi:[0,0,1]
	s_lshl_b64 s[54:55], s[54:55], 9
	v_pk_fma_f32 v[22:23], v[2:3], v[46:47], v[22:23] neg_lo:[1,0,0] neg_hi:[1,0,0]
	v_pk_mul_f32 v[64:65], v[2:3], v[62:63]
	s_waitcnt vmcnt(12)
	v_lshlrev_b32_e32 v16, 16, v66
	v_and_b32_e32 v17, 0xffff0000, v66
	global_store_dword v[26:27], v5, off nt
	v_cvt_pk_bf16_f32 v5, v24, v25
	v_lshl_add_u64 v[24:25], v[8:9], 0, s[54:55]
	v_pk_fma_f32 v[22:23], v[2:3], v[62:63], v[22:23]
	s_or_b32 s54, s44, 36
	s_mov_b32 s55, s39
	v_pk_mul_f32 v[32:33], v[32:33], v[16:17] op_sel:[1,0]
	global_store_dword v[24:25], v5, off nt
	v_pk_fma_f32 v[24:25], v[22:23], s[34:35], v[64:65] op_sel_hi:[1,0,1] neg_lo:[0,0,1] neg_hi:[0,0,1]
	s_lshl_b64 s[54:55], s[54:55], 9
	v_pk_fma_f32 v[22:23], v[2:3], v[50:51], v[22:23] neg_lo:[1,0,0] neg_hi:[1,0,0]
	v_pk_mul_f32 v[66:67], v[2:3], v[32:33]
	s_waitcnt vmcnt(13)
	v_lshlrev_b32_e32 v16, 16, v68
	v_and_b32_e32 v17, 0xffff0000, v68
	v_cvt_pk_bf16_f32 v5, v24, v25
	v_lshl_add_u64 v[24:25], v[8:9], 0, s[54:55]
	v_pk_fma_f32 v[22:23], v[2:3], v[32:33], v[22:23]
	s_or_b32 s54, s44, 37
	s_mov_b32 s55, s39
	v_pk_mul_f32 v[68:69], v[34:35], v[16:17] op_sel_hi:[0,1]
	global_store_dword v[24:25], v5, off nt
	v_pk_fma_f32 v[24:25], v[22:23], s[34:35], v[66:67] op_sel_hi:[1,0,1] neg_lo:[0,0,1] neg_hi:[0,0,1]
	s_lshl_b64 s[54:55], s[54:55], 9
	v_pk_fma_f32 v[22:23], v[2:3], v[54:55], v[22:23] neg_lo:[1,0,0] neg_hi:[1,0,0]
	v_pk_mul_f32 v[70:71], v[2:3], v[68:69]
	s_waitcnt vmcnt(13)
	v_lshlrev_b32_e32 v16, 16, v72
	v_and_b32_e32 v17, 0xffff0000, v72
	v_mov_b32_e32 v18, v35
	v_cvt_pk_bf16_f32 v5, v24, v25
	v_lshl_add_u64 v[24:25], v[8:9], 0, s[54:55]
	v_pk_fma_f32 v[22:23], v[2:3], v[68:69], v[22:23]
	s_or_b32 s54, s44, 38
	s_mov_b32 s55, s39
	v_pk_mul_f32 v[34:35], v[18:19], v[16:17] op_sel_hi:[0,1]
	global_store_dword v[24:25], v5, off nt
	v_pk_fma_f32 v[24:25], v[22:23], s[34:35], v[70:71] op_sel_hi:[1,0,1] neg_lo:[0,0,1] neg_hi:[0,0,1]
	s_lshl_b64 s[54:55], s[54:55], 9
	v_pk_fma_f32 v[22:23], v[2:3], v[58:59], v[22:23] neg_lo:[1,0,0] neg_hi:[1,0,0]
	v_pk_mul_f32 v[72:73], v[2:3], v[34:35]
	s_waitcnt vmcnt(13)
	v_lshlrev_b32_e32 v16, 16, v74
	v_and_b32_e32 v17, 0xffff0000, v74
	v_cvt_pk_bf16_f32 v5, v24, v25
	v_lshl_add_u64 v[24:25], v[8:9], 0, s[54:55]
	v_pk_fma_f32 v[22:23], v[2:3], v[34:35], v[22:23]
	s_or_b32 s54, s44, 39
	s_mov_b32 s55, s39
	s_waitcnt lgkmcnt(1)
	v_pk_mul_f32 v[74:75], v[36:37], v[16:17] op_sel_hi:[0,1]
	global_store_dword v[24:25], v5, off nt
	v_pk_fma_f32 v[24:25], v[22:23], s[34:35], v[72:73] op_sel_hi:[1,0,1] neg_lo:[0,0,1] neg_hi:[0,0,1]
	s_lshl_b64 s[54:55], s[54:55], 9
	v_pk_fma_f32 v[22:23], v[2:3], v[62:63], v[22:23] neg_lo:[1,0,0] neg_hi:[1,0,0]
	v_pk_mul_f32 v[76:77], v[2:3], v[74:75]
	s_waitcnt vmcnt(13)
	v_lshlrev_b32_e32 v16, 16, v78
	v_and_b32_e32 v17, 0xffff0000, v78
	v_cvt_pk_bf16_f32 v5, v24, v25
	v_lshl_add_u64 v[24:25], v[8:9], 0, s[54:55]
	v_pk_fma_f32 v[22:23], v[2:3], v[74:75], v[22:23]
	s_or_b32 s54, s44, 40
	s_mov_b32 s55, s39
	v_pk_mul_f32 v[36:37], v[36:37], v[16:17] op_sel:[1,0]
	global_store_dword v[24:25], v5, off nt
	v_pk_fma_f32 v[24:25], v[22:23], s[34:35], v[76:77] op_sel_hi:[1,0,1] neg_lo:[0,0,1] neg_hi:[0,0,1]
	s_lshl_b64 s[54:55], s[54:55], 9
	v_pk_fma_f32 v[22:23], v[2:3], v[32:33], v[22:23] neg_lo:[1,0,0] neg_hi:[1,0,0]
	v_pk_mul_f32 v[78:79], v[2:3], v[36:37]
	s_waitcnt vmcnt(13)
	v_lshlrev_b32_e32 v16, 16, v80
	v_and_b32_e32 v17, 0xffff0000, v80
	v_cvt_pk_bf16_f32 v5, v24, v25
	v_lshl_add_u64 v[24:25], v[8:9], 0, s[54:55]
	v_pk_fma_f32 v[22:23], v[2:3], v[36:37], v[22:23]
	s_or_b32 s54, s44, 41
	s_mov_b32 s55, s39
	v_pk_mul_f32 v[80:81], v[38:39], v[16:17] op_sel_hi:[0,1]
	global_store_dword v[24:25], v5, off nt
	v_pk_fma_f32 v[24:25], v[22:23], s[34:35], v[78:79] op_sel_hi:[1,0,1] neg_lo:[0,0,1] neg_hi:[0,0,1]
	s_lshl_b64 s[54:55], s[54:55], 9
	v_pk_fma_f32 v[22:23], v[2:3], v[68:69], v[22:23] neg_lo:[1,0,0] neg_hi:[1,0,0]
	v_pk_mul_f32 v[82:83], v[2:3], v[80:81]
	s_waitcnt vmcnt(13)
; __device__ __forceinline__ unsigned pk2(float lo, float hi) { f32x2 v = {lo, hi}; bf16x2_t b = __builtin_convertvector(v, bf16x2_t); return __builtin_bit_cast(unsigned, b); }
; __device__ __forceinline__ f32x2 ldx2(const bf16_t* p) { const unsigned w = *(const unsigned*)p; return (f32x2){__builtin_bit_cast(float, w << 16), __builtin_bit_cast(float, w & 0xffff0000u)}; }
; template <int W> __device__ __forceinline__ void pool_unit(const bf16_t* x, const LAS float* rs, f32x2 gn, bf16_t* Ag, size_t rb, int t0, int c, int g) {
;     ...
;     for (int bt = 0; bt < 4; ++bt) {
; #pragma unroll
;         for (int i = 0; i < 16; ++i) hn_[i] = ldx2(x + (rb + t0 + bt * 16 + i) * 1024 + c) * rs[16 + bt * 16 + i] * gn;
; #pragma unroll
;         for (int i = 0; i < 16; ++i) { const int t = t0 + bt * 16 + i;
;             win += hn_[i]; const float inv = 1.f / (float)((t + 1) < W ? (t + 1) : W);
;             const f32x2 a = win * inv - hn_[i];
;             *(unsigned*)(Ag + ((size_t)g * MT + rb + t) * 256 + (c & 255)) = pk2(a.x, a.y);
;             win -= (i - W + 1 >= 0) ? hn_[(i - W + 1 >= 0) ? (i - W + 1) : 0] : ring[(i - W + 17) & 15]; }
; #pragma unroll
;         for (int i = 0; i < 16; ++i) ring[i] = hn_[i];
	v_lshlrev_b32_e32 v16, 16, v84
	v_and_b32_e32 v17, 0xffff0000, v84
	v_mov_b32_e32 v18, v39
	v_cvt_pk_bf16_f32 v5, v24, v25
	v_lshl_add_u64 v[24:25], v[8:9], 0, s[54:55]
	v_pk_fma_f32 v[22:23], v[2:3], v[80:81], v[22:23]
	s_or_b32 s54, s44, 42
	s_mov_b32 s55, s39
	v_pk_mul_f32 v[38:39], v[18:19], v[16:17] op_sel_hi:[0,1]
	global_store_dword v[24:25], v5, off nt
	v_pk_fma_f32 v[24:25], v[22:23], s[34:35], v[82:83] op_sel_hi:[1,0,1] neg_lo:[0,0,1] neg_hi:[0,0,1]
	s_lshl_b64 s[54:55], s[54:55], 9
	v_pk_fma_f32 v[22:23], v[2:3], v[34:35], v[22:23] neg_lo:[1,0,0] neg_hi:[1,0,0]
	v_pk_mul_f32 v[84:85], v[2:3], v[38:39]
	s_waitcnt vmcnt(13)
	v_lshlrev_b32_e32 v16, 16, v86
	v_and_b32_e32 v17, 0xffff0000, v86
	v_cvt_pk_bf16_f32 v5, v24, v25
	v_lshl_add_u64 v[24:25], v[8:9], 0, s[54:55]
	v_pk_fma_f32 v[22:23], v[2:3], v[38:39], v[22:23]
	s_or_b32 s54, s44, 43
	s_mov_b32 s55, s39
	s_waitcnt lgkmcnt(0)
	v_pk_mul_f32 v[28:29], v[40:41], v[16:17] op_sel_hi:[0,1]
	global_store_dword v[24:25], v5, off nt
	v_pk_fma_f32 v[24:25], v[22:23], s[34:35], v[84:85] op_sel_hi:[1,0,1] neg_lo:[0,0,1] neg_hi:[0,0,1]
	s_lshl_b64 s[54:55], s[54:55], 9
	v_pk_fma_f32 v[22:23], v[2:3], v[74:75], v[22:23] neg_lo:[1,0,0] neg_hi:[1,0,0]
	v_pk_mul_f32 v[86:87], v[2:3], v[28:29]
	s_waitcnt vmcnt(13)
	v_lshlrev_b32_e32 v16, 16, v88
	v_and_b32_e32 v17, 0xffff0000, v88
	v_cvt_pk_bf16_f32 v5, v24, v25
	v_lshl_add_u64 v[24:25], v[8:9], 0, s[54:55]
	v_pk_fma_f32 v[22:23], v[2:3], v[28:29], v[22:23]
	s_or_b32 s54, s44, 44
	s_mov_b32 s55, s39
	v_pk_mul_f32 v[20:21], v[40:41], v[16:17] op_sel:[1,0]
	global_store_dword v[24:25], v5, off nt
	v_pk_fma_f32 v[24:25], v[22:23], s[34:35], v[86:87] op_sel_hi:[1,0,1] neg_lo:[0,0,1] neg_hi:[0,0,1]
	s_lshl_b64 s[54:55], s[54:55], 9
	v_pk_fma_f32 v[22:23], v[2:3], v[36:37], v[22:23] neg_lo:[1,0,0] neg_hi:[1,0,0]
	v_pk_mul_f32 v[40:41], v[2:3], v[20:21]
	s_waitcnt vmcnt(13)
	v_lshlrev_b32_e32 v16, 16, v89
	v_and_b32_e32 v17, 0xffff0000, v89
	v_cvt_pk_bf16_f32 v5, v24, v25
	v_lshl_add_u64 v[24:25], v[8:9], 0, s[54:55]
	v_pk_fma_f32 v[22:23], v[2:3], v[20:21], v[22:23]
	s_or_b32 s54, s44, 45
	s_mov_b32 s55, s39
	v_pk_mul_f32 v[18:19], v[42:43], v[16:17] op_sel_hi:[0,1]
	global_store_dword v[24:25], v5, off nt
	v_pk_fma_f32 v[24:25], v[22:23], s[34:35], v[40:41] op_sel_hi:[1,0,1] neg_lo:[0,0,1] neg_hi:[0,0,1]
	s_lshl_b64 s[54:55], s[54:55], 9
	v_pk_fma_f32 v[22:23], v[2:3], v[80:81], v[22:23] neg_lo:[1,0,0] neg_hi:[1,0,0]
	v_pk_mul_f32 v[88:89], v[2:3], v[18:19]
	s_waitcnt vmcnt(13)
	v_lshlrev_b32_e32 v16, 16, v90
	v_and_b32_e32 v17, 0xffff0000, v90
	v_mov_b32_e32 v42, v43
	v_cvt_pk_bf16_f32 v5, v24, v25
	v_lshl_add_u64 v[24:25], v[8:9], 0, s[54:55]
	v_pk_fma_f32 v[22:23], v[2:3], v[18:19], v[22:23]
	s_or_b32 s54, s44, 46
	s_mov_b32 s55, s39
	v_pk_mul_f32 v[16:17], v[42:43], v[16:17] op_sel_hi:[0,1]
	global_store_dword v[24:25], v5, off nt
	v_pk_fma_f32 v[24:25], v[22:23], s[34:35], v[88:89] op_sel_hi:[1,0,1] neg_lo:[0,0,1] neg_hi:[0,0,1]
	s_lshl_b64 s[54:55], s[54:55], 9
	v_pk_fma_f32 v[22:23], v[2:3], v[38:39], v[22:23] neg_lo:[1,0,0] neg_hi:[1,0,0]
	v_pk_mul_f32 v[42:43], v[2:3], v[16:17]
	v_cvt_pk_bf16_f32 v5, v24, v25
	v_lshl_add_u64 v[24:25], v[8:9], 0, s[54:55]
	v_pk_fma_f32 v[22:23], v[2:3], v[16:17], v[22:23]
	s_or_b32 s54, s44, 47
	s_mov_b32 s55, s39
	global_store_dword v[24:25], v5, off nt
	v_pk_fma_f32 v[24:25], v[22:23], s[34:35], v[42:43] op_sel_hi:[1,0,1] neg_lo:[0,0,1] neg_hi:[0,0,1]
	s_lshl_b64 s[54:55], s[54:55], 9
	v_cvt_pk_bf16_f32 v5, v24, v25
	v_lshl_add_u64 v[24:25], v[8:9], 0, s[54:55]
	global_store_dword v[24:25], v5, off nt
	global_load_dword v5, v[30:31], off
	s_nop 0
	global_load_dword v43, v[30:31], off offset:2048
	v_add_co_u32_e32 v24, vcc, s45, v14
	s_mov_b32 s45, 0x19000
	s_nop 0
	v_addc_co_u32_e32 v25, vcc, 0, v15, vcc
	global_load_dword v45, v[24:25], off offset:-4096
	v_add_co_u32_e32 v26, vcc, s45, v14
	s_mov_b32 s45, 0x1c000
	s_nop 0
	v_addc_co_u32_e32 v27, vcc, 0, v15, vcc
	global_load_dword v49, v[26:27], off offset:2048
	global_load_dword v51, v[24:25], off
	global_load_dword v55, v[24:25], off offset:2048
	v_add_co_u32_e32 v24, vcc, s45, v14
	s_mov_b32 s45, 0x1b000
	s_nop 0
	v_addc_co_u32_e32 v25, vcc, 0, v15, vcc
	global_load_dword v57, v[24:25], off offset:-4096
	v_add_co_u32_e32 v26, vcc, s45, v14
	s_mov_b32 s45, 0x1e000
	s_nop 0
	v_addc_co_u32_e32 v27, vcc, 0, v15, vcc
	global_load_dword v61, v[26:27], off offset:2048
	global_load_dword v63, v[24:25], off
	global_load_dword v67, v[24:25], off offset:2048
	v_add_co_u32_e32 v24, vcc, s45, v14
	s_mov_b32 s45, 0x1d000
	s_nop 0
	v_addc_co_u32_e32 v25, vcc, 0, v15, vcc
	global_load_dword v69, v[24:25], off offset:-4096
	v_add_co_u32_e32 v26, vcc, s45, v14
	s_mov_b32 s45, 0x1f000
	s_nop 0
	v_addc_co_u32_e32 v27, vcc, 0, v15, vcc
	global_load_dword v73, v[26:27], off offset:2048
	global_load_dword v75, v[24:25], off
	global_load_dword v79, v[24:25], off offset:2048
	v_add_co_u32_e32 v14, vcc, s45, v14
	s_or_b32 s54, s44, 48
	s_nop 0
	v_addc_co_u32_e32 v15, vcc, 0, v15, vcc
	global_load_dword v81, v[14:15], off
	global_load_dword v85, v[14:15], off offset:2048
	v_pk_fma_f32 v[14:15], v[2:3], v[28:29], v[22:23] neg_lo:[1,0,0] neg_hi:[1,0,0]
	ds_read_b128 v[22:25], v175 offset:256
	s_mov_b32 s55, s39
	s_lshl_b64 s[54:55], s[54:55], 9
	ds_read_b128 v[26:29], v175 offset:272
	ds_read_b128 v[30:33], v175 offset:288
	ds_read_b128 v[34:37], v175 offset:304
	s_mov_b32 s45, s39
	s_waitcnt vmcnt(15)
	v_lshlrev_b32_e32 v38, 16, v5
	v_and_b32_e32 v39, 0xffff0000, v5
	s_waitcnt lgkmcnt(3)
	v_pk_mul_f32 v[38:39], v[22:23], v[38:39] op_sel_hi:[0,1]
	v_pk_mul_f32 v[40:41], v[2:3], v[38:39]
	s_waitcnt vmcnt(14)
; __device__ __forceinline__ unsigned pk2(float lo, float hi) { f32x2 v = {lo, hi}; bf16x2_t b = __builtin_convertvector(v, bf16x2_t); return __builtin_bit_cast(unsigned, b); }
; __device__ __forceinline__ f32x2 ldx2(const bf16_t* p) { const unsigned w = *(const unsigned*)p; return (f32x2){__builtin_bit_cast(float, w << 16), __builtin_bit_cast(float, w & 0xffff0000u)}; }
; template <int W> __device__ __forceinline__ void pool_unit(const bf16_t* x, const LAS float* rs, f32x2 gn, bf16_t* Ag, size_t rb, int t0, int c, int g) {
;     ...
;     for (int bt = 0; bt < 4; ++bt) {
; #pragma unroll
;         for (int i = 0; i < 16; ++i) hn_[i] = ldx2(x + (rb + t0 + bt * 16 + i) * 1024 + c) * rs[16 + bt * 16 + i] * gn;
; #pragma unroll
;         for (int i = 0; i < 16; ++i) { const int t = t0 + bt * 16 + i;
;             win += hn_[i]; const float inv = 1.f / (float)((t + 1) < W ? (t + 1) : W);
;             const f32x2 a = win * inv - hn_[i];
;             *(unsigned*)(Ag + ((size_t)g * MT + rb + t) * 256 + (c & 255)) = pk2(a.x, a.y);
;             win -= (i - W + 1 >= 0) ? hn_[(i - W + 1 >= 0) ? (i - W + 1) : 0] : ring[(i - W + 17) & 15]; }
; #pragma unroll
	v_lshlrev_b32_e32 v42, 16, v43
	v_and_b32_e32 v43, 0xffff0000, v43
	v_pk_fma_f32 v[14:15], v[2:3], v[38:39], v[14:15]
	v_pk_mul_f32 v[22:23], v[22:23], v[42:43] op_sel:[1,0]
	v_pk_fma_f32 v[40:41], v[14:15], s[34:35], v[40:41] op_sel_hi:[1,0,1] neg_lo:[0,0,1] neg_hi:[0,0,1]
	v_pk_fma_f32 v[14:15], v[2:3], v[20:21], v[14:15] neg_lo:[1,0,0] neg_hi:[1,0,0]
	v_pk_mul_f32 v[42:43], v[2:3], v[22:23]
	s_waitcnt vmcnt(13)
	v_lshlrev_b32_e32 v44, 16, v45
	v_and_b32_e32 v45, 0xffff0000, v45
	v_cvt_pk_bf16_f32 v5, v40, v41
	v_lshl_add_u64 v[40:41], v[8:9], 0, s[54:55]
	v_pk_fma_f32 v[14:15], v[2:3], v[22:23], v[14:15]
	s_or_b32 s54, s44, 49
	s_mov_b32 s55, s39
	v_pk_mul_f32 v[44:45], v[24:25], v[44:45] op_sel_hi:[0,1]
	v_pk_fma_f32 v[20:21], v[14:15], s[34:35], v[42:43] op_sel_hi:[1,0,1] neg_lo:[0,0,1] neg_hi:[0,0,1]
	s_lshl_b64 s[54:55], s[54:55], 9
	v_pk_fma_f32 v[14:15], v[2:3], v[18:19], v[14:15] neg_lo:[1,0,0] neg_hi:[1,0,0]
	v_pk_mul_f32 v[46:47], v[2:3], v[44:45]
	s_waitcnt vmcnt(12)
	v_lshlrev_b32_e32 v48, 16, v49
	v_and_b32_e32 v49, 0xffff0000, v49
	v_mov_b32_e32 v24, v25
	global_store_dword v[40:41], v5, off nt
	v_cvt_pk_bf16_f32 v5, v20, v21
	v_lshl_add_u64 v[20:21], v[8:9], 0, s[54:55]
	v_pk_fma_f32 v[14:15], v[2:3], v[44:45], v[14:15]
	s_or_b32 s54, s44, 50
	s_mov_b32 s55, s39
	v_pk_mul_f32 v[24:25], v[24:25], v[48:49] op_sel_hi:[0,1]
	v_pk_fma_f32 v[18:19], v[14:15], s[34:35], v[46:47] op_sel_hi:[1,0,1] neg_lo:[0,0,1] neg_hi:[0,0,1]
	s_lshl_b64 s[54:55], s[54:55], 9
	v_pk_fma_f32 v[14:15], v[2:3], v[16:17], v[14:15] neg_lo:[1,0,0] neg_hi:[1,0,0]
	v_pk_mul_f32 v[48:49], v[2:3], v[24:25]
	s_waitcnt vmcnt(12)
	v_lshlrev_b32_e32 v50, 16, v51
	v_and_b32_e32 v51, 0xffff0000, v51
	global_store_dword v[20:21], v5, off nt
	v_cvt_pk_bf16_f32 v5, v18, v19
	v_lshl_add_u64 v[18:19], v[8:9], 0, s[54:55]
	v_pk_fma_f32 v[14:15], v[2:3], v[24:25], v[14:15]
	s_or_b32 s54, s44, 51
	s_mov_b32 s55, s39
	s_waitcnt lgkmcnt(2)
	v_pk_mul_f32 v[50:51], v[26:27], v[50:51] op_sel_hi:[0,1]
	v_pk_fma_f32 v[16:17], v[14:15], s[34:35], v[48:49] op_sel_hi:[1,0,1] neg_lo:[0,0,1] neg_hi:[0,0,1]
	s_lshl_b64 s[54:55], s[54:55], 9
	v_pk_fma_f32 v[14:15], v[2:3], v[38:39], v[14:15] neg_lo:[1,0,0] neg_hi:[1,0,0]
	v_pk_mul_f32 v[52:53], v[2:3], v[50:51]
	s_waitcnt vmcnt(12)
	v_lshlrev_b32_e32 v54, 16, v55
	v_and_b32_e32 v55, 0xffff0000, v55
	global_store_dword v[18:19], v5, off nt
	v_cvt_pk_bf16_f32 v5, v16, v17
	v_lshl_add_u64 v[16:17], v[8:9], 0, s[54:55]
	v_pk_fma_f32 v[14:15], v[2:3], v[50:51], v[14:15]
	s_or_b32 s54, s44, 52
	s_mov_b32 s55, s39
	v_pk_mul_f32 v[26:27], v[26:27], v[54:55] op_sel:[1,0]
	global_store_dword v[16:17], v5, off nt
	v_pk_fma_f32 v[16:17], v[14:15], s[34:35], v[52:53] op_sel_hi:[1,0,1] neg_lo:[0,0,1] neg_hi:[0,0,1]
	s_lshl_b64 s[54:55], s[54:55], 9
	v_pk_fma_f32 v[14:15], v[2:3], v[22:23], v[14:15] neg_lo:[1,0,0] neg_hi:[1,0,0]
	v_pk_mul_f32 v[54:55], v[2:3], v[26:27]
	s_waitcnt vmcnt(13)
	v_lshlrev_b32_e32 v56, 16, v57
	v_and_b32_e32 v57, 0xffff0000, v57
	v_cvt_pk_bf16_f32 v5, v16, v17
	v_lshl_add_u64 v[16:17], v[8:9], 0, s[54:55]
	v_pk_fma_f32 v[14:15], v[2:3], v[26:27], v[14:15]
	s_or_b32 s54, s44, 53
	s_mov_b32 s55, s39
	v_pk_mul_f32 v[56:57], v[28:29], v[56:57] op_sel_hi:[0,1]
	global_store_dword v[16:17], v5, off nt
	v_pk_fma_f32 v[16:17], v[14:15], s[34:35], v[54:55] op_sel_hi:[1,0,1] neg_lo:[0,0,1] neg_hi:[0,0,1]
	s_lshl_b64 s[54:55], s[54:55], 9
	v_pk_fma_f32 v[14:15], v[2:3], v[44:45], v[14:15] neg_lo:[1,0,0] neg_hi:[1,0,0]
	v_pk_mul_f32 v[58:59], v[2:3], v[56:57]
	s_waitcnt vmcnt(13)
	v_lshlrev_b32_e32 v60, 16, v61
	v_and_b32_e32 v61, 0xffff0000, v61
	v_mov_b32_e32 v28, v29
	v_cvt_pk_bf16_f32 v5, v16, v17
	v_lshl_add_u64 v[16:17], v[8:9], 0, s[54:55]
	v_pk_fma_f32 v[14:15], v[2:3], v[56:57], v[14:15]
	s_or_b32 s54, s44, 54
	s_mov_b32 s55, s39
	v_pk_mul_f32 v[28:29], v[28:29], v[60:61] op_sel_hi:[0,1]
	global_store_dword v[16:17], v5, off nt
	v_pk_fma_f32 v[16:17], v[14:15], s[34:35], v[58:59] op_sel_hi:[1,0,1] neg_lo:[0,0,1] neg_hi:[0,0,1]
	s_lshl_b64 s[54:55], s[54:55], 9
	v_pk_fma_f32 v[14:15], v[2:3], v[24:25], v[14:15] neg_lo:[1,0,0] neg_hi:[1,0,0]
	v_pk_mul_f32 v[60:61], v[2:3], v[28:29]
	s_waitcnt vmcnt(13)
	v_lshlrev_b32_e32 v62, 16, v63
	v_and_b32_e32 v63, 0xffff0000, v63
	v_cvt_pk_bf16_f32 v5, v16, v17
	v_lshl_add_u64 v[16:17], v[8:9], 0, s[54:55]
	v_pk_fma_f32 v[14:15], v[2:3], v[28:29], v[14:15]
	s_or_b32 s54, s44, 55
	s_mov_b32 s55, s39
	s_waitcnt lgkmcnt(1)
	v_pk_mul_f32 v[62:63], v[30:31], v[62:63] op_sel_hi:[0,1]
	global_store_dword v[16:17], v5, off nt
	v_pk_fma_f32 v[16:17], v[14:15], s[34:35], v[60:61] op_sel_hi:[1,0,1] neg_lo:[0,0,1] neg_hi:[0,0,1]
	s_lshl_b64 s[54:55], s[54:55], 9
	v_pk_fma_f32 v[14:15], v[2:3], v[50:51], v[14:15] neg_lo:[1,0,0] neg_hi:[1,0,0]
	v_pk_mul_f32 v[64:65], v[2:3], v[62:63]
	s_waitcnt vmcnt(13)
; __device__ __forceinline__ unsigned pk2(float lo, float hi) { f32x2 v = {lo, hi}; bf16x2_t b = __builtin_convertvector(v, bf16x2_t); return __builtin_bit_cast(unsigned, b); }
; __device__ __forceinline__ f32x2 ldx2(const bf16_t* p) { const unsigned w = *(const unsigned*)p; return (f32x2){__builtin_bit_cast(float, w << 16), __builtin_bit_cast(float, w & 0xffff0000u)}; }
; template <int W> __device__ __forceinline__ void pool_unit(const bf16_t* x, const LAS float* rs, f32x2 gn, bf16_t* Ag, size_t rb, int t0, int c, int g) {
;     ...
;     for (int bt = 0; bt < 4; ++bt) {
; #pragma unroll
;         for (int i = 0; i < 16; ++i) hn_[i] = ldx2(x + (rb + t0 + bt * 16 + i) * 1024 + c) * rs[16 + bt * 16 + i] * gn;
; #pragma unroll
;         for (int i = 0; i < 16; ++i) { const int t = t0 + bt * 16 + i;
;             win += hn_[i]; const float inv = 1.f / (float)((t + 1) < W ? (t + 1) : W);
;             const f32x2 a = win * inv - hn_[i];
;             *(unsigned*)(Ag + ((size_t)g * MT + rb + t) * 256 + (c & 255)) = pk2(a.x, a.y);
;             win -= (i - W + 1 >= 0) ? hn_[(i - W + 1 >= 0) ? (i - W + 1) : 0] : ring[(i - W + 17) & 15]; }
; #pragma unroll
;         for (int i = 0; i < 16; ++i) ring[i] = hn_[i];
	v_lshlrev_b32_e32 v66, 16, v67
	v_and_b32_e32 v67, 0xffff0000, v67
	v_cvt_pk_bf16_f32 v5, v16, v17
	v_lshl_add_u64 v[16:17], v[8:9], 0, s[54:55]
	v_pk_fma_f32 v[14:15], v[2:3], v[62:63], v[14:15]
	s_or_b32 s54, s44, 56
	s_mov_b32 s55, s39
	v_pk_mul_f32 v[30:31], v[30:31], v[66:67] op_sel:[1,0]
	global_store_dword v[16:17], v5, off nt
	v_pk_fma_f32 v[16:17], v[14:15], s[34:35], v[64:65] op_sel_hi:[1,0,1] neg_lo:[0,0,1] neg_hi:[0,0,1]
	s_lshl_b64 s[54:55], s[54:55], 9
	v_pk_fma_f32 v[14:15], v[2:3], v[26:27], v[14:15] neg_lo:[1,0,0] neg_hi:[1,0,0]
	v_pk_mul_f32 v[66:67], v[2:3], v[30:31]
	s_waitcnt vmcnt(13)
	v_lshlrev_b32_e32 v68, 16, v69
	v_and_b32_e32 v69, 0xffff0000, v69
	v_cvt_pk_bf16_f32 v5, v16, v17
	v_lshl_add_u64 v[16:17], v[8:9], 0, s[54:55]
	v_pk_fma_f32 v[14:15], v[2:3], v[30:31], v[14:15]
	s_or_b32 s54, s44, 57
	s_mov_b32 s55, s39
	v_pk_mul_f32 v[68:69], v[32:33], v[68:69] op_sel_hi:[0,1]
	global_store_dword v[16:17], v5, off nt
	v_pk_fma_f32 v[16:17], v[14:15], s[34:35], v[66:67] op_sel_hi:[1,0,1] neg_lo:[0,0,1] neg_hi:[0,0,1]
	s_lshl_b64 s[54:55], s[54:55], 9
	v_pk_fma_f32 v[14:15], v[2:3], v[56:57], v[14:15] neg_lo:[1,0,0] neg_hi:[1,0,0]
	v_pk_mul_f32 v[70:71], v[2:3], v[68:69]
	s_waitcnt vmcnt(13)
	v_lshlrev_b32_e32 v72, 16, v73
	v_and_b32_e32 v73, 0xffff0000, v73
	v_mov_b32_e32 v32, v33
	v_cvt_pk_bf16_f32 v5, v16, v17
	v_lshl_add_u64 v[16:17], v[8:9], 0, s[54:55]
	v_pk_fma_f32 v[14:15], v[2:3], v[68:69], v[14:15]
	s_or_b32 s54, s44, 58
	s_mov_b32 s55, s39
	v_pk_mul_f32 v[32:33], v[32:33], v[72:73] op_sel_hi:[0,1]
	global_store_dword v[16:17], v5, off nt
	v_pk_fma_f32 v[16:17], v[14:15], s[34:35], v[70:71] op_sel_hi:[1,0,1] neg_lo:[0,0,1] neg_hi:[0,0,1]
	s_lshl_b64 s[54:55], s[54:55], 9
	v_pk_fma_f32 v[14:15], v[2:3], v[28:29], v[14:15] neg_lo:[1,0,0] neg_hi:[1,0,0]
	v_pk_mul_f32 v[72:73], v[2:3], v[32:33]
	s_waitcnt vmcnt(13)
	v_lshlrev_b32_e32 v74, 16, v75
	v_and_b32_e32 v75, 0xffff0000, v75
	v_cvt_pk_bf16_f32 v5, v16, v17
	v_lshl_add_u64 v[16:17], v[8:9], 0, s[54:55]
	v_pk_fma_f32 v[14:15], v[2:3], v[32:33], v[14:15]
	s_or_b32 s54, s44, 59
	s_mov_b32 s55, s39
	s_waitcnt lgkmcnt(0)
	v_pk_mul_f32 v[74:75], v[34:35], v[74:75] op_sel_hi:[0,1]
	global_store_dword v[16:17], v5, off nt
	v_pk_fma_f32 v[16:17], v[14:15], s[34:35], v[72:73] op_sel_hi:[1,0,1] neg_lo:[0,0,1] neg_hi:[0,0,1]
	s_lshl_b64 s[54:55], s[54:55], 9
	v_pk_fma_f32 v[14:15], v[2:3], v[62:63], v[14:15] neg_lo:[1,0,0] neg_hi:[1,0,0]
	v_pk_mul_f32 v[76:77], v[2:3], v[74:75]
	s_waitcnt vmcnt(13)
	v_lshlrev_b32_e32 v78, 16, v79
	v_and_b32_e32 v79, 0xffff0000, v79
	v_cvt_pk_bf16_f32 v5, v16, v17
	v_lshl_add_u64 v[16:17], v[8:9], 0, s[54:55]
	v_pk_fma_f32 v[14:15], v[2:3], v[74:75], v[14:15]
	s_or_b32 s54, s44, 60
	s_mov_b32 s55, s39
	v_pk_mul_f32 v[34:35], v[34:35], v[78:79] op_sel:[1,0]
	global_store_dword v[16:17], v5, off nt
	v_pk_fma_f32 v[16:17], v[14:15], s[34:35], v[76:77] op_sel_hi:[1,0,1] neg_lo:[0,0,1] neg_hi:[0,0,1]
	s_lshl_b64 s[54:55], s[54:55], 9
	v_pk_fma_f32 v[14:15], v[2:3], v[30:31], v[14:15] neg_lo:[1,0,0] neg_hi:[1,0,0]
	v_pk_mul_f32 v[78:79], v[2:3], v[34:35]
	s_waitcnt vmcnt(13)
	v_lshlrev_b32_e32 v80, 16, v81
	v_and_b32_e32 v81, 0xffff0000, v81
	v_cvt_pk_bf16_f32 v5, v16, v17
	v_lshl_add_u64 v[16:17], v[8:9], 0, s[54:55]
	v_pk_fma_f32 v[14:15], v[2:3], v[34:35], v[14:15]
	s_or_b32 s54, s44, 61
	s_mov_b32 s55, s39
	v_pk_mul_f32 v[80:81], v[36:37], v[80:81] op_sel_hi:[0,1]
	global_store_dword v[16:17], v5, off nt
	v_pk_fma_f32 v[16:17], v[14:15], s[34:35], v[78:79] op_sel_hi:[1,0,1] neg_lo:[0,0,1] neg_hi:[0,0,1]
	s_lshl_b64 s[54:55], s[54:55], 9
	v_pk_fma_f32 v[14:15], v[2:3], v[68:69], v[14:15] neg_lo:[1,0,0] neg_hi:[1,0,0]
	v_pk_mul_f32 v[82:83], v[2:3], v[80:81]
	s_waitcnt vmcnt(13)
	v_lshlrev_b32_e32 v84, 16, v85
	v_and_b32_e32 v85, 0xffff0000, v85
	v_mov_b32_e32 v36, v37
	v_cvt_pk_bf16_f32 v5, v16, v17
	v_lshl_add_u64 v[16:17], v[8:9], 0, s[54:55]
	v_pk_fma_f32 v[14:15], v[2:3], v[80:81], v[14:15]
	s_or_b32 s44, s44, 62
	v_pk_mul_f32 v[36:37], v[36:37], v[84:85] op_sel_hi:[0,1]
	global_store_dword v[16:17], v5, off nt
	v_pk_fma_f32 v[16:17], v[14:15], s[34:35], v[82:83] op_sel_hi:[1,0,1] neg_lo:[0,0,1] neg_hi:[0,0,1]
	s_lshl_b64 s[44:45], s[44:45], 9
	v_pk_fma_f32 v[14:15], v[2:3], v[32:33], v[14:15] neg_lo:[1,0,0] neg_hi:[1,0,0]
	v_pk_mul_f32 v[84:85], v[2:3], v[36:37]
	v_cvt_pk_bf16_f32 v5, v16, v17
	v_lshl_add_u64 v[16:17], v[8:9], 0, s[44:45]
	v_pk_fma_f32 v[14:15], v[2:3], v[36:37], v[14:15]
	global_store_dword v[16:17], v5, off nt
	v_pk_fma_f32 v[16:17], v[14:15], s[34:35], v[84:85] op_sel_hi:[1,0,1] neg_lo:[0,0,1] neg_hi:[0,0,1]
	v_mov_b64_e32 v[14:15], s[38:39]
	s_or_b64 exec, exec, s[0:1]

; __device__ __forceinline__ unsigned pk2(float lo, float hi) { f32x2 v = {lo, hi}; bf16x2_t b = __builtin_convertvector(v, bf16x2_t); return __builtin_bit_cast(unsigned, b); }
; __device__ __forceinline__ f32x2 ldx2(const bf16_t* p) { const unsigned w = *(const unsigned*)p; return (f32x2){__builtin_bit_cast(float, w << 16), __builtin_bit_cast(float, w & 0xffff0000u)}; }
; template <int W> __device__ __forceinline__ void pool_unit(const bf16_t* x, const LAS float* rs, f32x2 gn, bf16_t* Ag, size_t rb, int t0, int c, int g) {
;     ...
;     for (int i = 16 - (W - 1); i < 16; ++i) win += ring[i];
; #pragma unroll
;     for (int bt = 0; bt < 4; ++bt) {
; #pragma unroll
;         for (int i = 0; i < 16; ++i) hn_[i] = ldx2(x + (rb + t0 + bt * 16 + i) * 1024 + c) * rs[16 + bt * 16 + i] * gn;
; #pragma unroll
;         for (int i = 0; i < 16; ++i) { const int t = t0 + bt * 16 + i;
;             win += hn_[i]; const float inv = 1.f / (float)((t + 1) < W ? (t + 1) : W);
;             const f32x2 a = win * inv - hn_[i];
;             *(unsigned*)(Ag + ((size_t)g * MT + rb + t) * 256 + (c & 255)) = pk2(a.x, a.y);
;             win -= (i - W + 1 >= 0) ? hn_[(i - W + 1 >= 0) ? (i - W + 1) : 0] : ring[(i - W + 17) & 15]; }
; #pragma unroll
.LBB0_1209:
	s_or_b32 s56, s48, s16
	s_mov_b32 s57, s49
	s_add_u32 s44, s48, 0x10000
	s_addc_u32 s45, s49, 0
	s_lshl_b64 s[56:57], s[56:57], 11
	v_lshl_add_u64 v[14:15], v[6:7], 0, s[56:57]
	v_add_co_u32_e32 v16, vcc, s23, v14
	s_movk_i32 s56, 0x1000
	s_nop 0
	v_addc_co_u32_e32 v17, vcc, 0, v15, vcc
	v_add_co_u32_e32 v18, vcc, s56, v14
	global_load_dword v5, v[14:15], off
	global_load_dword v27, v[14:15], off offset:2048
	v_addc_co_u32_e32 v19, vcc, 0, v15, vcc
	global_load_dword v44, v[16:17], off offset:-4096
	global_load_dword v45, v[18:19], off offset:2048
	global_load_dword v48, v[16:17], off
	global_load_dword v49, v[16:17], off offset:2048
	v_add_co_u32_e32 v16, vcc, s31, v14
	s_movk_i32 s56, 0x3000
	s_nop 0
	v_addc_co_u32_e32 v17, vcc, 0, v15, vcc
	global_load_dword v50, v[16:17], off offset:-4096
	v_add_co_u32_e32 v18, vcc, s56, v14
	s_movk_i32 s56, 0x5000
	s_nop 0
	v_addc_co_u32_e32 v19, vcc, 0, v15, vcc
	global_load_dword v68, v[18:19], off offset:2048
	global_load_dword v69, v[16:17], off
	global_load_dword v70, v[16:17], off offset:2048
	v_add_co_u32_e32 v16, vcc, s33, v14
	v_pk_add_f32 v[24:25], v[38:39], 0 op_sel_hi:[1,0]
	s_nop 0
	v_addc_co_u32_e32 v17, vcc, 0, v15, vcc
	global_load_dword v71, v[16:17], off offset:-4096
	v_add_co_u32_e32 v18, vcc, s56, v14
	v_pk_add_f32 v[24:25], v[24:25], v[30:31]
	s_nop 0
	v_addc_co_u32_e32 v19, vcc, 0, v15, vcc
	v_add_co_u32_e32 v46, vcc, s19, v14
	global_load_dword v72, v[18:19], off offset:2048
	global_load_dword v104, v[16:17], off
	global_load_dword v105, v[16:17], off offset:2048
	v_addc_co_u32_e32 v47, vcc, 0, v15, vcc
	global_load_dword v106, v[46:47], off offset:-4096
	s_movk_i32 s56, 0x7000
	v_pk_add_f32 v[24:25], v[24:25], v[40:41]
	v_add_co_u32_e32 v16, vcc, s56, v14
	v_pk_add_f32 v[24:25], v[24:25], v[34:35]
	s_nop 0
	v_addc_co_u32_e32 v17, vcc, 0, v15, vcc
	v_pk_add_f32 v[24:25], v[24:25], v[36:37]
	global_load_dword v107, v[16:17], off offset:2048
	ds_read_b128 v[16:19], v175 offset:64
	ds_read_b128 v[20:23], v175 offset:80
	ds_read_b128 v[64:67], v175 offset:96
	ds_read_b128 v[84:87], v175 offset:112
	v_pk_add_f32 v[24:25], v[24:25], v[32:33]
	s_waitcnt lgkmcnt(3)
	v_mov_b32_e32 v26, v19
	v_pk_add_f32 v[88:89], v[24:25], v[42:43]
	s_min_u32 s56, s16, 7
	s_add_i32 s56, s56, 1
	s_waitcnt vmcnt(15)
	v_lshlrev_b32_e32 v24, 16, v5
	v_and_b32_e32 v25, 0xffff0000, v5
	s_waitcnt vmcnt(14)
	v_lshlrev_b32_e32 v28, 16, v27
	v_and_b32_e32 v29, 0xffff0000, v27
	v_pk_mul_f32 v[62:63], v[16:17], v[24:25] op_sel_hi:[0,1]
	v_pk_mul_f32 v[58:59], v[16:17], v[28:29] op_sel:[1,0]
	s_waitcnt vmcnt(13)
	v_lshlrev_b32_e32 v16, 16, v44
	v_and_b32_e32 v17, 0xffff0000, v44
	v_pk_mul_f32 v[60:61], v[18:19], v[16:17] op_sel_hi:[0,1]
	s_waitcnt lgkmcnt(2)
	v_mov_b32_e32 v18, v23
	s_waitcnt vmcnt(12)
	v_lshlrev_b32_e32 v24, 16, v45
	s_waitcnt vmcnt(9)
	v_lshlrev_b32_e32 v16, 16, v50
	v_and_b32_e32 v17, 0xffff0000, v50
	v_pk_mul_f32 v[50:51], v[22:23], v[16:17] op_sel_hi:[0,1]
	v_and_b32_e32 v25, 0xffff0000, v45
	s_waitcnt vmcnt(8)
	v_lshlrev_b32_e32 v16, 16, v68
	v_and_b32_e32 v17, 0xffff0000, v68
	v_lshlrev_b32_e32 v28, 16, v48
	v_and_b32_e32 v29, 0xffff0000, v48
	v_lshlrev_b32_e32 v44, 16, v49
	v_and_b32_e32 v45, 0xffff0000, v49
	v_pk_mul_f32 v[48:49], v[18:19], v[16:17] op_sel_hi:[0,1]
	s_waitcnt vmcnt(7)
	v_lshlrev_b32_e32 v16, 16, v69
	v_and_b32_e32 v17, 0xffff0000, v69
	v_pk_mul_f32 v[52:53], v[20:21], v[44:45] op_sel:[1,0]
	s_waitcnt lgkmcnt(1)
	v_pk_mul_f32 v[44:45], v[64:65], v[16:17] op_sel_hi:[0,1]
	s_waitcnt vmcnt(6)
	v_lshlrev_b32_e32 v16, 16, v70
	v_and_b32_e32 v17, 0xffff0000, v70
	v_pk_mul_f32 v[54:55], v[20:21], v[28:29] op_sel_hi:[0,1]
	v_pk_mul_f32 v[28:29], v[64:65], v[16:17] op_sel:[1,0]
	s_waitcnt vmcnt(5)
	v_lshlrev_b32_e32 v16, 16, v71
	v_and_b32_e32 v17, 0xffff0000, v71
	v_pk_mul_f32 v[56:57], v[26:27], v[24:25] op_sel_hi:[0,1]
	v_pk_mul_f32 v[26:27], v[66:67], v[16:17] op_sel_hi:[0,1]
	s_waitcnt vmcnt(4)
	v_lshlrev_b32_e32 v16, 16, v72
	v_and_b32_e32 v17, 0xffff0000, v72
	v_mov_b32_e32 v18, v67
	v_pk_mul_f32 v[24:25], v[18:19], v[16:17] op_sel_hi:[0,1]
	s_waitcnt vmcnt(3)
	v_lshlrev_b32_e32 v16, 16, v104
	v_and_b32_e32 v17, 0xffff0000, v104
	s_waitcnt lgkmcnt(0)
	v_pk_mul_f32 v[22:23], v[84:85], v[16:17] op_sel_hi:[0,1]
	s_waitcnt vmcnt(2)
	v_lshlrev_b32_e32 v16, 16, v105
	v_and_b32_e32 v17, 0xffff0000, v105
	v_pk_mul_f32 v[20:21], v[84:85], v[16:17] op_sel:[1,0]
	s_waitcnt vmcnt(1)
; __device__ __forceinline__ unsigned pk2(float lo, float hi) { f32x2 v = {lo, hi}; bf16x2_t b = __builtin_convertvector(v, bf16x2_t); return __builtin_bit_cast(unsigned, b); }
; __device__ __forceinline__ f32x2 ldx2(const bf16_t* p) { const unsigned w = *(const unsigned*)p; return (f32x2){__builtin_bit_cast(float, w << 16), __builtin_bit_cast(float, w & 0xffff0000u)}; }
; template <int W> __device__ __forceinline__ void pool_unit(const bf16_t* x, const LAS float* rs, f32x2 gn, bf16_t* Ag, size_t rb, int t0, int c, int g) {
;     ...
;     for (int bt = 0; bt < 4; ++bt) {
; #pragma unroll
;         for (int i = 0; i < 16; ++i) hn_[i] = ldx2(x + (rb + t0 + bt * 16 + i) * 1024 + c) * rs[16 + bt * 16 + i] * gn;
; #pragma unroll
;         for (int i = 0; i < 16; ++i) { const int t = t0 + bt * 16 + i;
;             win += hn_[i]; const float inv = 1.f / (float)((t + 1) < W ? (t + 1) : W);
;             const f32x2 a = win * inv - hn_[i];
;             *(unsigned*)(Ag + ((size_t)g * MT + rb + t) * 256 + (c & 255)) = pk2(a.x, a.y);
;             win -= (i - W + 1 >= 0) ? hn_[(i - W + 1 >= 0) ? (i - W + 1) : 0] : ring[(i - W + 17) & 15]; }
; #pragma unroll
	v_lshlrev_b32_e32 v16, 16, v106
	v_and_b32_e32 v17, 0xffff0000, v106
	v_cvt_f32_ubyte0_e32 v5, s56
	v_pk_mul_f32 v[16:17], v[86:87], v[16:17] op_sel_hi:[0,1]
	v_div_scale_f32 v86, s[56:57], v5, v5, 1.0
	v_mov_b32_e32 v66, v87
	v_rcp_f32_e32 v87, v86
	v_pk_fma_f32 v[84:85], v[2:3], v[62:63], v[88:89]
	v_pk_mul_f32 v[90:91], v[2:3], v[62:63]
	s_or_b32 s56, s16, s44
	v_fma_f32 v88, -v86, v87, 1.0
	v_fmac_f32_e32 v87, v88, v87
	v_div_scale_f32 v88, vcc, 1.0, v5, 1.0
	v_mul_f32_e32 v89, v88, v87
	v_fma_f32 v104, -v86, v89, v88
	v_fmac_f32_e32 v89, v104, v87
	v_fma_f32 v86, -v86, v89, v88
	v_div_fmas_f32 v86, v86, v87, v89
	v_div_fixup_f32 v86, v86, v5, 1.0
	s_mov_b32 s57, s45
	v_pk_fma_f32 v[86:87], v[86:87], v[84:85], v[90:91] op_sel_hi:[0,1,1] neg_lo:[0,0,1] neg_hi:[0,0,1]
	s_lshl_b64 s[58:59], s[56:57], 9
	s_or_b32 s57, s16, 1
	v_cvt_pk_bf16_f32 v5, v86, v87
	v_lshl_add_u64 v[86:87], v[8:9], 0, s[58:59]
	s_min_u32 s58, s57, 7
	s_add_i32 s58, s58, 1
	v_cvt_f32_ubyte0_e32 v88, s58
	v_div_scale_f32 v89, s[58:59], v88, v88, 1.0
	v_rcp_f32_e32 v90, v89
	global_store_dword v[86:87], v5, off nt
	v_pk_add_f32 v[38:39], v[84:85], v[38:39] neg_lo:[0,1] neg_hi:[0,1]
	v_pk_mul_f32 v[92:93], v[2:3], v[58:59]
	v_fma_f32 v5, -v89, v90, 1.0
	v_fmac_f32_e32 v90, v5, v90
	v_div_scale_f32 v5, vcc, 1.0, v88, 1.0
	v_mul_f32_e32 v84, v5, v90
	v_fma_f32 v85, -v89, v84, v5
	v_fmac_f32_e32 v84, v85, v90
	v_fma_f32 v5, -v89, v84, v5
	v_div_fmas_f32 v5, v5, v90, v84
	v_pk_fma_f32 v[38:39], v[2:3], v[58:59], v[38:39]
	v_div_fixup_f32 v84, v5, v88, 1.0
	s_or_b32 s58, s44, s57
	s_mov_b32 s59, s45
	v_pk_fma_f32 v[84:85], v[84:85], v[38:39], v[92:93] op_sel_hi:[0,1,1] neg_lo:[0,0,1] neg_hi:[0,0,1]
	s_lshl_b64 s[58:59], s[58:59], 9
	s_or_b32 s57, s16, 2
	v_cvt_pk_bf16_f32 v5, v84, v85
	v_lshl_add_u64 v[84:85], v[8:9], 0, s[58:59]
	s_min_u32 s58, s57, 7
	s_add_i32 s58, s58, 1
	v_cvt_f32_ubyte0_e32 v86, s58
	v_div_scale_f32 v87, s[58:59], v86, v86, 1.0
	v_rcp_f32_e32 v88, v87
	global_store_dword v[84:85], v5, off nt
	v_pk_add_f32 v[30:31], v[38:39], v[30:31] neg_lo:[0,1] neg_hi:[0,1]
	v_pk_mul_f32 v[94:95], v[2:3], v[60:61]
	v_fma_f32 v5, -v87, v88, 1.0
	v_fmac_f32_e32 v88, v5, v88
	v_div_scale_f32 v5, vcc, 1.0, v86, 1.0
	v_mul_f32_e32 v38, v5, v88
	v_fma_f32 v39, -v87, v38, v5
	v_fmac_f32_e32 v38, v39, v88
	v_fma_f32 v5, -v87, v38, v5
	v_div_fmas_f32 v5, v5, v88, v38
	v_pk_fma_f32 v[30:31], v[2:3], v[60:61], v[30:31]
	v_div_fixup_f32 v38, v5, v86, 1.0
	s_or_b32 s58, s44, s57
	s_mov_b32 s59, s45
	v_pk_fma_f32 v[38:39], v[38:39], v[30:31], v[94:95] op_sel_hi:[0,1,1] neg_lo:[0,0,1] neg_hi:[0,0,1]
	s_lshl_b64 s[58:59], s[58:59], 9
	s_or_b32 s57, s16, 3
	v_cvt_pk_bf16_f32 v5, v38, v39
	v_lshl_add_u64 v[38:39], v[8:9], 0, s[58:59]
	s_min_u32 s58, s57, 7
	s_add_i32 s58, s58, 1
	v_cvt_f32_ubyte0_e32 v84, s58
	v_div_scale_f32 v85, s[58:59], v84, v84, 1.0
	v_rcp_f32_e32 v86, v85
	global_store_dword v[38:39], v5, off nt
	v_pk_add_f32 v[30:31], v[30:31], v[40:41] neg_lo:[0,1] neg_hi:[0,1]
	v_pk_mul_f32 v[96:97], v[2:3], v[56:57]
	v_fma_f32 v5, -v85, v86, 1.0
	v_fmac_f32_e32 v86, v5, v86
	v_div_scale_f32 v5, vcc, 1.0, v84, 1.0
	v_mul_f32_e32 v38, v5, v86
	v_fma_f32 v39, -v85, v38, v5
	v_fmac_f32_e32 v38, v39, v86
	v_fma_f32 v5, -v85, v38, v5
	v_div_fmas_f32 v5, v5, v86, v38
	v_pk_fma_f32 v[30:31], v[2:3], v[56:57], v[30:31]
	v_div_fixup_f32 v38, v5, v84, 1.0
	s_or_b32 s58, s44, s57
	s_mov_b32 s59, s45
	v_pk_fma_f32 v[38:39], v[38:39], v[30:31], v[96:97] op_sel_hi:[0,1,1] neg_lo:[0,0,1] neg_hi:[0,0,1]
	s_lshl_b64 s[58:59], s[58:59], 9
	s_or_b32 s57, s16, 4
	v_cvt_pk_bf16_f32 v5, v38, v39
	v_lshl_add_u64 v[38:39], v[8:9], 0, s[58:59]
	s_min_u32 s58, s57, 7
	s_add_i32 s58, s58, 1
	v_cvt_f32_ubyte0_e32 v40, s58
	v_div_scale_f32 v41, s[58:59], v40, v40, 1.0
	v_rcp_f32_e32 v84, v41
	global_store_dword v[38:39], v5, off nt
	v_pk_add_f32 v[30:31], v[30:31], v[34:35] neg_lo:[0,1] neg_hi:[0,1]
	v_pk_mul_f32 v[98:99], v[2:3], v[54:55]
	v_fma_f32 v5, -v41, v84, 1.0
	v_fmac_f32_e32 v84, v5, v84
	v_div_scale_f32 v5, vcc, 1.0, v40, 1.0
	v_mul_f32_e32 v34, v5, v84
	v_fma_f32 v35, -v41, v34, v5
	v_fmac_f32_e32 v34, v35, v84
	v_fma_f32 v5, -v41, v34, v5
	v_div_fmas_f32 v5, v5, v84, v34
	v_pk_fma_f32 v[30:31], v[2:3], v[54:55], v[30:31]
	v_div_fixup_f32 v34, v5, v40, 1.0
	s_or_b32 s58, s44, s57
	s_mov_b32 s59, s45
	v_pk_fma_f32 v[34:35], v[34:35], v[30:31], v[98:99] op_sel_hi:[0,1,1] neg_lo:[0,0,1] neg_hi:[0,0,1]
	s_lshl_b64 s[58:59], s[58:59], 9
	s_or_b32 s57, s16, 5
	v_cvt_pk_bf16_f32 v5, v34, v35
	v_lshl_add_u64 v[34:35], v[8:9], 0, s[58:59]
	s_min_u32 s58, s57, 7
	s_add_i32 s58, s58, 1
	v_cvt_f32_ubyte0_e32 v38, s58
	v_div_scale_f32 v39, s[58:59], v38, v38, 1.0
	v_rcp_f32_e32 v40, v39
	global_store_dword v[34:35], v5, off nt
	v_pk_add_f32 v[30:31], v[30:31], v[36:37] neg_lo:[0,1] neg_hi:[0,1]
	v_pk_mul_f32 v[100:101], v[2:3], v[52:53]
	v_fma_f32 v5, -v39, v40, 1.0
	v_fmac_f32_e32 v40, v5, v40
	v_div_scale_f32 v5, vcc, 1.0, v38, 1.0
	v_mul_f32_e32 v34, v5, v40
	v_fma_f32 v35, -v39, v34, v5
	v_fmac_f32_e32 v34, v35, v40
	v_fma_f32 v5, -v39, v34, v5
	v_div_fmas_f32 v5, v5, v40, v34
	v_pk_fma_f32 v[30:31], v[2:3], v[52:53], v[30:31]
	v_div_fixup_f32 v34, v5, v38, 1.0
	s_or_b32 s58, s44, s57
	s_mov_b32 s59, s45
	v_pk_fma_f32 v[34:35], v[34:35], v[30:31], v[100:101] op_sel_hi:[0,1,1] neg_lo:[0,0,1] neg_hi:[0,0,1]
	s_lshl_b64 s[58:59], s[58:59], 9
	s_or_b32 s57, s16, 6
	v_cvt_pk_bf16_f32 v5, v34, v35
	v_lshl_add_u64 v[34:35], v[8:9], 0, s[58:59]
	s_min_u32 s58, s57, 7
	s_add_i32 s58, s58, 1
	v_cvt_f32_ubyte0_e32 v36, s58
	v_div_scale_f32 v37, s[58:59], v36, v36, 1.0
	v_rcp_f32_e32 v38, v37
; __device__ __forceinline__ unsigned pk2(float lo, float hi) { f32x2 v = {lo, hi}; bf16x2_t b = __builtin_convertvector(v, bf16x2_t); return __builtin_bit_cast(unsigned, b); }
; __device__ __forceinline__ f32x2 ldx2(const bf16_t* p) { const unsigned w = *(const unsigned*)p; return (f32x2){__builtin_bit_cast(float, w << 16), __builtin_bit_cast(float, w & 0xffff0000u)}; }
; template <int W> __device__ __forceinline__ void pool_unit(const bf16_t* x, const LAS float* rs, f32x2 gn, bf16_t* Ag, size_t rb, int t0, int c, int g) {
;     ...
;     for (int bt = 0; bt < 4; ++bt) {
; #pragma unroll
;         for (int i = 0; i < 16; ++i) hn_[i] = ldx2(x + (rb + t0 + bt * 16 + i) * 1024 + c) * rs[16 + bt * 16 + i] * gn;
; #pragma unroll
;         for (int i = 0; i < 16; ++i) { const int t = t0 + bt * 16 + i;
;             win += hn_[i]; const float inv = 1.f / (float)((t + 1) < W ? (t + 1) : W);
;             const f32x2 a = win * inv - hn_[i];
;             *(unsigned*)(Ag + ((size_t)g * MT + rb + t) * 256 + (c & 255)) = pk2(a.x, a.y);
;             win -= (i - W + 1 >= 0) ? hn_[(i - W + 1 >= 0) ? (i - W + 1) : 0] : ring[(i - W + 17) & 15]; }
; #pragma unroll
;         for (int i = 0; i < 16; ++i) ring[i] = hn_[i];
	global_store_dword v[34:35], v5, off nt
	v_pk_add_f32 v[30:31], v[30:31], v[32:33] neg_lo:[0,1] neg_hi:[0,1]
	v_pk_mul_f32 v[82:83], v[2:3], v[50:51]
	v_fma_f32 v5, -v37, v38, 1.0
	v_fmac_f32_e32 v38, v5, v38
	v_div_scale_f32 v5, vcc, 1.0, v36, 1.0
	v_mul_f32_e32 v32, v5, v38
	v_fma_f32 v33, -v37, v32, v5
	v_fmac_f32_e32 v32, v33, v38
	v_fma_f32 v5, -v37, v32, v5
	v_div_fmas_f32 v5, v5, v38, v32
	v_pk_fma_f32 v[30:31], v[2:3], v[50:51], v[30:31]
	v_div_fixup_f32 v32, v5, v36, 1.0
	s_or_b32 s58, s44, s57
	s_mov_b32 s59, s45
	v_pk_fma_f32 v[32:33], v[32:33], v[30:31], v[82:83] op_sel_hi:[0,1,1] neg_lo:[0,0,1] neg_hi:[0,0,1]
	s_lshl_b64 s[58:59], s[58:59], 9
	v_pk_add_f32 v[30:31], v[30:31], v[42:43] neg_lo:[0,1] neg_hi:[0,1]
	v_pk_mul_f32 v[80:81], v[2:3], v[48:49]
	v_cvt_pk_bf16_f32 v5, v32, v33
	v_lshl_add_u64 v[32:33], v[8:9], 0, s[58:59]
	v_pk_fma_f32 v[30:31], v[2:3], v[48:49], v[30:31]
	s_or_b32 s58, s56, 7
	s_mov_b32 s59, s45
	global_store_dword v[32:33], v5, off nt
	v_pk_fma_f32 v[32:33], v[30:31], s[22:23], v[80:81] op_sel_hi:[1,0,1] neg_lo:[0,0,1] neg_hi:[0,0,1]
	s_lshl_b64 s[58:59], s[58:59], 9
	v_pk_fma_f32 v[30:31], v[2:3], v[62:63], v[30:31] neg_lo:[1,0,0] neg_hi:[1,0,0]
	v_pk_mul_f32 v[78:79], v[2:3], v[44:45]
	v_cvt_pk_bf16_f32 v5, v32, v33
	v_lshl_add_u64 v[32:33], v[8:9], 0, s[58:59]
	v_pk_fma_f32 v[30:31], v[2:3], v[44:45], v[30:31]
	s_or_b32 s58, s56, 8
	s_mov_b32 s59, s45
	global_store_dword v[32:33], v5, off nt
	v_pk_fma_f32 v[32:33], v[30:31], s[22:23], v[78:79] op_sel_hi:[1,0,1] neg_lo:[0,0,1] neg_hi:[0,0,1]
	s_lshl_b64 s[58:59], s[58:59], 9
	v_pk_fma_f32 v[30:31], v[2:3], v[58:59], v[30:31] neg_lo:[1,0,0] neg_hi:[1,0,0]
	v_pk_mul_f32 v[76:77], v[2:3], v[28:29]
	v_cvt_pk_bf16_f32 v5, v32, v33
	v_lshl_add_u64 v[32:33], v[8:9], 0, s[58:59]
	v_pk_fma_f32 v[30:31], v[2:3], v[28:29], v[30:31]
	s_or_b32 s58, s56, 9
	s_mov_b32 s59, s45
	global_store_dword v[32:33], v5, off nt
	v_pk_fma_f32 v[32:33], v[30:31], s[22:23], v[76:77] op_sel_hi:[1,0,1] neg_lo:[0,0,1] neg_hi:[0,0,1]
	s_lshl_b64 s[58:59], s[58:59], 9
	v_pk_fma_f32 v[30:31], v[2:3], v[60:61], v[30:31] neg_lo:[1,0,0] neg_hi:[1,0,0]
	v_pk_mul_f32 v[74:75], v[2:3], v[26:27]
	v_cvt_pk_bf16_f32 v5, v32, v33
	v_lshl_add_u64 v[32:33], v[8:9], 0, s[58:59]
	v_pk_fma_f32 v[30:31], v[2:3], v[26:27], v[30:31]
	s_or_b32 s58, s56, 10
	s_mov_b32 s59, s45
	global_store_dword v[32:33], v5, off nt
	v_pk_fma_f32 v[32:33], v[30:31], s[22:23], v[74:75] op_sel_hi:[1,0,1] neg_lo:[0,0,1] neg_hi:[0,0,1]
	s_lshl_b64 s[58:59], s[58:59], 9
	v_pk_fma_f32 v[30:31], v[2:3], v[56:57], v[30:31] neg_lo:[1,0,0] neg_hi:[1,0,0]
	v_pk_mul_f32 v[72:73], v[2:3], v[24:25]
	v_cvt_pk_bf16_f32 v5, v32, v33
	v_lshl_add_u64 v[32:33], v[8:9], 0, s[58:59]
	v_pk_fma_f32 v[30:31], v[2:3], v[24:25], v[30:31]
	s_or_b32 s58, s56, 11
	s_mov_b32 s59, s45
	global_store_dword v[32:33], v5, off nt
	v_pk_fma_f32 v[32:33], v[30:31], s[22:23], v[72:73] op_sel_hi:[1,0,1] neg_lo:[0,0,1] neg_hi:[0,0,1]
	s_lshl_b64 s[58:59], s[58:59], 9
	v_pk_fma_f32 v[30:31], v[2:3], v[54:55], v[30:31] neg_lo:[1,0,0] neg_hi:[1,0,0]
	v_pk_mul_f32 v[70:71], v[2:3], v[22:23]
	v_cvt_pk_bf16_f32 v5, v32, v33
	v_lshl_add_u64 v[32:33], v[8:9], 0, s[58:59]
	v_pk_fma_f32 v[30:31], v[2:3], v[22:23], v[30:31]
	s_or_b32 s58, s56, 12
	s_mov_b32 s59, s45
	global_store_dword v[32:33], v5, off nt
	v_pk_fma_f32 v[32:33], v[30:31], s[22:23], v[70:71] op_sel_hi:[1,0,1] neg_lo:[0,0,1] neg_hi:[0,0,1]
	s_lshl_b64 s[58:59], s[58:59], 9
	v_pk_fma_f32 v[30:31], v[2:3], v[52:53], v[30:31] neg_lo:[1,0,0] neg_hi:[1,0,0]
	v_pk_mul_f32 v[68:69], v[2:3], v[20:21]
	v_cvt_pk_bf16_f32 v5, v32, v33
	v_lshl_add_u64 v[32:33], v[8:9], 0, s[58:59]
	v_pk_fma_f32 v[30:31], v[2:3], v[20:21], v[30:31]
	s_or_b32 s58, s56, 13
	s_mov_b32 s59, s45
	global_store_dword v[32:33], v5, off nt
	v_pk_fma_f32 v[32:33], v[30:31], s[22:23], v[68:69] op_sel_hi:[1,0,1] neg_lo:[0,0,1] neg_hi:[0,0,1]
	s_lshl_b64 s[58:59], s[58:59], 9
	v_pk_fma_f32 v[30:31], v[2:3], v[50:51], v[30:31] neg_lo:[1,0,0] neg_hi:[1,0,0]
	v_pk_mul_f32 v[64:65], v[2:3], v[16:17]
	s_waitcnt vmcnt(13)
	v_lshlrev_b32_e32 v18, 16, v107
	v_and_b32_e32 v19, 0xffff0000, v107
	v_cvt_pk_bf16_f32 v5, v32, v33
	v_lshl_add_u64 v[32:33], v[8:9], 0, s[58:59]
	v_pk_fma_f32 v[30:31], v[2:3], v[16:17], v[30:31]
	s_or_b32 s58, s56, 14
	s_mov_b32 s59, s45
	v_pk_mul_f32 v[18:19], v[66:67], v[18:19] op_sel_hi:[0,1]
	global_store_dword v[32:33], v5, off nt
	v_pk_fma_f32 v[32:33], v[30:31], s[22:23], v[64:65] op_sel_hi:[1,0,1] neg_lo:[0,0,1] neg_hi:[0,0,1]
	s_lshl_b64 s[58:59], s[58:59], 9
	v_pk_fma_f32 v[30:31], v[2:3], v[48:49], v[30:31] neg_lo:[1,0,0] neg_hi:[1,0,0]
	v_pk_mul_f32 v[66:67], v[2:3], v[18:19]
	v_cvt_pk_bf16_f32 v5, v32, v33
	v_lshl_add_u64 v[32:33], v[8:9], 0, s[58:59]
	v_pk_fma_f32 v[30:31], v[2:3], v[18:19], v[30:31]
	s_or_b32 s58, s56, 15
	s_mov_b32 s59, s45
	global_store_dword v[32:33], v5, off nt
	v_pk_fma_f32 v[32:33], v[30:31], s[22:23], v[66:67] op_sel_hi:[1,0,1] neg_lo:[0,0,1] neg_hi:[0,0,1]
	s_lshl_b64 s[58:59], s[58:59], 9
	v_cvt_pk_bf16_f32 v5, v32, v33
	v_lshl_add_u64 v[32:33], v[8:9], 0, s[58:59]
	global_store_dword v[32:33], v5, off nt
	global_load_dword v5, v[46:47], off
	s_nop 0
	global_load_dword v40, v[46:47], off offset:2048
	v_add_co_u32_e32 v32, vcc, s92, v14
	s_mov_b32 s57, 0x9000
	s_nop 0
	v_addc_co_u32_e32 v33, vcc, 0, v15, vcc
	global_load_dword v41, v[32:33], off offset:-4096
	v_add_co_u32_e32 v34, vcc, s57, v14
	s_mov_b32 s57, 0xb000
	s_nop 0
	v_addc_co_u32_e32 v35, vcc, 0, v15, vcc
	global_load_dword v42, v[34:35], off offset:2048
	global_load_dword v43, v[32:33], off
	global_load_dword v78, v[32:33], off offset:2048
; __device__ __forceinline__ unsigned pk2(float lo, float hi) { f32x2 v = {lo, hi}; bf16x2_t b = __builtin_convertvector(v, bf16x2_t); return __builtin_bit_cast(unsigned, b); }
; __device__ __forceinline__ f32x2 ldx2(const bf16_t* p) { const unsigned w = *(const unsigned*)p; return (f32x2){__builtin_bit_cast(float, w << 16), __builtin_bit_cast(float, w & 0xffff0000u)}; }
; template <int W> __device__ __forceinline__ void pool_unit(const bf16_t* x, const LAS float* rs, f32x2 gn, bf16_t* Ag, size_t rb, int t0, int c, int g) {
;     ...
;     for (int bt = 0; bt < 4; ++bt) {
; #pragma unroll
;         for (int i = 0; i < 16; ++i) hn_[i] = ldx2(x + (rb + t0 + bt * 16 + i) * 1024 + c) * rs[16 + bt * 16 + i] * gn;
; #pragma unroll
;         for (int i = 0; i < 16; ++i) { const int t = t0 + bt * 16 + i;
;             win += hn_[i]; const float inv = 1.f / (float)((t + 1) < W ? (t + 1) : W);
;             const f32x2 a = win * inv - hn_[i];
;             *(unsigned*)(Ag + ((size_t)g * MT + rb + t) * 256 + (c & 255)) = pk2(a.x, a.y);
;             win -= (i - W + 1 >= 0) ? hn_[(i - W + 1 >= 0) ? (i - W + 1) : 0] : ring[(i - W + 17) & 15]; }
; #pragma unroll
	v_add_co_u32_e32 v32, vcc, s12, v14
	v_pk_fma_f32 v[56:57], v[2:3], v[44:45], v[30:31] neg_lo:[1,0,0] neg_hi:[1,0,0]
	s_nop 0
	v_addc_co_u32_e32 v33, vcc, 0, v15, vcc
	global_load_dword v82, v[32:33], off offset:-4096
	v_add_co_u32_e32 v34, vcc, s57, v14
	s_mov_b32 s57, 0xe000
	s_nop 0
	v_addc_co_u32_e32 v35, vcc, 0, v15, vcc
	global_load_dword v86, v[34:35], off offset:2048
	global_load_dword v90, v[32:33], off
	global_load_dword v92, v[32:33], off offset:2048
	v_add_co_u32_e32 v32, vcc, s57, v14
	s_mov_b32 s57, 0xd000
	s_nop 0
	v_addc_co_u32_e32 v33, vcc, 0, v15, vcc
	global_load_dword v93, v[32:33], off offset:-4096
	v_add_co_u32_e32 v34, vcc, s57, v14
	s_mov_b32 s57, 0xf000
	s_nop 0
	v_addc_co_u32_e32 v35, vcc, 0, v15, vcc
	global_load_dword v94, v[34:35], off offset:2048
	global_load_dword v95, v[32:33], off
	global_load_dword v96, v[32:33], off offset:2048
	v_add_co_u32_e32 v46, vcc, s63, v14
	s_or_b32 s58, s56, 16
	s_nop 0
	v_addc_co_u32_e32 v47, vcc, 0, v15, vcc
	global_load_dword v97, v[46:47], off offset:-4096
	v_add_co_u32_e32 v32, vcc, s57, v14
	s_mov_b32 s59, s45
	s_nop 0
	v_addc_co_u32_e32 v33, vcc, 0, v15, vcc
	global_load_dword v98, v[32:33], off offset:2048
	ds_read_b128 v[30:33], v175 offset:128
	s_lshl_b64 s[58:59], s[58:59], 9
	ds_read_b128 v[34:37], v175 offset:144
	ds_read_b128 v[48:51], v175 offset:160
	ds_read_b128 v[52:55], v175 offset:176
	s_mov_b32 s57, 0x12000
	s_waitcnt vmcnt(15)
	v_lshlrev_b32_e32 v38, 16, v5
	v_and_b32_e32 v39, 0xffff0000, v5
	s_waitcnt lgkmcnt(3)
	v_pk_mul_f32 v[58:59], v[30:31], v[38:39] op_sel_hi:[0,1]
	v_pk_mul_f32 v[60:61], v[2:3], v[58:59]
	s_waitcnt vmcnt(14)
	v_lshlrev_b32_e32 v38, 16, v40
	v_and_b32_e32 v39, 0xffff0000, v40
	v_pk_fma_f32 v[56:57], v[2:3], v[58:59], v[56:57]
	v_pk_mul_f32 v[62:63], v[30:31], v[38:39] op_sel:[1,0]
	v_pk_fma_f32 v[60:61], v[56:57], s[22:23], v[60:61] op_sel_hi:[1,0,1] neg_lo:[0,0,1] neg_hi:[0,0,1]
	v_pk_fma_f32 v[28:29], v[2:3], v[28:29], v[56:57] neg_lo:[1,0,0] neg_hi:[1,0,0]
	v_pk_mul_f32 v[64:65], v[2:3], v[62:63]
	s_waitcnt vmcnt(13)
	v_lshlrev_b32_e32 v30, 16, v41
	v_and_b32_e32 v31, 0xffff0000, v41
	v_cvt_pk_bf16_f32 v5, v60, v61
	v_lshl_add_u64 v[60:61], v[8:9], 0, s[58:59]
	v_pk_fma_f32 v[28:29], v[2:3], v[62:63], v[28:29]
	s_or_b32 s58, s56, 17
	s_mov_b32 s59, s45
	v_pk_mul_f32 v[66:67], v[32:33], v[30:31] op_sel_hi:[0,1]
	v_pk_fma_f32 v[56:57], v[28:29], s[22:23], v[64:65] op_sel_hi:[1,0,1] neg_lo:[0,0,1] neg_hi:[0,0,1]
	s_lshl_b64 s[58:59], s[58:59], 9
	v_pk_fma_f32 v[26:27], v[2:3], v[26:27], v[28:29] neg_lo:[1,0,0] neg_hi:[1,0,0]
	v_pk_mul_f32 v[68:69], v[2:3], v[66:67]
	s_waitcnt vmcnt(12)
	v_lshlrev_b32_e32 v30, 16, v42
	v_and_b32_e32 v31, 0xffff0000, v42
	v_mov_b32_e32 v32, v33
	global_store_dword v[60:61], v5, off nt
	v_cvt_pk_bf16_f32 v5, v56, v57
	v_lshl_add_u64 v[56:57], v[8:9], 0, s[58:59]
	v_pk_fma_f32 v[26:27], v[2:3], v[66:67], v[26:27]
	s_or_b32 s58, s56, 18
	s_mov_b32 s59, s45
	v_pk_mul_f32 v[70:71], v[32:33], v[30:31] op_sel_hi:[0,1]
	v_pk_fma_f32 v[28:29], v[26:27], s[22:23], v[68:69] op_sel_hi:[1,0,1] neg_lo:[0,0,1] neg_hi:[0,0,1]
	s_lshl_b64 s[58:59], s[58:59], 9
	v_pk_fma_f32 v[24:25], v[2:3], v[24:25], v[26:27] neg_lo:[1,0,0] neg_hi:[1,0,0]
	v_pk_mul_f32 v[72:73], v[2:3], v[70:71]
	s_waitcnt vmcnt(12)
	v_lshlrev_b32_e32 v30, 16, v43
	v_and_b32_e32 v31, 0xffff0000, v43
	global_store_dword v[56:57], v5, off nt
	v_cvt_pk_bf16_f32 v5, v28, v29
	v_lshl_add_u64 v[28:29], v[8:9], 0, s[58:59]
	v_pk_fma_f32 v[24:25], v[2:3], v[70:71], v[24:25]
	s_or_b32 s58, s56, 19
	s_mov_b32 s59, s45
	s_waitcnt lgkmcnt(2)
	v_pk_mul_f32 v[74:75], v[34:35], v[30:31] op_sel_hi:[0,1]
	v_pk_fma_f32 v[26:27], v[24:25], s[22:23], v[72:73] op_sel_hi:[1,0,1] neg_lo:[0,0,1] neg_hi:[0,0,1]
	s_lshl_b64 s[58:59], s[58:59], 9
	v_pk_fma_f32 v[22:23], v[2:3], v[22:23], v[24:25] neg_lo:[1,0,0] neg_hi:[1,0,0]
	v_pk_mul_f32 v[76:77], v[2:3], v[74:75]
	s_waitcnt vmcnt(12)
	v_lshlrev_b32_e32 v30, 16, v78
	v_and_b32_e32 v31, 0xffff0000, v78
	global_store_dword v[28:29], v5, off nt
	v_cvt_pk_bf16_f32 v5, v26, v27
	v_lshl_add_u64 v[26:27], v[8:9], 0, s[58:59]
	v_pk_fma_f32 v[22:23], v[2:3], v[74:75], v[22:23]
	s_or_b32 s58, s56, 20
	s_mov_b32 s59, s45
	v_pk_mul_f32 v[78:79], v[34:35], v[30:31] op_sel:[1,0]
	v_pk_fma_f32 v[24:25], v[22:23], s[22:23], v[76:77] op_sel_hi:[1,0,1] neg_lo:[0,0,1] neg_hi:[0,0,1]
	s_lshl_b64 s[58:59], s[58:59], 9
	v_pk_fma_f32 v[20:21], v[2:3], v[20:21], v[22:23] neg_lo:[1,0,0] neg_hi:[1,0,0]
	v_pk_mul_f32 v[80:81], v[2:3], v[78:79]
	s_waitcnt vmcnt(12)
	v_lshlrev_b32_e32 v30, 16, v82
	v_and_b32_e32 v31, 0xffff0000, v82
	global_store_dword v[26:27], v5, off nt
	v_cvt_pk_bf16_f32 v5, v24, v25
	v_lshl_add_u64 v[24:25], v[8:9], 0, s[58:59]
	v_pk_fma_f32 v[20:21], v[2:3], v[78:79], v[20:21]
	s_or_b32 s58, s56, 21
	s_mov_b32 s59, s45
	v_pk_mul_f32 v[82:83], v[36:37], v[30:31] op_sel_hi:[0,1]
	v_pk_fma_f32 v[22:23], v[20:21], s[22:23], v[80:81] op_sel_hi:[1,0,1] neg_lo:[0,0,1] neg_hi:[0,0,1]
	s_lshl_b64 s[58:59], s[58:59], 9
	v_pk_fma_f32 v[16:17], v[2:3], v[16:17], v[20:21] neg_lo:[1,0,0] neg_hi:[1,0,0]
	v_pk_mul_f32 v[84:85], v[2:3], v[82:83]
	s_waitcnt vmcnt(12)
	v_lshlrev_b32_e32 v30, 16, v86
	v_and_b32_e32 v31, 0xffff0000, v86
	v_mov_b32_e32 v32, v37
	global_store_dword v[24:25], v5, off nt
	v_cvt_pk_bf16_f32 v5, v22, v23
	v_lshl_add_u64 v[22:23], v[8:9], 0, s[58:59]
	v_pk_fma_f32 v[16:17], v[2:3], v[82:83], v[16:17]
	s_or_b32 s58, s56, 22
	s_mov_b32 s59, s45
	v_pk_mul_f32 v[86:87], v[32:33], v[30:31] op_sel_hi:[0,1]
	v_pk_fma_f32 v[20:21], v[16:17], s[22:23], v[84:85] op_sel_hi:[1,0,1] neg_lo:[0,0,1] neg_hi:[0,0,1]
	s_lshl_b64 s[58:59], s[58:59], 9
	v_pk_fma_f32 v[16:17], v[2:3], v[18:19], v[16:17] neg_lo:[1,0,0] neg_hi:[1,0,0]
	v_pk_mul_f32 v[88:89], v[2:3], v[86:87]
	s_waitcnt vmcnt(12)
; __device__ __forceinline__ unsigned pk2(float lo, float hi) { f32x2 v = {lo, hi}; bf16x2_t b = __builtin_convertvector(v, bf16x2_t); return __builtin_bit_cast(unsigned, b); }
; __device__ __forceinline__ f32x2 ldx2(const bf16_t* p) { const unsigned w = *(const unsigned*)p; return (f32x2){__builtin_bit_cast(float, w << 16), __builtin_bit_cast(float, w & 0xffff0000u)}; }
; template <int W> __device__ __forceinline__ void pool_unit(const bf16_t* x, const LAS float* rs, f32x2 gn, bf16_t* Ag, size_t rb, int t0, int c, int g) {
;     ...
;     for (int bt = 0; bt < 4; ++bt) {
; #pragma unroll
;         for (int i = 0; i < 16; ++i) hn_[i] = ldx2(x + (rb + t0 + bt * 16 + i) * 1024 + c) * rs[16 + bt * 16 + i] * gn;
; #pragma unroll
;         for (int i = 0; i < 16; ++i) { const int t = t0 + bt * 16 + i;
;             win += hn_[i]; const float inv = 1.f / (float)((t + 1) < W ? (t + 1) : W);
;             const f32x2 a = win * inv - hn_[i];
;             *(unsigned*)(Ag + ((size_t)g * MT + rb + t) * 256 + (c & 255)) = pk2(a.x, a.y);
;             win -= (i - W + 1 >= 0) ? hn_[(i - W + 1 >= 0) ? (i - W + 1) : 0] : ring[(i - W + 17) & 15]; }
; #pragma unroll
	v_lshlrev_b32_e32 v30, 16, v90
	v_and_b32_e32 v31, 0xffff0000, v90
	global_store_dword v[22:23], v5, off nt
	v_cvt_pk_bf16_f32 v5, v20, v21
	v_lshl_add_u64 v[20:21], v[8:9], 0, s[58:59]
	v_pk_fma_f32 v[16:17], v[2:3], v[86:87], v[16:17]
	s_or_b32 s58, s56, 23
	s_mov_b32 s59, s45
	s_waitcnt lgkmcnt(1)
	v_pk_mul_f32 v[44:45], v[48:49], v[30:31] op_sel_hi:[0,1]
	v_pk_fma_f32 v[18:19], v[16:17], s[22:23], v[88:89] op_sel_hi:[1,0,1] neg_lo:[0,0,1] neg_hi:[0,0,1]
	s_lshl_b64 s[58:59], s[58:59], 9
	v_pk_fma_f32 v[16:17], v[2:3], v[58:59], v[16:17] neg_lo:[1,0,0] neg_hi:[1,0,0]
	v_pk_mul_f32 v[90:91], v[2:3], v[44:45]
	s_waitcnt vmcnt(12)
	v_lshlrev_b32_e32 v30, 16, v92
	v_and_b32_e32 v31, 0xffff0000, v92
	global_store_dword v[20:21], v5, off nt
	v_cvt_pk_bf16_f32 v5, v18, v19
	v_lshl_add_u64 v[18:19], v[8:9], 0, s[58:59]
	v_pk_fma_f32 v[16:17], v[2:3], v[44:45], v[16:17]
	s_or_b32 s58, s56, 24
	s_mov_b32 s59, s45
	v_pk_mul_f32 v[42:43], v[48:49], v[30:31] op_sel:[1,0]
	global_store_dword v[18:19], v5, off nt
	v_pk_fma_f32 v[18:19], v[16:17], s[22:23], v[90:91] op_sel_hi:[1,0,1] neg_lo:[0,0,1] neg_hi:[0,0,1]
	s_lshl_b64 s[58:59], s[58:59], 9
	v_pk_fma_f32 v[16:17], v[2:3], v[62:63], v[16:17] neg_lo:[1,0,0] neg_hi:[1,0,0]
	v_pk_mul_f32 v[48:49], v[2:3], v[42:43]
	s_waitcnt vmcnt(13)
	v_lshlrev_b32_e32 v30, 16, v93
	v_and_b32_e32 v31, 0xffff0000, v93
	v_cvt_pk_bf16_f32 v5, v18, v19
	v_lshl_add_u64 v[18:19], v[8:9], 0, s[58:59]
	v_pk_fma_f32 v[16:17], v[2:3], v[42:43], v[16:17]
	s_or_b32 s58, s56, 25
	s_mov_b32 s59, s45
	v_pk_mul_f32 v[40:41], v[50:51], v[30:31] op_sel_hi:[0,1]
	global_store_dword v[18:19], v5, off nt
	v_pk_fma_f32 v[18:19], v[16:17], s[22:23], v[48:49] op_sel_hi:[1,0,1] neg_lo:[0,0,1] neg_hi:[0,0,1]
	s_lshl_b64 s[58:59], s[58:59], 9
	v_pk_fma_f32 v[16:17], v[2:3], v[66:67], v[16:17] neg_lo:[1,0,0] neg_hi:[1,0,0]
	v_pk_mul_f32 v[92:93], v[2:3], v[40:41]
	s_waitcnt vmcnt(13)
	v_lshlrev_b32_e32 v30, 16, v94
	v_and_b32_e32 v31, 0xffff0000, v94
	v_mov_b32_e32 v32, v51
	v_cvt_pk_bf16_f32 v5, v18, v19
	v_lshl_add_u64 v[18:19], v[8:9], 0, s[58:59]
	v_pk_fma_f32 v[16:17], v[2:3], v[40:41], v[16:17]
	s_or_b32 s58, s56, 26
	s_mov_b32 s59, s45
	v_pk_mul_f32 v[38:39], v[32:33], v[30:31] op_sel_hi:[0,1]
	global_store_dword v[18:19], v5, off nt
	v_pk_fma_f32 v[18:19], v[16:17], s[22:23], v[92:93] op_sel_hi:[1,0,1] neg_lo:[0,0,1] neg_hi:[0,0,1]
	s_lshl_b64 s[58:59], s[58:59], 9
	v_pk_fma_f32 v[16:17], v[2:3], v[70:71], v[16:17] neg_lo:[1,0,0] neg_hi:[1,0,0]
	v_pk_mul_f32 v[50:51], v[2:3], v[38:39]
	s_waitcnt vmcnt(13)
	v_lshlrev_b32_e32 v30, 16, v95
	v_and_b32_e32 v31, 0xffff0000, v95
	v_cvt_pk_bf16_f32 v5, v18, v19
	v_lshl_add_u64 v[18:19], v[8:9], 0, s[58:59]
	v_pk_fma_f32 v[16:17], v[2:3], v[38:39], v[16:17]
	s_or_b32 s58, s56, 27
	s_mov_b32 s59, s45
	s_waitcnt lgkmcnt(0)
	v_pk_mul_f32 v[36:37], v[52:53], v[30:31] op_sel_hi:[0,1]
	global_store_dword v[18:19], v5, off nt
	v_pk_fma_f32 v[18:19], v[16:17], s[22:23], v[50:51] op_sel_hi:[1,0,1] neg_lo:[0,0,1] neg_hi:[0,0,1]
	s_lshl_b64 s[58:59], s[58:59], 9
	v_pk_fma_f32 v[16:17], v[2:3], v[74:75], v[16:17] neg_lo:[1,0,0] neg_hi:[1,0,0]
	v_pk_mul_f32 v[94:95], v[2:3], v[36:37]
	s_waitcnt vmcnt(13)
	v_lshlrev_b32_e32 v30, 16, v96
	v_and_b32_e32 v31, 0xffff0000, v96
	v_cvt_pk_bf16_f32 v5, v18, v19
	v_lshl_add_u64 v[18:19], v[8:9], 0, s[58:59]
	v_pk_fma_f32 v[16:17], v[2:3], v[36:37], v[16:17]
	s_or_b32 s58, s56, 28
	s_mov_b32 s59, s45
	v_pk_mul_f32 v[34:35], v[52:53], v[30:31] op_sel:[1,0]
	global_store_dword v[18:19], v5, off nt
	v_pk_fma_f32 v[18:19], v[16:17], s[22:23], v[94:95] op_sel_hi:[1,0,1] neg_lo:[0,0,1] neg_hi:[0,0,1]
	s_lshl_b64 s[58:59], s[58:59], 9
	v_pk_fma_f32 v[16:17], v[2:3], v[78:79], v[16:17] neg_lo:[1,0,0] neg_hi:[1,0,0]
	v_pk_mul_f32 v[52:53], v[2:3], v[34:35]
	s_waitcnt vmcnt(13)
	v_lshlrev_b32_e32 v30, 16, v97
	v_and_b32_e32 v31, 0xffff0000, v97
	v_cvt_pk_bf16_f32 v5, v18, v19
	v_lshl_add_u64 v[18:19], v[8:9], 0, s[58:59]
	v_pk_fma_f32 v[16:17], v[2:3], v[34:35], v[16:17]
	s_or_b32 s58, s56, 29
	s_mov_b32 s59, s45
	v_pk_mul_f32 v[32:33], v[54:55], v[30:31] op_sel_hi:[0,1]
	global_store_dword v[18:19], v5, off nt
	v_pk_fma_f32 v[18:19], v[16:17], s[22:23], v[52:53] op_sel_hi:[1,0,1] neg_lo:[0,0,1] neg_hi:[0,0,1]
	s_lshl_b64 s[58:59], s[58:59], 9
	v_pk_fma_f32 v[16:17], v[2:3], v[82:83], v[16:17] neg_lo:[1,0,0] neg_hi:[1,0,0]
	v_pk_mul_f32 v[96:97], v[2:3], v[32:33]
	s_waitcnt vmcnt(13)
; __device__ __forceinline__ unsigned pk2(float lo, float hi) { f32x2 v = {lo, hi}; bf16x2_t b = __builtin_convertvector(v, bf16x2_t); return __builtin_bit_cast(unsigned, b); }
; __device__ __forceinline__ f32x2 ldx2(const bf16_t* p) { const unsigned w = *(const unsigned*)p; return (f32x2){__builtin_bit_cast(float, w << 16), __builtin_bit_cast(float, w & 0xffff0000u)}; }
; template <int W> __device__ __forceinline__ void pool_unit(const bf16_t* x, const LAS float* rs, f32x2 gn, bf16_t* Ag, size_t rb, int t0, int c, int g) {
;     ...
;     for (int bt = 0; bt < 4; ++bt) {
; #pragma unroll
;         for (int i = 0; i < 16; ++i) hn_[i] = ldx2(x + (rb + t0 + bt * 16 + i) * 1024 + c) * rs[16 + bt * 16 + i] * gn;
; #pragma unroll
;         for (int i = 0; i < 16; ++i) { const int t = t0 + bt * 16 + i;
;             win += hn_[i]; const float inv = 1.f / (float)((t + 1) < W ? (t + 1) : W);
;             const f32x2 a = win * inv - hn_[i];
;             *(unsigned*)(Ag + ((size_t)g * MT + rb + t) * 256 + (c & 255)) = pk2(a.x, a.y);
;             win -= (i - W + 1 >= 0) ? hn_[(i - W + 1 >= 0) ? (i - W + 1) : 0] : ring[(i - W + 17) & 15]; }
; #pragma unroll
;         for (int i = 0; i < 16; ++i) ring[i] = hn_[i];
	v_lshlrev_b32_e32 v30, 16, v98
	v_and_b32_e32 v31, 0xffff0000, v98
	v_mov_b32_e32 v54, v55
	v_cvt_pk_bf16_f32 v5, v18, v19
	v_lshl_add_u64 v[18:19], v[8:9], 0, s[58:59]
	v_pk_fma_f32 v[16:17], v[2:3], v[32:33], v[16:17]
	s_or_b32 s58, s56, 30
	s_mov_b32 s59, s45
	v_pk_mul_f32 v[30:31], v[54:55], v[30:31] op_sel_hi:[0,1]
	global_store_dword v[18:19], v5, off nt
	v_pk_fma_f32 v[18:19], v[16:17], s[22:23], v[96:97] op_sel_hi:[1,0,1] neg_lo:[0,0,1] neg_hi:[0,0,1]
	s_lshl_b64 s[58:59], s[58:59], 9
	v_pk_fma_f32 v[16:17], v[2:3], v[86:87], v[16:17] neg_lo:[1,0,0] neg_hi:[1,0,0]
	v_pk_mul_f32 v[54:55], v[2:3], v[30:31]
	v_cvt_pk_bf16_f32 v5, v18, v19
	v_lshl_add_u64 v[18:19], v[8:9], 0, s[58:59]
	v_pk_fma_f32 v[16:17], v[2:3], v[30:31], v[16:17]
	s_or_b32 s58, s56, 31
	s_mov_b32 s59, s45
	global_store_dword v[18:19], v5, off nt
	v_pk_fma_f32 v[18:19], v[16:17], s[22:23], v[54:55] op_sel_hi:[1,0,1] neg_lo:[0,0,1] neg_hi:[0,0,1]
	s_lshl_b64 s[58:59], s[58:59], 9
	v_cvt_pk_bf16_f32 v5, v18, v19
	v_lshl_add_u64 v[18:19], v[8:9], 0, s[58:59]
	global_store_dword v[18:19], v5, off nt
	global_load_dword v5, v[46:47], off
	s_nop 0
	global_load_dword v26, v[46:47], off offset:2048
	v_add_co_u32_e32 v18, vcc, s57, v14
	s_mov_b32 s57, 0x11000
	s_nop 0
	v_addc_co_u32_e32 v19, vcc, 0, v15, vcc
	global_load_dword v27, v[18:19], off offset:-4096
	v_add_co_u32_e32 v20, vcc, s57, v14
	s_mov_b32 s57, 0x14000
	s_nop 0
	v_addc_co_u32_e32 v21, vcc, 0, v15, vcc
	global_load_dword v28, v[20:21], off offset:2048
	global_load_dword v29, v[18:19], off
	global_load_dword v78, v[18:19], off offset:2048
	v_add_co_u32_e32 v18, vcc, s57, v14
	s_mov_b32 s57, 0x13000
	s_nop 0
	v_addc_co_u32_e32 v19, vcc, 0, v15, vcc
	global_load_dword v82, v[18:19], off offset:-4096
	v_add_co_u32_e32 v20, vcc, s57, v14
	s_mov_b32 s57, 0x16000
	s_nop 0
	v_addc_co_u32_e32 v21, vcc, 0, v15, vcc
	global_load_dword v86, v[20:21], off offset:2048
	global_load_dword v90, v[18:19], off
	global_load_dword v92, v[18:19], off offset:2048
	v_add_co_u32_e32 v18, vcc, s57, v14
	s_mov_b32 s57, 0x15000
	s_nop 0
	v_addc_co_u32_e32 v19, vcc, 0, v15, vcc
	global_load_dword v93, v[18:19], off offset:-4096
	v_add_co_u32_e32 v20, vcc, s57, v14
	s_mov_b32 s57, 0x18000
	s_nop 0
	v_addc_co_u32_e32 v21, vcc, 0, v15, vcc
	global_load_dword v94, v[20:21], off offset:2048
	global_load_dword v95, v[18:19], off
	global_load_dword v96, v[18:19], off offset:2048
	v_add_co_u32_e32 v46, vcc, s57, v14
	s_mov_b32 s57, 0x17000
	s_nop 0
	v_addc_co_u32_e32 v47, vcc, 0, v15, vcc
	global_load_dword v97, v[46:47], off offset:-4096
	v_add_co_u32_e32 v18, vcc, s57, v14
	v_pk_fma_f32 v[56:57], v[2:3], v[44:45], v[16:17] neg_lo:[1,0,0] neg_hi:[1,0,0]
	s_nop 0
	v_addc_co_u32_e32 v19, vcc, 0, v15, vcc
	global_load_dword v98, v[18:19], off offset:2048
	ds_read_b128 v[16:19], v175 offset:192
	s_or_b32 s58, s56, 32
	s_mov_b32 s59, s45
	s_lshl_b64 s[58:59], s[58:59], 9
	ds_read_b128 v[20:23], v175 offset:208
	ds_read_b128 v[48:51], v175 offset:224
	ds_read_b128 v[52:55], v175 offset:240
	s_mov_b32 s57, 0x1a000
	s_waitcnt vmcnt(15)
	v_lshlrev_b32_e32 v24, 16, v5
	v_and_b32_e32 v25, 0xffff0000, v5
	s_waitcnt lgkmcnt(3)
	v_pk_mul_f32 v[58:59], v[16:17], v[24:25] op_sel_hi:[0,1]
	v_pk_mul_f32 v[60:61], v[2:3], v[58:59]
	s_waitcnt vmcnt(14)
	v_lshlrev_b32_e32 v24, 16, v26
	v_and_b32_e32 v25, 0xffff0000, v26
	v_pk_fma_f32 v[56:57], v[2:3], v[58:59], v[56:57]
	v_pk_mul_f32 v[62:63], v[16:17], v[24:25] op_sel:[1,0]
	v_pk_fma_f32 v[60:61], v[56:57], s[22:23], v[60:61] op_sel_hi:[1,0,1] neg_lo:[0,0,1] neg_hi:[0,0,1]
	v_pk_fma_f32 v[42:43], v[2:3], v[42:43], v[56:57] neg_lo:[1,0,0] neg_hi:[1,0,0]
	v_pk_mul_f32 v[64:65], v[2:3], v[62:63]
	s_waitcnt vmcnt(13)
	v_lshlrev_b32_e32 v16, 16, v27
	v_and_b32_e32 v17, 0xffff0000, v27
	v_cvt_pk_bf16_f32 v5, v60, v61
	v_lshl_add_u64 v[60:61], v[8:9], 0, s[58:59]
	v_pk_fma_f32 v[42:43], v[2:3], v[62:63], v[42:43]
	s_or_b32 s58, s56, 33
	s_mov_b32 s59, s45
	v_pk_mul_f32 v[66:67], v[18:19], v[16:17] op_sel_hi:[0,1]
	v_pk_fma_f32 v[56:57], v[42:43], s[22:23], v[64:65] op_sel_hi:[1,0,1] neg_lo:[0,0,1] neg_hi:[0,0,1]
	s_lshl_b64 s[58:59], s[58:59], 9
	v_pk_fma_f32 v[40:41], v[2:3], v[40:41], v[42:43] neg_lo:[1,0,0] neg_hi:[1,0,0]
	v_pk_mul_f32 v[68:69], v[2:3], v[66:67]
	s_waitcnt vmcnt(12)
	v_lshlrev_b32_e32 v16, 16, v28
	v_and_b32_e32 v17, 0xffff0000, v28
	v_mov_b32_e32 v18, v19
	global_store_dword v[60:61], v5, off nt
	v_cvt_pk_bf16_f32 v5, v56, v57
	v_lshl_add_u64 v[56:57], v[8:9], 0, s[58:59]
	v_pk_fma_f32 v[40:41], v[2:3], v[66:67], v[40:41]
	s_or_b32 s58, s56, 34
	s_mov_b32 s59, s45
	v_pk_mul_f32 v[70:71], v[18:19], v[16:17] op_sel_hi:[0,1]
	v_pk_fma_f32 v[42:43], v[40:41], s[22:23], v[68:69] op_sel_hi:[1,0,1] neg_lo:[0,0,1] neg_hi:[0,0,1]
	s_lshl_b64 s[58:59], s[58:59], 9
	v_pk_fma_f32 v[38:39], v[2:3], v[38:39], v[40:41] neg_lo:[1,0,0] neg_hi:[1,0,0]
	v_pk_mul_f32 v[72:73], v[2:3], v[70:71]
	s_waitcnt vmcnt(12)
	v_lshlrev_b32_e32 v16, 16, v29
	v_and_b32_e32 v17, 0xffff0000, v29
	global_store_dword v[56:57], v5, off nt
	v_cvt_pk_bf16_f32 v5, v42, v43
	v_lshl_add_u64 v[42:43], v[8:9], 0, s[58:59]
	v_pk_fma_f32 v[38:39], v[2:3], v[70:71], v[38:39]
	s_or_b32 s58, s56, 35
	s_mov_b32 s59, s45
	s_waitcnt lgkmcnt(2)
	v_pk_mul_f32 v[74:75], v[20:21], v[16:17] op_sel_hi:[0,1]
	v_pk_fma_f32 v[40:41], v[38:39], s[22:23], v[72:73] op_sel_hi:[1,0,1] neg_lo:[0,0,1] neg_hi:[0,0,1]
	s_lshl_b64 s[58:59], s[58:59], 9
	v_pk_fma_f32 v[36:37], v[2:3], v[36:37], v[38:39] neg_lo:[1,0,0] neg_hi:[1,0,0]
	v_pk_mul_f32 v[76:77], v[2:3], v[74:75]
	s_waitcnt vmcnt(12)
; __device__ __forceinline__ unsigned pk2(float lo, float hi) { f32x2 v = {lo, hi}; bf16x2_t b = __builtin_convertvector(v, bf16x2_t); return __builtin_bit_cast(unsigned, b); }
; __device__ __forceinline__ f32x2 ldx2(const bf16_t* p) { const unsigned w = *(const unsigned*)p; return (f32x2){__builtin_bit_cast(float, w << 16), __builtin_bit_cast(float, w & 0xffff0000u)}; }
; template <int W> __device__ __forceinline__ void pool_unit(const bf16_t* x, const LAS float* rs, f32x2 gn, bf16_t* Ag, size_t rb, int t0, int c, int g) {
;     ...
;     for (int bt = 0; bt < 4; ++bt) {
; #pragma unroll
;         for (int i = 0; i < 16; ++i) hn_[i] = ldx2(x + (rb + t0 + bt * 16 + i) * 1024 + c) * rs[16 + bt * 16 + i] * gn;
; #pragma unroll
;         for (int i = 0; i < 16; ++i) { const int t = t0 + bt * 16 + i;
;             win += hn_[i]; const float inv = 1.f / (float)((t + 1) < W ? (t + 1) : W);
;             const f32x2 a = win * inv - hn_[i];
;             *(unsigned*)(Ag + ((size_t)g * MT + rb + t) * 256 + (c & 255)) = pk2(a.x, a.y);
;             win -= (i - W + 1 >= 0) ? hn_[(i - W + 1 >= 0) ? (i - W + 1) : 0] : ring[(i - W + 17) & 15]; }
; #pragma unroll
;         for (int i = 0; i < 16; ++i) ring[i] = hn_[i];
	v_lshlrev_b32_e32 v16, 16, v78
	v_and_b32_e32 v17, 0xffff0000, v78
	global_store_dword v[42:43], v5, off nt
	v_cvt_pk_bf16_f32 v5, v40, v41
	v_lshl_add_u64 v[40:41], v[8:9], 0, s[58:59]
	v_pk_fma_f32 v[36:37], v[2:3], v[74:75], v[36:37]
	s_or_b32 s58, s56, 36
	s_mov_b32 s59, s45
	v_pk_mul_f32 v[78:79], v[20:21], v[16:17] op_sel:[1,0]
	v_pk_fma_f32 v[38:39], v[36:37], s[22:23], v[76:77] op_sel_hi:[1,0,1] neg_lo:[0,0,1] neg_hi:[0,0,1]
	s_lshl_b64 s[58:59], s[58:59], 9
	v_pk_fma_f32 v[34:35], v[2:3], v[34:35], v[36:37] neg_lo:[1,0,0] neg_hi:[1,0,0]
	v_pk_mul_f32 v[80:81], v[2:3], v[78:79]
	s_waitcnt vmcnt(12)
	v_lshlrev_b32_e32 v16, 16, v82
	v_and_b32_e32 v17, 0xffff0000, v82
	global_store_dword v[40:41], v5, off nt
	v_cvt_pk_bf16_f32 v5, v38, v39
	v_lshl_add_u64 v[38:39], v[8:9], 0, s[58:59]
	v_pk_fma_f32 v[34:35], v[2:3], v[78:79], v[34:35]
	s_or_b32 s58, s56, 37
	s_mov_b32 s59, s45
	v_pk_mul_f32 v[82:83], v[22:23], v[16:17] op_sel_hi:[0,1]
	v_pk_fma_f32 v[36:37], v[34:35], s[22:23], v[80:81] op_sel_hi:[1,0,1] neg_lo:[0,0,1] neg_hi:[0,0,1]
	s_lshl_b64 s[58:59], s[58:59], 9
	v_pk_fma_f32 v[32:33], v[2:3], v[32:33], v[34:35] neg_lo:[1,0,0] neg_hi:[1,0,0]
	v_pk_mul_f32 v[84:85], v[2:3], v[82:83]
	s_waitcnt vmcnt(12)
	v_lshlrev_b32_e32 v16, 16, v86
	v_and_b32_e32 v17, 0xffff0000, v86
	v_mov_b32_e32 v18, v23
	global_store_dword v[38:39], v5, off nt
	v_cvt_pk_bf16_f32 v5, v36, v37
	v_lshl_add_u64 v[36:37], v[8:9], 0, s[58:59]
	v_pk_fma_f32 v[32:33], v[2:3], v[82:83], v[32:33]
	s_or_b32 s58, s56, 38
	s_mov_b32 s59, s45
	v_pk_mul_f32 v[86:87], v[18:19], v[16:17] op_sel_hi:[0,1]
	v_pk_fma_f32 v[34:35], v[32:33], s[22:23], v[84:85] op_sel_hi:[1,0,1] neg_lo:[0,0,1] neg_hi:[0,0,1]
	s_lshl_b64 s[58:59], s[58:59], 9
	v_pk_fma_f32 v[30:31], v[2:3], v[30:31], v[32:33] neg_lo:[1,0,0] neg_hi:[1,0,0]
	v_pk_mul_f32 v[88:89], v[2:3], v[86:87]
	s_waitcnt vmcnt(12)
	v_lshlrev_b32_e32 v16, 16, v90
	v_and_b32_e32 v17, 0xffff0000, v90
	global_store_dword v[36:37], v5, off nt
	v_cvt_pk_bf16_f32 v5, v34, v35
	v_lshl_add_u64 v[34:35], v[8:9], 0, s[58:59]
	v_pk_fma_f32 v[30:31], v[2:3], v[86:87], v[30:31]
	s_or_b32 s58, s56, 39
	s_mov_b32 s59, s45
	s_waitcnt lgkmcnt(1)
	v_pk_mul_f32 v[44:45], v[48:49], v[16:17] op_sel_hi:[0,1]
	v_pk_fma_f32 v[32:33], v[30:31], s[22:23], v[88:89] op_sel_hi:[1,0,1] neg_lo:[0,0,1] neg_hi:[0,0,1]
	s_lshl_b64 s[58:59], s[58:59], 9
	v_pk_fma_f32 v[30:31], v[2:3], v[58:59], v[30:31] neg_lo:[1,0,0] neg_hi:[1,0,0]
	v_pk_mul_f32 v[90:91], v[2:3], v[44:45]
	s_waitcnt vmcnt(12)
	v_lshlrev_b32_e32 v16, 16, v92
	v_and_b32_e32 v17, 0xffff0000, v92
	global_store_dword v[34:35], v5, off nt
	v_cvt_pk_bf16_f32 v5, v32, v33
	v_lshl_add_u64 v[32:33], v[8:9], 0, s[58:59]
	v_pk_fma_f32 v[30:31], v[2:3], v[44:45], v[30:31]
	s_or_b32 s58, s56, 40
	s_mov_b32 s59, s45
	v_pk_mul_f32 v[28:29], v[48:49], v[16:17] op_sel:[1,0]
	global_store_dword v[32:33], v5, off nt
	v_pk_fma_f32 v[32:33], v[30:31], s[22:23], v[90:91] op_sel_hi:[1,0,1] neg_lo:[0,0,1] neg_hi:[0,0,1]
	s_lshl_b64 s[58:59], s[58:59], 9
	v_pk_fma_f32 v[30:31], v[2:3], v[62:63], v[30:31] neg_lo:[1,0,0] neg_hi:[1,0,0]
	v_pk_mul_f32 v[48:49], v[2:3], v[28:29]
	s_waitcnt vmcnt(13)
	v_lshlrev_b32_e32 v16, 16, v93
	v_and_b32_e32 v17, 0xffff0000, v93
	v_cvt_pk_bf16_f32 v5, v32, v33
	v_lshl_add_u64 v[32:33], v[8:9], 0, s[58:59]
	v_pk_fma_f32 v[30:31], v[2:3], v[28:29], v[30:31]
	s_or_b32 s58, s56, 41
	s_mov_b32 s59, s45
	v_pk_mul_f32 v[26:27], v[50:51], v[16:17] op_sel_hi:[0,1]
	global_store_dword v[32:33], v5, off nt
	v_pk_fma_f32 v[32:33], v[30:31], s[22:23], v[48:49] op_sel_hi:[1,0,1] neg_lo:[0,0,1] neg_hi:[0,0,1]
	s_lshl_b64 s[58:59], s[58:59], 9
	v_pk_fma_f32 v[30:31], v[2:3], v[66:67], v[30:31] neg_lo:[1,0,0] neg_hi:[1,0,0]
	v_pk_mul_f32 v[92:93], v[2:3], v[26:27]
	s_waitcnt vmcnt(13)
	v_lshlrev_b32_e32 v16, 16, v94
	v_and_b32_e32 v17, 0xffff0000, v94
	v_mov_b32_e32 v18, v51
	v_cvt_pk_bf16_f32 v5, v32, v33
	v_lshl_add_u64 v[32:33], v[8:9], 0, s[58:59]
	v_pk_fma_f32 v[30:31], v[2:3], v[26:27], v[30:31]
	s_or_b32 s58, s56, 42
	s_mov_b32 s59, s45
	v_pk_mul_f32 v[24:25], v[18:19], v[16:17] op_sel_hi:[0,1]
	global_store_dword v[32:33], v5, off nt
	v_pk_fma_f32 v[32:33], v[30:31], s[22:23], v[92:93] op_sel_hi:[1,0,1] neg_lo:[0,0,1] neg_hi:[0,0,1]
	s_lshl_b64 s[58:59], s[58:59], 9
	v_pk_fma_f32 v[30:31], v[2:3], v[70:71], v[30:31] neg_lo:[1,0,0] neg_hi:[1,0,0]
	v_pk_mul_f32 v[50:51], v[2:3], v[24:25]
	s_waitcnt vmcnt(13)
	v_lshlrev_b32_e32 v16, 16, v95
	v_and_b32_e32 v17, 0xffff0000, v95
	v_cvt_pk_bf16_f32 v5, v32, v33
	v_lshl_add_u64 v[32:33], v[8:9], 0, s[58:59]
	v_pk_fma_f32 v[30:31], v[2:3], v[24:25], v[30:31]
	s_or_b32 s58, s56, 43
	s_mov_b32 s59, s45
	s_waitcnt lgkmcnt(0)
	v_pk_mul_f32 v[22:23], v[52:53], v[16:17] op_sel_hi:[0,1]
	global_store_dword v[32:33], v5, off nt
	v_pk_fma_f32 v[32:33], v[30:31], s[22:23], v[50:51] op_sel_hi:[1,0,1] neg_lo:[0,0,1] neg_hi:[0,0,1]
	s_lshl_b64 s[58:59], s[58:59], 9
	v_pk_fma_f32 v[30:31], v[2:3], v[74:75], v[30:31] neg_lo:[1,0,0] neg_hi:[1,0,0]
	v_pk_mul_f32 v[94:95], v[2:3], v[22:23]
	s_waitcnt vmcnt(13)
	v_lshlrev_b32_e32 v16, 16, v96
	v_and_b32_e32 v17, 0xffff0000, v96
	v_cvt_pk_bf16_f32 v5, v32, v33
	v_lshl_add_u64 v[32:33], v[8:9], 0, s[58:59]
	v_pk_fma_f32 v[30:31], v[2:3], v[22:23], v[30:31]
	s_or_b32 s58, s56, 44
	s_mov_b32 s59, s45
	v_pk_mul_f32 v[20:21], v[52:53], v[16:17] op_sel:[1,0]
	global_store_dword v[32:33], v5, off nt
	v_pk_fma_f32 v[32:33], v[30:31], s[22:23], v[94:95] op_sel_hi:[1,0,1] neg_lo:[0,0,1] neg_hi:[0,0,1]
	s_lshl_b64 s[58:59], s[58:59], 9
	v_pk_fma_f32 v[30:31], v[2:3], v[78:79], v[30:31] neg_lo:[1,0,0] neg_hi:[1,0,0]
	v_pk_mul_f32 v[52:53], v[2:3], v[20:21]
	s_waitcnt vmcnt(13)
; __device__ __forceinline__ unsigned pk2(float lo, float hi) { f32x2 v = {lo, hi}; bf16x2_t b = __builtin_convertvector(v, bf16x2_t); return __builtin_bit_cast(unsigned, b); }
; __device__ __forceinline__ f32x2 ldx2(const bf16_t* p) { const unsigned w = *(const unsigned*)p; return (f32x2){__builtin_bit_cast(float, w << 16), __builtin_bit_cast(float, w & 0xffff0000u)}; }
; template <int W> __device__ __forceinline__ void pool_unit(const bf16_t* x, const LAS float* rs, f32x2 gn, bf16_t* Ag, size_t rb, int t0, int c, int g) {
;     ...
;     for (int bt = 0; bt < 4; ++bt) {
; #pragma unroll
;         for (int i = 0; i < 16; ++i) hn_[i] = ldx2(x + (rb + t0 + bt * 16 + i) * 1024 + c) * rs[16 + bt * 16 + i] * gn;
; #pragma unroll
;         for (int i = 0; i < 16; ++i) { const int t = t0 + bt * 16 + i;
;             win += hn_[i]; const float inv = 1.f / (float)((t + 1) < W ? (t + 1) : W);
;             const f32x2 a = win * inv - hn_[i];
;             *(unsigned*)(Ag + ((size_t)g * MT + rb + t) * 256 + (c & 255)) = pk2(a.x, a.y);
;             win -= (i - W + 1 >= 0) ? hn_[(i - W + 1 >= 0) ? (i - W + 1) : 0] : ring[(i - W + 17) & 15]; }
; #pragma unroll
;         for (int i = 0; i < 16; ++i) ring[i] = hn_[i];
	v_lshlrev_b32_e32 v16, 16, v97
	v_and_b32_e32 v17, 0xffff0000, v97
	v_cvt_pk_bf16_f32 v5, v32, v33
	v_lshl_add_u64 v[32:33], v[8:9], 0, s[58:59]
	v_pk_fma_f32 v[30:31], v[2:3], v[20:21], v[30:31]
	s_or_b32 s58, s56, 45
	s_mov_b32 s59, s45
	v_pk_mul_f32 v[18:19], v[54:55], v[16:17] op_sel_hi:[0,1]
	global_store_dword v[32:33], v5, off nt
	v_pk_fma_f32 v[32:33], v[30:31], s[22:23], v[52:53] op_sel_hi:[1,0,1] neg_lo:[0,0,1] neg_hi:[0,0,1]
	s_lshl_b64 s[58:59], s[58:59], 9
	v_pk_fma_f32 v[30:31], v[2:3], v[82:83], v[30:31] neg_lo:[1,0,0] neg_hi:[1,0,0]
	v_pk_mul_f32 v[96:97], v[2:3], v[18:19]
	s_waitcnt vmcnt(13)
	v_lshlrev_b32_e32 v16, 16, v98
	v_and_b32_e32 v17, 0xffff0000, v98
	v_mov_b32_e32 v54, v55
	v_cvt_pk_bf16_f32 v5, v32, v33
	v_lshl_add_u64 v[32:33], v[8:9], 0, s[58:59]
	v_pk_fma_f32 v[30:31], v[2:3], v[18:19], v[30:31]
	s_or_b32 s58, s56, 46
	s_mov_b32 s59, s45
	v_pk_mul_f32 v[16:17], v[54:55], v[16:17] op_sel_hi:[0,1]
	global_store_dword v[32:33], v5, off nt
	v_pk_fma_f32 v[32:33], v[30:31], s[22:23], v[96:97] op_sel_hi:[1,0,1] neg_lo:[0,0,1] neg_hi:[0,0,1]
	s_lshl_b64 s[58:59], s[58:59], 9
	v_pk_fma_f32 v[30:31], v[2:3], v[86:87], v[30:31] neg_lo:[1,0,0] neg_hi:[1,0,0]
	v_pk_mul_f32 v[54:55], v[2:3], v[16:17]
	v_cvt_pk_bf16_f32 v5, v32, v33
	v_lshl_add_u64 v[32:33], v[8:9], 0, s[58:59]
	v_pk_fma_f32 v[30:31], v[2:3], v[16:17], v[30:31]
	s_or_b32 s58, s56, 47
	s_mov_b32 s59, s45
	global_store_dword v[32:33], v5, off nt
	v_pk_fma_f32 v[32:33], v[30:31], s[22:23], v[54:55] op_sel_hi:[1,0,1] neg_lo:[0,0,1] neg_hi:[0,0,1]
	s_lshl_b64 s[58:59], s[58:59], 9
	v_cvt_pk_bf16_f32 v5, v32, v33
	v_lshl_add_u64 v[32:33], v[8:9], 0, s[58:59]
	global_store_dword v[32:33], v5, off nt
	global_load_dword v5, v[46:47], off
	s_nop 0
	global_load_dword v51, v[46:47], off offset:2048
	v_add_co_u32_e32 v32, vcc, s57, v14
	s_mov_b32 s57, 0x19000
	s_nop 0
	v_addc_co_u32_e32 v33, vcc, 0, v15, vcc
	global_load_dword v53, v[32:33], off offset:-4096
	v_add_co_u32_e32 v34, vcc, s57, v14
	s_mov_b32 s57, 0x1c000
	s_nop 0
	v_addc_co_u32_e32 v35, vcc, 0, v15, vcc
	global_load_dword v57, v[34:35], off offset:2048
	global_load_dword v59, v[32:33], off
	global_load_dword v63, v[32:33], off offset:2048
	v_add_co_u32_e32 v32, vcc, s57, v14
	s_mov_b32 s57, 0x1b000
	s_nop 0
	v_addc_co_u32_e32 v33, vcc, 0, v15, vcc
	global_load_dword v65, v[32:33], off offset:-4096
	v_add_co_u32_e32 v34, vcc, s57, v14
	s_mov_b32 s57, 0x1e000
	s_nop 0
	v_addc_co_u32_e32 v35, vcc, 0, v15, vcc
	global_load_dword v69, v[34:35], off offset:2048
	global_load_dword v71, v[32:33], off
	global_load_dword v75, v[32:33], off offset:2048
	v_add_co_u32_e32 v32, vcc, s57, v14
	s_mov_b32 s57, 0x1d000
	s_nop 0
	v_addc_co_u32_e32 v33, vcc, 0, v15, vcc
	global_load_dword v77, v[32:33], off offset:-4096
	v_add_co_u32_e32 v34, vcc, s57, v14
	s_mov_b32 s57, 0x1f000
	s_nop 0
	v_addc_co_u32_e32 v35, vcc, 0, v15, vcc
	global_load_dword v81, v[34:35], off offset:2048
	global_load_dword v83, v[32:33], off
	global_load_dword v87, v[32:33], off offset:2048
	v_add_co_u32_e32 v14, vcc, s57, v14
	s_or_b32 s58, s56, 48
	s_nop 0
	v_addc_co_u32_e32 v15, vcc, 0, v15, vcc
	global_load_dword v89, v[14:15], off
	global_load_dword v93, v[14:15], off offset:2048
	v_pk_fma_f32 v[14:15], v[2:3], v[44:45], v[30:31] neg_lo:[1,0,0] neg_hi:[1,0,0]
	ds_read_b128 v[30:33], v175 offset:256
	s_mov_b32 s59, s45
	s_lshl_b64 s[58:59], s[58:59], 9
	ds_read_b128 v[34:37], v175 offset:272
	ds_read_b128 v[38:41], v175 offset:288
	ds_read_b128 v[42:45], v175 offset:304
	s_mov_b32 s57, s45
	s_waitcnt vmcnt(15)
	v_lshlrev_b32_e32 v46, 16, v5
	v_and_b32_e32 v47, 0xffff0000, v5
	s_waitcnt lgkmcnt(3)
	v_pk_mul_f32 v[46:47], v[30:31], v[46:47] op_sel_hi:[0,1]
	v_pk_mul_f32 v[48:49], v[2:3], v[46:47]
	s_waitcnt vmcnt(14)
	v_lshlrev_b32_e32 v50, 16, v51
	v_and_b32_e32 v51, 0xffff0000, v51
	v_pk_fma_f32 v[14:15], v[2:3], v[46:47], v[14:15]
	v_pk_mul_f32 v[30:31], v[30:31], v[50:51] op_sel:[1,0]
	v_pk_fma_f32 v[48:49], v[14:15], s[22:23], v[48:49] op_sel_hi:[1,0,1] neg_lo:[0,0,1] neg_hi:[0,0,1]
	v_pk_fma_f32 v[14:15], v[2:3], v[28:29], v[14:15] neg_lo:[1,0,0] neg_hi:[1,0,0]
	v_pk_mul_f32 v[50:51], v[2:3], v[30:31]
	s_waitcnt vmcnt(13)
	v_lshlrev_b32_e32 v52, 16, v53
	v_and_b32_e32 v53, 0xffff0000, v53
	v_cvt_pk_bf16_f32 v5, v48, v49
	v_lshl_add_u64 v[48:49], v[8:9], 0, s[58:59]
	v_pk_fma_f32 v[14:15], v[2:3], v[30:31], v[14:15]
	s_or_b32 s58, s56, 49
	s_mov_b32 s59, s45
	v_pk_mul_f32 v[52:53], v[32:33], v[52:53] op_sel_hi:[0,1]
	v_pk_fma_f32 v[28:29], v[14:15], s[22:23], v[50:51] op_sel_hi:[1,0,1] neg_lo:[0,0,1] neg_hi:[0,0,1]
	s_lshl_b64 s[58:59], s[58:59], 9
	v_pk_fma_f32 v[14:15], v[2:3], v[26:27], v[14:15] neg_lo:[1,0,0] neg_hi:[1,0,0]
	v_pk_mul_f32 v[54:55], v[2:3], v[52:53]
	s_waitcnt vmcnt(12)
	v_lshlrev_b32_e32 v56, 16, v57
	v_and_b32_e32 v57, 0xffff0000, v57
	v_mov_b32_e32 v32, v33
	global_store_dword v[48:49], v5, off nt
	v_cvt_pk_bf16_f32 v5, v28, v29
	v_lshl_add_u64 v[28:29], v[8:9], 0, s[58:59]
	v_pk_fma_f32 v[14:15], v[2:3], v[52:53], v[14:15]
	s_or_b32 s58, s56, 50
	s_mov_b32 s59, s45
	v_pk_mul_f32 v[32:33], v[32:33], v[56:57] op_sel_hi:[0,1]
	v_pk_fma_f32 v[26:27], v[14:15], s[22:23], v[54:55] op_sel_hi:[1,0,1] neg_lo:[0,0,1] neg_hi:[0,0,1]
	s_lshl_b64 s[58:59], s[58:59], 9
	v_pk_fma_f32 v[14:15], v[2:3], v[24:25], v[14:15] neg_lo:[1,0,0] neg_hi:[1,0,0]
	v_pk_mul_f32 v[56:57], v[2:3], v[32:33]
	s_waitcnt vmcnt(12)
	v_lshlrev_b32_e32 v58, 16, v59
	v_and_b32_e32 v59, 0xffff0000, v59
	global_store_dword v[28:29], v5, off nt
	v_cvt_pk_bf16_f32 v5, v26, v27
	v_lshl_add_u64 v[26:27], v[8:9], 0, s[58:59]
	v_pk_fma_f32 v[14:15], v[2:3], v[32:33], v[14:15]
	s_or_b32 s58, s56, 51
	s_mov_b32 s59, s45
	s_waitcnt lgkmcnt(2)
; __device__ __forceinline__ unsigned pk2(float lo, float hi) { f32x2 v = {lo, hi}; bf16x2_t b = __builtin_convertvector(v, bf16x2_t); return __builtin_bit_cast(unsigned, b); }
; __device__ __forceinline__ f32x2 ldx2(const bf16_t* p) { const unsigned w = *(const unsigned*)p; return (f32x2){__builtin_bit_cast(float, w << 16), __builtin_bit_cast(float, w & 0xffff0000u)}; }
; template <int W> __device__ __forceinline__ void pool_unit(const bf16_t* x, const LAS float* rs, f32x2 gn, bf16_t* Ag, size_t rb, int t0, int c, int g) {
;     ...
;     for (int bt = 0; bt < 4; ++bt) {
; #pragma unroll
;         for (int i = 0; i < 16; ++i) hn_[i] = ldx2(x + (rb + t0 + bt * 16 + i) * 1024 + c) * rs[16 + bt * 16 + i] * gn;
; #pragma unroll
;         for (int i = 0; i < 16; ++i) { const int t = t0 + bt * 16 + i;
;             win += hn_[i]; const float inv = 1.f / (float)((t + 1) < W ? (t + 1) : W);
;             const f32x2 a = win * inv - hn_[i];
;             *(unsigned*)(Ag + ((size_t)g * MT + rb + t) * 256 + (c & 255)) = pk2(a.x, a.y);
;             win -= (i - W + 1 >= 0) ? hn_[(i - W + 1 >= 0) ? (i - W + 1) : 0] : ring[(i - W + 17) & 15]; }
; #pragma unroll
;         for (int i = 0; i < 16; ++i) ring[i] = hn_[i];
	v_pk_mul_f32 v[58:59], v[34:35], v[58:59] op_sel_hi:[0,1]
	v_pk_fma_f32 v[24:25], v[14:15], s[22:23], v[56:57] op_sel_hi:[1,0,1] neg_lo:[0,0,1] neg_hi:[0,0,1]
	s_lshl_b64 s[58:59], s[58:59], 9
	v_pk_fma_f32 v[14:15], v[2:3], v[22:23], v[14:15] neg_lo:[1,0,0] neg_hi:[1,0,0]
	v_pk_mul_f32 v[60:61], v[2:3], v[58:59]
	s_waitcnt vmcnt(12)
	v_lshlrev_b32_e32 v62, 16, v63
	v_and_b32_e32 v63, 0xffff0000, v63
	global_store_dword v[26:27], v5, off nt
	v_cvt_pk_bf16_f32 v5, v24, v25
	v_lshl_add_u64 v[24:25], v[8:9], 0, s[58:59]
	v_pk_fma_f32 v[14:15], v[2:3], v[58:59], v[14:15]
	s_or_b32 s58, s56, 52
	s_mov_b32 s59, s45
	v_pk_mul_f32 v[34:35], v[34:35], v[62:63] op_sel:[1,0]
	v_pk_fma_f32 v[22:23], v[14:15], s[22:23], v[60:61] op_sel_hi:[1,0,1] neg_lo:[0,0,1] neg_hi:[0,0,1]
	s_lshl_b64 s[58:59], s[58:59], 9
	v_pk_fma_f32 v[14:15], v[2:3], v[20:21], v[14:15] neg_lo:[1,0,0] neg_hi:[1,0,0]
	v_pk_mul_f32 v[62:63], v[2:3], v[34:35]
	s_waitcnt vmcnt(12)
	v_lshlrev_b32_e32 v64, 16, v65
	v_and_b32_e32 v65, 0xffff0000, v65
	global_store_dword v[24:25], v5, off nt
	v_cvt_pk_bf16_f32 v5, v22, v23
	v_lshl_add_u64 v[22:23], v[8:9], 0, s[58:59]
	v_pk_fma_f32 v[14:15], v[2:3], v[34:35], v[14:15]
	s_or_b32 s58, s56, 53
	s_mov_b32 s59, s45
	v_pk_mul_f32 v[64:65], v[36:37], v[64:65] op_sel_hi:[0,1]
	v_pk_fma_f32 v[20:21], v[14:15], s[22:23], v[62:63] op_sel_hi:[1,0,1] neg_lo:[0,0,1] neg_hi:[0,0,1]
	s_lshl_b64 s[58:59], s[58:59], 9
	v_pk_fma_f32 v[14:15], v[2:3], v[18:19], v[14:15] neg_lo:[1,0,0] neg_hi:[1,0,0]
	v_pk_mul_f32 v[66:67], v[2:3], v[64:65]
	s_waitcnt vmcnt(12)
	v_lshlrev_b32_e32 v68, 16, v69
	v_and_b32_e32 v69, 0xffff0000, v69
	v_mov_b32_e32 v36, v37
	global_store_dword v[22:23], v5, off nt
	v_cvt_pk_bf16_f32 v5, v20, v21
	v_lshl_add_u64 v[20:21], v[8:9], 0, s[58:59]
	v_pk_fma_f32 v[14:15], v[2:3], v[64:65], v[14:15]
	s_or_b32 s58, s56, 54
	s_mov_b32 s59, s45
	v_pk_mul_f32 v[36:37], v[36:37], v[68:69] op_sel_hi:[0,1]
	v_pk_fma_f32 v[18:19], v[14:15], s[22:23], v[66:67] op_sel_hi:[1,0,1] neg_lo:[0,0,1] neg_hi:[0,0,1]
	s_lshl_b64 s[58:59], s[58:59], 9
	v_pk_fma_f32 v[14:15], v[2:3], v[16:17], v[14:15] neg_lo:[1,0,0] neg_hi:[1,0,0]
	v_pk_mul_f32 v[68:69], v[2:3], v[36:37]
	s_waitcnt vmcnt(12)
	v_lshlrev_b32_e32 v70, 16, v71
	v_and_b32_e32 v71, 0xffff0000, v71
	global_store_dword v[20:21], v5, off nt
	v_cvt_pk_bf16_f32 v5, v18, v19
	v_lshl_add_u64 v[18:19], v[8:9], 0, s[58:59]
	v_pk_fma_f32 v[14:15], v[2:3], v[36:37], v[14:15]
	s_or_b32 s58, s56, 55
	s_mov_b32 s59, s45
	s_waitcnt lgkmcnt(1)
	v_pk_mul_f32 v[70:71], v[38:39], v[70:71] op_sel_hi:[0,1]
	v_pk_fma_f32 v[16:17], v[14:15], s[22:23], v[68:69] op_sel_hi:[1,0,1] neg_lo:[0,0,1] neg_hi:[0,0,1]
	s_lshl_b64 s[58:59], s[58:59], 9
	v_pk_fma_f32 v[14:15], v[2:3], v[46:47], v[14:15] neg_lo:[1,0,0] neg_hi:[1,0,0]
	v_pk_mul_f32 v[72:73], v[2:3], v[70:71]
	s_waitcnt vmcnt(12)
	v_lshlrev_b32_e32 v74, 16, v75
	v_and_b32_e32 v75, 0xffff0000, v75
	global_store_dword v[18:19], v5, off nt
	v_cvt_pk_bf16_f32 v5, v16, v17
	v_lshl_add_u64 v[16:17], v[8:9], 0, s[58:59]
	v_pk_fma_f32 v[14:15], v[2:3], v[70:71], v[14:15]
	s_or_b32 s58, s56, 56
	s_mov_b32 s59, s45
	v_pk_mul_f32 v[38:39], v[38:39], v[74:75] op_sel:[1,0]
	global_store_dword v[16:17], v5, off nt
	v_pk_fma_f32 v[16:17], v[14:15], s[22:23], v[72:73] op_sel_hi:[1,0,1] neg_lo:[0,0,1] neg_hi:[0,0,1]
	s_lshl_b64 s[58:59], s[58:59], 9
	v_pk_fma_f32 v[14:15], v[2:3], v[30:31], v[14:15] neg_lo:[1,0,0] neg_hi:[1,0,0]
	v_pk_mul_f32 v[74:75], v[2:3], v[38:39]
	s_waitcnt vmcnt(13)
; __device__ __forceinline__ unsigned pk2(float lo, float hi) { f32x2 v = {lo, hi}; bf16x2_t b = __builtin_convertvector(v, bf16x2_t); return __builtin_bit_cast(unsigned, b); }
; __device__ __forceinline__ f32x2 ldx2(const bf16_t* p) { const unsigned w = *(const unsigned*)p; return (f32x2){__builtin_bit_cast(float, w << 16), __builtin_bit_cast(float, w & 0xffff0000u)}; }
; template <int W> __device__ __forceinline__ void pool_unit(const bf16_t* x, const LAS float* rs, f32x2 gn, bf16_t* Ag, size_t rb, int t0, int c, int g) {
;     ...
;     for (int bt = 0; bt < 4; ++bt) {
; #pragma unroll
;         for (int i = 0; i < 16; ++i) hn_[i] = ldx2(x + (rb + t0 + bt * 16 + i) * 1024 + c) * rs[16 + bt * 16 + i] * gn;
; #pragma unroll
;         for (int i = 0; i < 16; ++i) { const int t = t0 + bt * 16 + i;
;             win += hn_[i]; const float inv = 1.f / (float)((t + 1) < W ? (t + 1) : W);
;             const f32x2 a = win * inv - hn_[i];
;             *(unsigned*)(Ag + ((size_t)g * MT + rb + t) * 256 + (c & 255)) = pk2(a.x, a.y);
;             win -= (i - W + 1 >= 0) ? hn_[(i - W + 1 >= 0) ? (i - W + 1) : 0] : ring[(i - W + 17) & 15]; }
; #pragma unroll
;         for (int i = 0; i < 16; ++i) ring[i] = hn_[i];
	v_lshlrev_b32_e32 v76, 16, v77
	v_and_b32_e32 v77, 0xffff0000, v77
	v_cvt_pk_bf16_f32 v5, v16, v17
	v_lshl_add_u64 v[16:17], v[8:9], 0, s[58:59]
	v_pk_fma_f32 v[14:15], v[2:3], v[38:39], v[14:15]
	s_or_b32 s58, s56, 57
	s_mov_b32 s59, s45
	v_pk_mul_f32 v[76:77], v[40:41], v[76:77] op_sel_hi:[0,1]
	global_store_dword v[16:17], v5, off nt
	v_pk_fma_f32 v[16:17], v[14:15], s[22:23], v[74:75] op_sel_hi:[1,0,1] neg_lo:[0,0,1] neg_hi:[0,0,1]
	s_lshl_b64 s[58:59], s[58:59], 9
	v_pk_fma_f32 v[14:15], v[2:3], v[52:53], v[14:15] neg_lo:[1,0,0] neg_hi:[1,0,0]
	v_pk_mul_f32 v[78:79], v[2:3], v[76:77]
	s_waitcnt vmcnt(13)
	v_lshlrev_b32_e32 v80, 16, v81
	v_and_b32_e32 v81, 0xffff0000, v81
	v_mov_b32_e32 v40, v41
	v_cvt_pk_bf16_f32 v5, v16, v17
	v_lshl_add_u64 v[16:17], v[8:9], 0, s[58:59]
	v_pk_fma_f32 v[14:15], v[2:3], v[76:77], v[14:15]
	s_or_b32 s58, s56, 58
	s_mov_b32 s59, s45
	v_pk_mul_f32 v[40:41], v[40:41], v[80:81] op_sel_hi:[0,1]
	global_store_dword v[16:17], v5, off nt
	v_pk_fma_f32 v[16:17], v[14:15], s[22:23], v[78:79] op_sel_hi:[1,0,1] neg_lo:[0,0,1] neg_hi:[0,0,1]
	s_lshl_b64 s[58:59], s[58:59], 9
	v_pk_fma_f32 v[14:15], v[2:3], v[32:33], v[14:15] neg_lo:[1,0,0] neg_hi:[1,0,0]
	v_pk_mul_f32 v[80:81], v[2:3], v[40:41]
	s_waitcnt vmcnt(13)
	v_lshlrev_b32_e32 v82, 16, v83
	v_and_b32_e32 v83, 0xffff0000, v83
	v_cvt_pk_bf16_f32 v5, v16, v17
	v_lshl_add_u64 v[16:17], v[8:9], 0, s[58:59]
	v_pk_fma_f32 v[14:15], v[2:3], v[40:41], v[14:15]
	s_or_b32 s58, s56, 59
	s_mov_b32 s59, s45
	s_waitcnt lgkmcnt(0)
	v_pk_mul_f32 v[82:83], v[42:43], v[82:83] op_sel_hi:[0,1]
	global_store_dword v[16:17], v5, off nt
	v_pk_fma_f32 v[16:17], v[14:15], s[22:23], v[80:81] op_sel_hi:[1,0,1] neg_lo:[0,0,1] neg_hi:[0,0,1]
	s_lshl_b64 s[58:59], s[58:59], 9
	v_pk_fma_f32 v[14:15], v[2:3], v[58:59], v[14:15] neg_lo:[1,0,0] neg_hi:[1,0,0]
	v_pk_mul_f32 v[84:85], v[2:3], v[82:83]
	s_waitcnt vmcnt(13)
	v_lshlrev_b32_e32 v86, 16, v87
	v_and_b32_e32 v87, 0xffff0000, v87
	v_cvt_pk_bf16_f32 v5, v16, v17
	v_lshl_add_u64 v[16:17], v[8:9], 0, s[58:59]
	v_pk_fma_f32 v[14:15], v[2:3], v[82:83], v[14:15]
	s_or_b32 s58, s56, 60
	s_mov_b32 s59, s45
	v_pk_mul_f32 v[42:43], v[42:43], v[86:87] op_sel:[1,0]
	global_store_dword v[16:17], v5, off nt
	v_pk_fma_f32 v[16:17], v[14:15], s[22:23], v[84:85] op_sel_hi:[1,0,1] neg_lo:[0,0,1] neg_hi:[0,0,1]
	s_lshl_b64 s[58:59], s[58:59], 9
	v_pk_fma_f32 v[14:15], v[2:3], v[34:35], v[14:15] neg_lo:[1,0,0] neg_hi:[1,0,0]
	v_pk_mul_f32 v[86:87], v[2:3], v[42:43]
	s_waitcnt vmcnt(13)
	v_lshlrev_b32_e32 v88, 16, v89
	v_and_b32_e32 v89, 0xffff0000, v89
	v_cvt_pk_bf16_f32 v5, v16, v17
	v_lshl_add_u64 v[16:17], v[8:9], 0, s[58:59]
	v_pk_fma_f32 v[14:15], v[2:3], v[42:43], v[14:15]
	s_or_b32 s58, s56, 61
	s_mov_b32 s59, s45
	v_pk_mul_f32 v[88:89], v[44:45], v[88:89] op_sel_hi:[0,1]
	global_store_dword v[16:17], v5, off nt
	v_pk_fma_f32 v[16:17], v[14:15], s[22:23], v[86:87] op_sel_hi:[1,0,1] neg_lo:[0,0,1] neg_hi:[0,0,1]
	s_lshl_b64 s[58:59], s[58:59], 9
	v_pk_fma_f32 v[14:15], v[2:3], v[64:65], v[14:15] neg_lo:[1,0,0] neg_hi:[1,0,0]
	v_pk_mul_f32 v[90:91], v[2:3], v[88:89]
	s_waitcnt vmcnt(13)
	v_lshlrev_b32_e32 v92, 16, v93
	v_and_b32_e32 v93, 0xffff0000, v93
	v_mov_b32_e32 v44, v45
	v_cvt_pk_bf16_f32 v5, v16, v17
	v_lshl_add_u64 v[16:17], v[8:9], 0, s[58:59]
	v_pk_fma_f32 v[14:15], v[2:3], v[88:89], v[14:15]
	s_or_b32 s56, s56, 62
	v_pk_mul_f32 v[44:45], v[44:45], v[92:93] op_sel_hi:[0,1]
	global_store_dword v[16:17], v5, off nt
	v_pk_fma_f32 v[16:17], v[14:15], s[22:23], v[90:91] op_sel_hi:[1,0,1] neg_lo:[0,0,1] neg_hi:[0,0,1]
	s_lshl_b64 s[56:57], s[56:57], 9
	v_pk_fma_f32 v[14:15], v[2:3], v[36:37], v[14:15] neg_lo:[1,0,0] neg_hi:[1,0,0]
	v_pk_mul_f32 v[92:93], v[2:3], v[44:45]
	v_cvt_pk_bf16_f32 v5, v16, v17
	v_lshl_add_u64 v[16:17], v[8:9], 0, s[56:57]
	v_pk_fma_f32 v[14:15], v[2:3], v[44:45], v[14:15]
	global_store_dword v[16:17], v5, off nt
	v_pk_fma_f32 v[16:17], v[14:15], s[22:23], v[92:93] op_sel_hi:[1,0,1] neg_lo:[0,0,1] neg_hi:[0,0,1]
	s_xor_b64 s[56:57], exec, -1

; __device__ __forceinline__ f32x2 ldx2(const bf16_t* p) { const unsigned w = *(const unsigned*)p; return (f32x2){__builtin_bit_cast(float, w << 16), __builtin_bit_cast(float, w & 0xffff0000u)}; }
; template <int W> __device__ __forceinline__ void pool_unit(const bf16_t* x, const LAS float* rs, f32x2 gn, bf16_t* Ag, size_t rb, int t0, int c, int g) {
;     ...
;     for (int i = 0; i < 16; ++i) { const int t = t0 - 16 + i; ring[i] = (t >= 0) ? ldx2(x + (rb + t) * 1024 + c) * rs[i] * gn : (f32x2){0.f, 0.f}; }
;     f32x2 win = (f32x2){0.f, 0.f};
; #pragma unroll
;     for (int i = 16 - (W - 1); i < 16; ++i) win += ring[i];
; #pragma unroll
;     for (int bt = 0; bt < 4; ++bt) {
; #pragma unroll
;         for (int i = 0; i < 16; ++i) hn_[i] = ldx2(x + (rb + t0 + bt * 16 + i) * 1024 + c) * rs[16 + bt * 16 + i] * gn;
.LBB0_1243:
	s_or_b32 s0, s48, s16
	s_mov_b32 s1, s49
	s_lshl_b64 s[0:1], s[0:1], 11
	v_lshl_add_u64 v[16:17], v[6:7], 0, s[0:1]
	v_add_co_u32_e32 v14, vcc, s23, v16
	s_movk_i32 s0, 0x1000
	s_nop 0
	v_addc_co_u32_e32 v15, vcc, 0, v17, vcc
	v_add_co_u32_e32 v18, vcc, s0, v16
	global_load_dword v5, v[16:17], off
	global_load_dword v31, v[16:17], off offset:2048
	v_addc_co_u32_e32 v19, vcc, 0, v17, vcc
	global_load_dword v44, v[14:15], off offset:-4096
	global_load_dword v45, v[18:19], off offset:2048
	global_load_dword v48, v[14:15], off
	global_load_dword v49, v[14:15], off offset:2048
	v_add_co_u32_e32 v14, vcc, s31, v16
	s_movk_i32 s0, 0x3000
	s_nop 0
	v_addc_co_u32_e32 v15, vcc, 0, v17, vcc
	v_add_co_u32_e32 v18, vcc, s0, v16
	global_load_dword v50, v[14:15], off offset:-4096
	s_nop 0
	v_addc_co_u32_e32 v19, vcc, 0, v17, vcc
	v_add_co_u32_e32 v26, vcc, s33, v16
	s_movk_i32 s0, 0x5000
	s_nop 0
	v_addc_co_u32_e32 v27, vcc, 0, v17, vcc
	global_load_dword v86, v[18:19], off offset:2048
	global_load_dword v87, v[14:15], off
	global_load_dword v88, v[14:15], off offset:2048
	v_add_co_u32_e32 v14, vcc, s0, v16
	global_load_dword v89, v[26:27], off offset:-4096
	global_load_dword v122, v[26:27], off
	v_addc_co_u32_e32 v15, vcc, 0, v17, vcc
	global_load_dword v90, v[14:15], off offset:2048
	v_add_co_u32_e32 v80, vcc, s19, v16
	ds_read_b128 v[18:21], v175 offset:64
	ds_read_b128 v[22:25], v175 offset:80
	global_load_dword v123, v[26:27], off offset:2048
	v_addc_co_u32_e32 v81, vcc, 0, v17, vcc
	global_load_dword v124, v[80:81], off offset:-4096
	s_movk_i32 s0, 0x7000
	v_add_co_u32_e32 v26, vcc, s0, v16
	v_pk_add_f32 v[28:29], v[68:69], 0 op_sel_hi:[1,0]
	s_nop 0
	v_addc_co_u32_e32 v27, vcc, 0, v17, vcc
	global_load_dword v125, v[26:27], off offset:2048
	v_pk_add_f32 v[26:27], v[28:29], v[38:39]
	ds_read_b128 v[82:85], v175 offset:96
	ds_read_b128 v[104:107], v175 offset:112
	v_pk_add_f32 v[26:27], v[26:27], v[70:71]
	s_waitcnt lgkmcnt(3)
	v_mov_b32_e32 v28, v21
	v_pk_add_f32 v[26:27], v[26:27], v[46:47]
	s_min_u32 s0, s16, 15
	v_pk_add_f32 v[26:27], v[26:27], v[66:67]
	s_add_i32 s0, s0, 1
	v_pk_add_f32 v[26:27], v[26:27], v[42:43]
	s_or_b32 s44, s16, 1
	v_pk_add_f32 v[26:27], v[26:27], v[64:65]
	v_lshl_add_u64 v[14:15], s[48:49], 0, v[10:11]
	v_pk_add_f32 v[26:27], v[26:27], v[40:41]
	s_andn2_b64 s[54:55], s[54:55], exec
	v_pk_add_f32 v[26:27], v[26:27], v[62:63]
	s_waitcnt vmcnt(14)
	v_lshlrev_b32_e32 v30, 16, v31
	v_pk_add_f32 v[26:27], v[26:27], v[36:37]
	v_and_b32_e32 v31, 0xffff0000, v31
	v_pk_add_f32 v[26:27], v[26:27], v[60:61]
	v_pk_mul_f32 v[74:75], v[18:19], v[30:31] op_sel:[1,0]
	v_pk_add_f32 v[26:27], v[26:27], v[34:35]
	v_pk_mul_f32 v[112:113], v[2:3], v[74:75]
	v_pk_add_f32 v[26:27], v[26:27], v[58:59]
	s_nop 0
	v_pk_add_f32 v[26:27], v[26:27], v[32:33]
	s_nop 0
	v_pk_add_f32 v[108:109], v[26:27], v[76:77]
	v_lshlrev_b32_e32 v26, 16, v5
	v_and_b32_e32 v27, 0xffff0000, v5
	v_pk_mul_f32 v[78:79], v[18:19], v[26:27] op_sel_hi:[0,1]
	s_waitcnt vmcnt(13)
	v_lshlrev_b32_e32 v18, 16, v44
	v_and_b32_e32 v19, 0xffff0000, v44
	v_pk_mul_f32 v[72:73], v[20:21], v[18:19] op_sel_hi:[0,1]
	s_waitcnt vmcnt(11)
	v_lshlrev_b32_e32 v18, 16, v48
	v_and_b32_e32 v19, 0xffff0000, v48
	s_waitcnt lgkmcnt(2)
	v_pk_mul_f32 v[54:55], v[22:23], v[18:19] op_sel_hi:[0,1]
	s_waitcnt vmcnt(10)
	v_lshlrev_b32_e32 v18, 16, v49
	v_and_b32_e32 v19, 0xffff0000, v49
	v_pk_mul_f32 v[52:53], v[22:23], v[18:19] op_sel:[1,0]
	s_waitcnt vmcnt(9)
	v_lshlrev_b32_e32 v18, 16, v50
	v_and_b32_e32 v19, 0xffff0000, v50
	v_pk_mul_f32 v[50:51], v[24:25], v[18:19] op_sel_hi:[0,1]
	s_waitcnt vmcnt(8)
	v_lshlrev_b32_e32 v18, 16, v86
	v_and_b32_e32 v19, 0xffff0000, v86
	v_mov_b32_e32 v20, v25
	v_pk_mul_f32 v[48:49], v[20:21], v[18:19] op_sel_hi:[0,1]
	s_waitcnt vmcnt(7)
	v_lshlrev_b32_e32 v18, 16, v87
	v_and_b32_e32 v19, 0xffff0000, v87
	v_lshlrev_b32_e32 v26, 16, v45
	v_and_b32_e32 v27, 0xffff0000, v45
	s_waitcnt lgkmcnt(1)
	v_pk_mul_f32 v[44:45], v[82:83], v[18:19] op_sel_hi:[0,1]
	s_waitcnt vmcnt(6)
	v_lshlrev_b32_e32 v18, 16, v88
	v_and_b32_e32 v19, 0xffff0000, v88
	v_pk_mul_f32 v[30:31], v[82:83], v[18:19] op_sel:[1,0]
	s_waitcnt vmcnt(5)
	v_lshlrev_b32_e32 v18, 16, v89
	v_and_b32_e32 v19, 0xffff0000, v89
	v_pk_mul_f32 v[56:57], v[28:29], v[26:27] op_sel_hi:[0,1]
	v_pk_mul_f32 v[28:29], v[84:85], v[18:19] op_sel_hi:[0,1]
	s_waitcnt vmcnt(3)
	v_lshlrev_b32_e32 v18, 16, v90
	v_and_b32_e32 v19, 0xffff0000, v90
	v_mov_b32_e32 v20, v85
	v_pk_mul_f32 v[26:27], v[20:21], v[18:19] op_sel_hi:[0,1]
	v_lshlrev_b32_e32 v18, 16, v122
	v_and_b32_e32 v19, 0xffff0000, v122
	s_waitcnt lgkmcnt(0)
	v_pk_mul_f32 v[24:25], v[104:105], v[18:19] op_sel_hi:[0,1]
	s_waitcnt vmcnt(2)
	v_lshlrev_b32_e32 v18, 16, v123
	v_and_b32_e32 v19, 0xffff0000, v123
	v_pk_mul_f32 v[22:23], v[104:105], v[18:19] op_sel:[1,0]
	s_waitcnt vmcnt(1)
; __device__ __forceinline__ unsigned pk2(float lo, float hi) { f32x2 v = {lo, hi}; bf16x2_t b = __builtin_convertvector(v, bf16x2_t); return __builtin_bit_cast(unsigned, b); }
; template <int W> __device__ __forceinline__ void pool_unit(const bf16_t* x, const LAS float* rs, f32x2 gn, bf16_t* Ag, size_t rb, int t0, int c, int g) {
;     ...
;         for (int i = 0; i < 16; ++i) { const int t = t0 + bt * 16 + i;
;             win += hn_[i]; const float inv = 1.f / (float)((t + 1) < W ? (t + 1) : W);
;             const f32x2 a = win * inv - hn_[i];
;             *(unsigned*)(Ag + ((size_t)g * MT + rb + t) * 256 + (c & 255)) = pk2(a.x, a.y);
;             win -= (i - W + 1 >= 0) ? hn_[(i - W + 1 >= 0) ? (i - W + 1) : 0] : ring[(i - W + 17) & 15]; }
	v_lshlrev_b32_e32 v18, 16, v124
	v_and_b32_e32 v19, 0xffff0000, v124
	v_cvt_f32_ubyte0_e32 v5, s0
	v_pk_mul_f32 v[18:19], v[106:107], v[18:19] op_sel_hi:[0,1]
	v_div_scale_f32 v106, s[0:1], v5, v5, 1.0
	v_mov_b32_e32 v84, v107
	v_rcp_f32_e32 v107, v106
	v_pk_fma_f32 v[104:105], v[2:3], v[78:79], v[108:109]
	s_min_u32 s0, s44, 15
	s_add_i32 s0, s0, 1
	v_fma_f32 v108, -v106, v107, 1.0
	v_fmac_f32_e32 v107, v108, v107
	v_div_scale_f32 v108, vcc, 1.0, v5, 1.0
	v_mul_f32_e32 v109, v108, v107
	v_fma_f32 v122, -v106, v109, v108
	v_fmac_f32_e32 v109, v122, v107
	v_fma_f32 v106, -v106, v109, v108
	v_div_fmas_f32 v106, v106, v107, v109
	v_cvt_f32_ubyte0_e32 v108, s0
	v_pk_mul_f32 v[110:111], v[2:3], v[78:79]
	v_div_fixup_f32 v106, v106, v5, 1.0
	v_div_scale_f32 v109, s[0:1], v108, v108, 1.0
	v_pk_fma_f32 v[106:107], v[106:107], v[104:105], v[110:111] op_sel_hi:[0,1,1] neg_lo:[0,0,1] neg_hi:[0,0,1]
	v_rcp_f32_e32 v110, v109
	v_cvt_pk_bf16_f32 v5, v106, v107
	v_or_b32_e32 v106, s16, v14
	v_mov_b32_e32 v107, v15
	v_lshlrev_b64 v[106:107], 9, v[106:107]
	v_lshl_add_u64 v[106:107], v[8:9], 0, v[106:107]
	global_store_dword v[106:107], v5, off nt
	v_fma_f32 v5, -v109, v110, 1.0
	v_fmac_f32_e32 v110, v5, v110
	v_div_scale_f32 v5, vcc, 1.0, v108, 1.0
	v_pk_add_f32 v[68:69], v[104:105], v[68:69] neg_lo:[0,1] neg_hi:[0,1]
	v_mul_f32_e32 v104, v5, v110
	v_fma_f32 v105, -v109, v104, v5
	v_fmac_f32_e32 v104, v105, v110
	v_fma_f32 v5, -v109, v104, v5
	v_div_fmas_f32 v5, v5, v110, v104
	v_pk_fma_f32 v[68:69], v[2:3], v[74:75], v[68:69]
	v_div_fixup_f32 v104, v5, v108, 1.0
	v_pk_fma_f32 v[104:105], v[104:105], v[68:69], v[112:113] op_sel_hi:[0,1,1] neg_lo:[0,0,1] neg_hi:[0,0,1]
	v_cvt_pk_bf16_f32 v5, v104, v105
	v_or_b32_e32 v104, s44, v14
	s_or_b32 s44, s16, 2
	s_min_u32 s0, s44, 15
	s_add_i32 s0, s0, 1
	v_cvt_f32_ubyte0_e32 v106, s0
	v_div_scale_f32 v107, s[0:1], v106, v106, 1.0
	v_rcp_f32_e32 v108, v107
	v_mov_b32_e32 v105, v15
	v_lshlrev_b64 v[104:105], 9, v[104:105]
	v_lshl_add_u64 v[104:105], v[8:9], 0, v[104:105]
	global_store_dword v[104:105], v5, off nt
	v_fma_f32 v5, -v107, v108, 1.0
	v_fmac_f32_e32 v108, v5, v108
	v_div_scale_f32 v5, vcc, 1.0, v106, 1.0
	v_pk_add_f32 v[38:39], v[68:69], v[38:39] neg_lo:[0,1] neg_hi:[0,1]
	v_mul_f32_e32 v68, v5, v108
	v_fma_f32 v69, -v107, v68, v5
	v_fmac_f32_e32 v68, v69, v108
	v_fma_f32 v5, -v107, v68, v5
	v_div_fmas_f32 v5, v5, v108, v68
	v_pk_mul_f32 v[114:115], v[2:3], v[72:73]
	v_pk_fma_f32 v[38:39], v[2:3], v[72:73], v[38:39]
	v_div_fixup_f32 v68, v5, v106, 1.0
	v_pk_fma_f32 v[68:69], v[68:69], v[38:39], v[114:115] op_sel_hi:[0,1,1] neg_lo:[0,0,1] neg_hi:[0,0,1]
	v_cvt_pk_bf16_f32 v5, v68, v69
	v_or_b32_e32 v68, s44, v14
	s_or_b32 s44, s16, 3
	s_min_u32 s0, s44, 15
	s_add_i32 s0, s0, 1
	v_cvt_f32_ubyte0_e32 v104, s0
	v_div_scale_f32 v105, s[0:1], v104, v104, 1.0
	v_rcp_f32_e32 v106, v105
	v_mov_b32_e32 v69, v15
	v_lshlrev_b64 v[68:69], 9, v[68:69]
	v_lshl_add_u64 v[68:69], v[8:9], 0, v[68:69]
	global_store_dword v[68:69], v5, off nt
	v_fma_f32 v5, -v105, v106, 1.0
	v_fmac_f32_e32 v106, v5, v106
	v_div_scale_f32 v5, vcc, 1.0, v104, 1.0
	v_mul_f32_e32 v68, v5, v106
	v_fma_f32 v69, -v105, v68, v5
	v_fmac_f32_e32 v68, v69, v106
	v_fma_f32 v5, -v105, v68, v5
	v_pk_add_f32 v[38:39], v[38:39], v[70:71] neg_lo:[0,1] neg_hi:[0,1]
	v_div_fmas_f32 v5, v5, v106, v68
	v_pk_mul_f32 v[116:117], v[2:3], v[56:57]
	v_pk_fma_f32 v[38:39], v[2:3], v[56:57], v[38:39]
	v_div_fixup_f32 v68, v5, v104, 1.0
	v_pk_fma_f32 v[68:69], v[68:69], v[38:39], v[116:117] op_sel_hi:[0,1,1] neg_lo:[0,0,1] neg_hi:[0,0,1]
	v_cvt_pk_bf16_f32 v5, v68, v69
	v_or_b32_e32 v68, s44, v14
	s_or_b32 s44, s16, 4
	s_min_u32 s0, s44, 15
	s_add_i32 s0, s0, 1
	v_cvt_f32_ubyte0_e32 v70, s0
	v_div_scale_f32 v71, s[0:1], v70, v70, 1.0
	v_rcp_f32_e32 v104, v71
	v_mov_b32_e32 v69, v15
	v_lshlrev_b64 v[68:69], 9, v[68:69]
	v_lshl_add_u64 v[68:69], v[8:9], 0, v[68:69]
	global_store_dword v[68:69], v5, off nt
	v_fma_f32 v5, -v71, v104, 1.0
	v_fmac_f32_e32 v104, v5, v104
	v_div_scale_f32 v5, vcc, 1.0, v70, 1.0
	v_pk_add_f32 v[38:39], v[38:39], v[46:47] neg_lo:[0,1] neg_hi:[0,1]
	v_mul_f32_e32 v46, v5, v104
	v_fma_f32 v47, -v71, v46, v5
	v_fmac_f32_e32 v46, v47, v104
	v_fma_f32 v5, -v71, v46, v5
	v_div_fmas_f32 v5, v5, v104, v46
	v_pk_mul_f32 v[118:119], v[2:3], v[54:55]
	v_pk_fma_f32 v[38:39], v[2:3], v[54:55], v[38:39]
	v_div_fixup_f32 v46, v5, v70, 1.0
	v_pk_fma_f32 v[46:47], v[46:47], v[38:39], v[118:119] op_sel_hi:[0,1,1] neg_lo:[0,0,1] neg_hi:[0,0,1]
	v_cvt_pk_bf16_f32 v5, v46, v47
	v_or_b32_e32 v46, s44, v14
	s_or_b32 s44, s16, 5
	s_min_u32 s0, s44, 15
	s_add_i32 s0, s0, 1
	v_cvt_f32_ubyte0_e32 v68, s0
	v_div_scale_f32 v69, s[0:1], v68, v68, 1.0
	v_rcp_f32_e32 v70, v69
	v_mov_b32_e32 v47, v15
	v_lshlrev_b64 v[46:47], 9, v[46:47]
	v_lshl_add_u64 v[46:47], v[8:9], 0, v[46:47]
	global_store_dword v[46:47], v5, off nt
	v_fma_f32 v5, -v69, v70, 1.0
	v_fmac_f32_e32 v70, v5, v70
	v_div_scale_f32 v5, vcc, 1.0, v68, 1.0
	v_mul_f32_e32 v46, v5, v70
	v_fma_f32 v47, -v69, v46, v5
	v_fmac_f32_e32 v46, v47, v70
	v_fma_f32 v5, -v69, v46, v5
	v_pk_add_f32 v[38:39], v[38:39], v[66:67] neg_lo:[0,1] neg_hi:[0,1]
	v_div_fmas_f32 v5, v5, v70, v46
	v_pk_mul_f32 v[120:121], v[2:3], v[52:53]
	v_pk_fma_f32 v[38:39], v[2:3], v[52:53], v[38:39]
	v_div_fixup_f32 v46, v5, v68, 1.0
	v_pk_fma_f32 v[46:47], v[46:47], v[38:39], v[120:121] op_sel_hi:[0,1,1] neg_lo:[0,0,1] neg_hi:[0,0,1]
	v_cvt_pk_bf16_f32 v5, v46, v47
	v_or_b32_e32 v46, s44, v14
	s_or_b32 s44, s16, 6
	s_min_u32 s0, s44, 15
	s_add_i32 s0, s0, 1
	v_cvt_f32_ubyte0_e32 v66, s0
	v_div_scale_f32 v67, s[0:1], v66, v66, 1.0
	v_rcp_f32_e32 v68, v67
; __device__ __forceinline__ unsigned pk2(float lo, float hi) { f32x2 v = {lo, hi}; bf16x2_t b = __builtin_convertvector(v, bf16x2_t); return __builtin_bit_cast(unsigned, b); }
; template <int W> __device__ __forceinline__ void pool_unit(const bf16_t* x, const LAS float* rs, f32x2 gn, bf16_t* Ag, size_t rb, int t0, int c, int g) {
;     ...
;         for (int i = 0; i < 16; ++i) { const int t = t0 + bt * 16 + i;
;             win += hn_[i]; const float inv = 1.f / (float)((t + 1) < W ? (t + 1) : W);
;             const f32x2 a = win * inv - hn_[i];
;             *(unsigned*)(Ag + ((size_t)g * MT + rb + t) * 256 + (c & 255)) = pk2(a.x, a.y);
;             win -= (i - W + 1 >= 0) ? hn_[(i - W + 1 >= 0) ? (i - W + 1) : 0] : ring[(i - W + 17) & 15]; }
	v_mov_b32_e32 v47, v15
	v_lshlrev_b64 v[46:47], 9, v[46:47]
	v_lshl_add_u64 v[46:47], v[8:9], 0, v[46:47]
	global_store_dword v[46:47], v5, off nt
	v_fma_f32 v5, -v67, v68, 1.0
	v_fmac_f32_e32 v68, v5, v68
	v_div_scale_f32 v5, vcc, 1.0, v66, 1.0
	v_pk_add_f32 v[38:39], v[38:39], v[42:43] neg_lo:[0,1] neg_hi:[0,1]
	v_mul_f32_e32 v42, v5, v68
	v_fma_f32 v43, -v67, v42, v5
	v_fmac_f32_e32 v42, v43, v68
	v_fma_f32 v5, -v67, v42, v5
	v_div_fmas_f32 v5, v5, v68, v42
	v_pk_mul_f32 v[100:101], v[2:3], v[50:51]
	v_pk_fma_f32 v[38:39], v[2:3], v[50:51], v[38:39]
	v_div_fixup_f32 v42, v5, v66, 1.0
	v_pk_fma_f32 v[42:43], v[42:43], v[38:39], v[100:101] op_sel_hi:[0,1,1] neg_lo:[0,0,1] neg_hi:[0,0,1]
	v_cvt_pk_bf16_f32 v5, v42, v43
	v_or_b32_e32 v42, s44, v14
	s_or_b32 s44, s16, 7
	s_min_u32 s0, s44, 15
	s_add_i32 s0, s0, 1
	v_cvt_f32_ubyte0_e32 v46, s0
	v_div_scale_f32 v47, s[0:1], v46, v46, 1.0
	v_rcp_f32_e32 v66, v47
	v_mov_b32_e32 v43, v15
	v_lshlrev_b64 v[42:43], 9, v[42:43]
	v_lshl_add_u64 v[42:43], v[8:9], 0, v[42:43]
	global_store_dword v[42:43], v5, off nt
	v_fma_f32 v5, -v47, v66, 1.0
	v_fmac_f32_e32 v66, v5, v66
	v_div_scale_f32 v5, vcc, 1.0, v46, 1.0
	v_mul_f32_e32 v42, v5, v66
	v_fma_f32 v43, -v47, v42, v5
	v_fmac_f32_e32 v42, v43, v66
	v_fma_f32 v5, -v47, v42, v5
	v_pk_add_f32 v[38:39], v[38:39], v[64:65] neg_lo:[0,1] neg_hi:[0,1]
	v_div_fmas_f32 v5, v5, v66, v42
	v_pk_mul_f32 v[98:99], v[2:3], v[48:49]
	v_pk_fma_f32 v[38:39], v[2:3], v[48:49], v[38:39]
	v_div_fixup_f32 v42, v5, v46, 1.0
	v_pk_fma_f32 v[42:43], v[42:43], v[38:39], v[98:99] op_sel_hi:[0,1,1] neg_lo:[0,0,1] neg_hi:[0,0,1]
	v_cvt_pk_bf16_f32 v5, v42, v43
	v_or_b32_e32 v42, s44, v14
	s_or_b32 s44, s16, 8
	s_min_u32 s0, s44, 15
	s_add_i32 s0, s0, 1
	v_cvt_f32_ubyte0_e32 v46, s0
	v_div_scale_f32 v47, s[0:1], v46, v46, 1.0
	v_rcp_f32_e32 v64, v47
	v_mov_b32_e32 v43, v15
	v_lshlrev_b64 v[42:43], 9, v[42:43]
	v_lshl_add_u64 v[42:43], v[8:9], 0, v[42:43]
	global_store_dword v[42:43], v5, off nt
	v_fma_f32 v5, -v47, v64, 1.0
	v_fmac_f32_e32 v64, v5, v64
	v_div_scale_f32 v5, vcc, 1.0, v46, 1.0
	v_pk_add_f32 v[38:39], v[38:39], v[40:41] neg_lo:[0,1] neg_hi:[0,1]
	v_mul_f32_e32 v40, v5, v64
	v_fma_f32 v41, -v47, v40, v5
	v_fmac_f32_e32 v40, v41, v64
	v_fma_f32 v5, -v47, v40, v5
	v_div_fmas_f32 v5, v5, v64, v40
	v_pk_mul_f32 v[96:97], v[2:3], v[44:45]
	v_pk_fma_f32 v[38:39], v[2:3], v[44:45], v[38:39]
	v_div_fixup_f32 v40, v5, v46, 1.0
	v_pk_fma_f32 v[40:41], v[40:41], v[38:39], v[96:97] op_sel_hi:[0,1,1] neg_lo:[0,0,1] neg_hi:[0,0,1]
	v_cvt_pk_bf16_f32 v5, v40, v41
	v_or_b32_e32 v40, s44, v14
	s_or_b32 s44, s16, 9
	s_min_u32 s0, s44, 15
	s_add_i32 s0, s0, 1
	v_cvt_f32_ubyte0_e32 v42, s0
	v_div_scale_f32 v43, s[0:1], v42, v42, 1.0
	v_rcp_f32_e32 v46, v43
	v_mov_b32_e32 v41, v15
	v_lshlrev_b64 v[40:41], 9, v[40:41]
	v_lshl_add_u64 v[40:41], v[8:9], 0, v[40:41]
	global_store_dword v[40:41], v5, off nt
	v_fma_f32 v5, -v43, v46, 1.0
	v_fmac_f32_e32 v46, v5, v46
	v_div_scale_f32 v5, vcc, 1.0, v42, 1.0
	v_mul_f32_e32 v40, v5, v46
	v_fma_f32 v41, -v43, v40, v5
	v_fmac_f32_e32 v40, v41, v46
	v_fma_f32 v5, -v43, v40, v5
	v_pk_add_f32 v[38:39], v[38:39], v[62:63] neg_lo:[0,1] neg_hi:[0,1]
	v_div_fmas_f32 v5, v5, v46, v40
	v_pk_mul_f32 v[94:95], v[2:3], v[30:31]
	v_pk_fma_f32 v[38:39], v[2:3], v[30:31], v[38:39]
	v_div_fixup_f32 v40, v5, v42, 1.0
	v_pk_fma_f32 v[40:41], v[40:41], v[38:39], v[94:95] op_sel_hi:[0,1,1] neg_lo:[0,0,1] neg_hi:[0,0,1]
	v_cvt_pk_bf16_f32 v5, v40, v41
	v_or_b32_e32 v40, s44, v14
	s_or_b32 s44, s16, 10
	s_min_u32 s0, s44, 15
	s_add_i32 s0, s0, 1
	v_cvt_f32_ubyte0_e32 v42, s0
	v_div_scale_f32 v43, s[0:1], v42, v42, 1.0
	v_rcp_f32_e32 v46, v43
	v_mov_b32_e32 v41, v15
	v_lshlrev_b64 v[40:41], 9, v[40:41]
	v_lshl_add_u64 v[40:41], v[8:9], 0, v[40:41]
	global_store_dword v[40:41], v5, off nt
	v_fma_f32 v5, -v43, v46, 1.0
	v_fmac_f32_e32 v46, v5, v46
	v_div_scale_f32 v5, vcc, 1.0, v42, 1.0
	v_pk_add_f32 v[36:37], v[38:39], v[36:37] neg_lo:[0,1] neg_hi:[0,1]
	v_mul_f32_e32 v38, v5, v46
	v_fma_f32 v39, -v43, v38, v5
	v_fmac_f32_e32 v38, v39, v46
	v_fma_f32 v5, -v43, v38, v5
	v_div_fmas_f32 v5, v5, v46, v38
	v_pk_mul_f32 v[92:93], v[2:3], v[28:29]
	v_pk_fma_f32 v[36:37], v[2:3], v[28:29], v[36:37]
	v_div_fixup_f32 v38, v5, v42, 1.0
	v_pk_fma_f32 v[38:39], v[38:39], v[36:37], v[92:93] op_sel_hi:[0,1,1] neg_lo:[0,0,1] neg_hi:[0,0,1]
	v_cvt_pk_bf16_f32 v5, v38, v39
	v_or_b32_e32 v38, s44, v14
	s_or_b32 s44, s16, 11
	s_min_u32 s0, s44, 15
	s_add_i32 s0, s0, 1
	v_cvt_f32_ubyte0_e32 v40, s0
	v_div_scale_f32 v41, s[0:1], v40, v40, 1.0
	v_rcp_f32_e32 v42, v41
	v_mov_b32_e32 v39, v15
	v_lshlrev_b64 v[38:39], 9, v[38:39]
	v_lshl_add_u64 v[38:39], v[8:9], 0, v[38:39]
	global_store_dword v[38:39], v5, off nt
	v_fma_f32 v5, -v41, v42, 1.0
	v_fmac_f32_e32 v42, v5, v42
	v_div_scale_f32 v5, vcc, 1.0, v40, 1.0
	v_mul_f32_e32 v38, v5, v42
	v_fma_f32 v39, -v41, v38, v5
	v_fmac_f32_e32 v38, v39, v42
	v_fma_f32 v5, -v41, v38, v5
	v_pk_add_f32 v[36:37], v[36:37], v[60:61] neg_lo:[0,1] neg_hi:[0,1]
	v_div_fmas_f32 v5, v5, v42, v38
	v_pk_mul_f32 v[90:91], v[2:3], v[26:27]
	v_pk_fma_f32 v[36:37], v[2:3], v[26:27], v[36:37]
	v_div_fixup_f32 v38, v5, v40, 1.0
	v_pk_fma_f32 v[38:39], v[38:39], v[36:37], v[90:91] op_sel_hi:[0,1,1] neg_lo:[0,0,1] neg_hi:[0,0,1]
	v_cvt_pk_bf16_f32 v5, v38, v39
	v_or_b32_e32 v38, s44, v14
	s_or_b32 s44, s16, 12
	s_min_u32 s0, s44, 15
	s_add_i32 s0, s0, 1
	v_cvt_f32_ubyte0_e32 v40, s0
	v_div_scale_f32 v41, s[0:1], v40, v40, 1.0
	v_rcp_f32_e32 v42, v41
	v_mov_b32_e32 v39, v15
	v_lshlrev_b64 v[38:39], 9, v[38:39]
	v_lshl_add_u64 v[38:39], v[8:9], 0, v[38:39]
; __device__ __forceinline__ unsigned pk2(float lo, float hi) { f32x2 v = {lo, hi}; bf16x2_t b = __builtin_convertvector(v, bf16x2_t); return __builtin_bit_cast(unsigned, b); }
; __device__ __forceinline__ f32x2 ldx2(const bf16_t* p) { const unsigned w = *(const unsigned*)p; return (f32x2){__builtin_bit_cast(float, w << 16), __builtin_bit_cast(float, w & 0xffff0000u)}; }
; template <int W> __device__ __forceinline__ void pool_unit(const bf16_t* x, const LAS float* rs, f32x2 gn, bf16_t* Ag, size_t rb, int t0, int c, int g) {
;     ...
;         for (int i = 0; i < 16; ++i) hn_[i] = ldx2(x + (rb + t0 + bt * 16 + i) * 1024 + c) * rs[16 + bt * 16 + i] * gn;
; #pragma unroll
;         for (int i = 0; i < 16; ++i) { const int t = t0 + bt * 16 + i;
;             win += hn_[i]; const float inv = 1.f / (float)((t + 1) < W ? (t + 1) : W);
;             const f32x2 a = win * inv - hn_[i];
;             *(unsigned*)(Ag + ((size_t)g * MT + rb + t) * 256 + (c & 255)) = pk2(a.x, a.y);
;             win -= (i - W + 1 >= 0) ? hn_[(i - W + 1 >= 0) ? (i - W + 1) : 0] : ring[(i - W + 17) & 15]; }
; #pragma unroll
;         for (int i = 0; i < 16; ++i) ring[i] = hn_[i];
	global_store_dword v[38:39], v5, off nt
	v_fma_f32 v5, -v41, v42, 1.0
	v_fmac_f32_e32 v42, v5, v42
	v_div_scale_f32 v5, vcc, 1.0, v40, 1.0
	v_pk_add_f32 v[34:35], v[36:37], v[34:35] neg_lo:[0,1] neg_hi:[0,1]
	v_mul_f32_e32 v36, v5, v42
	v_fma_f32 v37, -v41, v36, v5
	v_fmac_f32_e32 v36, v37, v42
	v_fma_f32 v5, -v41, v36, v5
	v_div_fmas_f32 v5, v5, v42, v36
	v_pk_mul_f32 v[88:89], v[2:3], v[24:25]
	v_pk_fma_f32 v[34:35], v[2:3], v[24:25], v[34:35]
	v_div_fixup_f32 v36, v5, v40, 1.0
	v_pk_fma_f32 v[36:37], v[36:37], v[34:35], v[88:89] op_sel_hi:[0,1,1] neg_lo:[0,0,1] neg_hi:[0,0,1]
	v_cvt_pk_bf16_f32 v5, v36, v37
	v_or_b32_e32 v36, s44, v14
	s_or_b32 s44, s16, 13
	s_min_u32 s0, s44, 15
	s_add_i32 s0, s0, 1
	v_cvt_f32_ubyte0_e32 v38, s0
	v_div_scale_f32 v39, s[0:1], v38, v38, 1.0
	v_rcp_f32_e32 v40, v39
	v_mov_b32_e32 v37, v15
	v_lshlrev_b64 v[36:37], 9, v[36:37]
	v_lshl_add_u64 v[36:37], v[8:9], 0, v[36:37]
	global_store_dword v[36:37], v5, off nt
	v_fma_f32 v5, -v39, v40, 1.0
	v_fmac_f32_e32 v40, v5, v40
	v_div_scale_f32 v5, vcc, 1.0, v38, 1.0
	v_mul_f32_e32 v36, v5, v40
	v_fma_f32 v37, -v39, v36, v5
	v_fmac_f32_e32 v36, v37, v40
	v_fma_f32 v5, -v39, v36, v5
	v_pk_add_f32 v[34:35], v[34:35], v[58:59] neg_lo:[0,1] neg_hi:[0,1]
	v_div_fmas_f32 v5, v5, v40, v36
	v_pk_mul_f32 v[86:87], v[2:3], v[22:23]
	v_pk_fma_f32 v[34:35], v[2:3], v[22:23], v[34:35]
	v_div_fixup_f32 v36, v5, v38, 1.0
	v_pk_fma_f32 v[36:37], v[36:37], v[34:35], v[86:87] op_sel_hi:[0,1,1] neg_lo:[0,0,1] neg_hi:[0,0,1]
	v_cvt_pk_bf16_f32 v5, v36, v37
	v_or_b32_e32 v36, s44, v14
	s_or_b32 s44, s16, 14
	s_min_u32 s0, s44, 15
	s_add_i32 s0, s0, 1
	v_cvt_f32_ubyte0_e32 v38, s0
	v_div_scale_f32 v39, s[0:1], v38, v38, 1.0
	v_rcp_f32_e32 v40, v39
	v_mov_b32_e32 v37, v15
	v_lshlrev_b64 v[36:37], 9, v[36:37]
	v_lshl_add_u64 v[36:37], v[8:9], 0, v[36:37]
	global_store_dword v[36:37], v5, off nt
	v_fma_f32 v5, -v39, v40, 1.0
	v_fmac_f32_e32 v40, v5, v40
	v_div_scale_f32 v5, vcc, 1.0, v38, 1.0
	v_pk_add_f32 v[32:33], v[34:35], v[32:33] neg_lo:[0,1] neg_hi:[0,1]
	v_mul_f32_e32 v34, v5, v40
	v_fma_f32 v35, -v39, v34, v5
	v_fmac_f32_e32 v34, v35, v40
	v_fma_f32 v5, -v39, v34, v5
	v_div_fmas_f32 v5, v5, v40, v34
	v_pk_mul_f32 v[82:83], v[2:3], v[18:19]
	v_pk_fma_f32 v[32:33], v[2:3], v[18:19], v[32:33]
	v_div_fixup_f32 v34, v5, v38, 1.0
	v_pk_fma_f32 v[34:35], v[34:35], v[32:33], v[82:83] op_sel_hi:[0,1,1] neg_lo:[0,0,1] neg_hi:[0,0,1]
	s_waitcnt vmcnt(14)
	v_lshlrev_b32_e32 v20, 16, v125
	v_and_b32_e32 v21, 0xffff0000, v125
	v_cvt_pk_bf16_f32 v5, v34, v35
	v_or_b32_e32 v34, s44, v14
	v_mov_b32_e32 v35, v15
	v_pk_mul_f32 v[20:21], v[84:85], v[20:21] op_sel_hi:[0,1]
	v_lshlrev_b64 v[34:35], 9, v[34:35]
	v_pk_add_f32 v[32:33], v[32:33], v[76:77] neg_lo:[0,1] neg_hi:[0,1]
	v_pk_mul_f32 v[84:85], v[2:3], v[20:21]
	v_lshl_add_u64 v[34:35], v[8:9], 0, v[34:35]
	v_pk_fma_f32 v[32:33], v[2:3], v[20:21], v[32:33]
	global_store_dword v[34:35], v5, off nt
	v_pk_fma_f32 v[34:35], v[32:33], s[30:31], v[84:85] op_sel_hi:[1,0,1] neg_lo:[0,0,1] neg_hi:[0,0,1]
	s_mov_b32 s0, 0x9000
	v_cvt_pk_bf16_f32 v5, v34, v35
	v_or3_b32 v34, s16, 15, v14
	v_mov_b32_e32 v35, v15
	v_lshlrev_b64 v[34:35], 9, v[34:35]
	v_lshl_add_u64 v[34:35], v[8:9], 0, v[34:35]
	global_store_dword v[34:35], v5, off nt
	global_load_dword v5, v[80:81], off
	s_nop 0
	global_load_dword v42, v[80:81], off offset:2048
	v_add_co_u32_e32 v34, vcc, s92, v16
	v_pk_fma_f32 v[90:91], v[2:3], v[78:79], v[32:33] neg_lo:[1,0,0] neg_hi:[1,0,0]
	s_nop 0
	v_addc_co_u32_e32 v35, vcc, 0, v17, vcc
	global_load_dword v43, v[34:35], off offset:-4096
	v_add_co_u32_e32 v36, vcc, s0, v16
	s_mov_b32 s0, 0xb000
	s_nop 0
	v_addc_co_u32_e32 v37, vcc, 0, v17, vcc
	global_load_dword v46, v[36:37], off offset:2048
	global_load_dword v47, v[34:35], off
	global_load_dword v58, v[34:35], off offset:2048
	v_add_co_u32_e32 v34, vcc, s12, v16
	s_waitcnt vmcnt(5)
	v_lshlrev_b32_e32 v40, 16, v5
	v_addc_co_u32_e32 v35, vcc, 0, v17, vcc
	global_load_dword v59, v[34:35], off offset:-4096
	v_add_co_u32_e32 v36, vcc, s0, v16
	s_mov_b32 s0, 0xe000
	s_nop 0
	v_addc_co_u32_e32 v37, vcc, 0, v17, vcc
	global_load_dword v60, v[36:37], off offset:2048
	global_load_dword v110, v[34:35], off
	global_load_dword v112, v[34:35], off offset:2048
	v_add_co_u32_e32 v34, vcc, s0, v16
	s_mov_b32 s0, 0xd000
	s_nop 0
	v_addc_co_u32_e32 v35, vcc, 0, v17, vcc
	global_load_dword v113, v[34:35], off offset:-4096
	v_add_co_u32_e32 v36, vcc, s0, v16
	s_mov_b32 s0, 0xf000
	s_nop 0
	v_addc_co_u32_e32 v37, vcc, 0, v17, vcc
	global_load_dword v114, v[36:37], off offset:2048
	global_load_dword v115, v[34:35], off
	global_load_dword v116, v[34:35], off offset:2048
	v_add_co_u32_e32 v80, vcc, s63, v16
	v_and_b32_e32 v41, 0xffff0000, v5
	s_nop 0
	v_addc_co_u32_e32 v81, vcc, 0, v17, vcc
	global_load_dword v117, v[80:81], off offset:-4096
	v_add_co_u32_e32 v34, vcc, s0, v16
	s_mov_b32 s0, 0x12000
	s_nop 0
	v_addc_co_u32_e32 v35, vcc, 0, v17, vcc
	global_load_dword v118, v[34:35], off offset:2048
	ds_read_b128 v[32:35], v175 offset:128
	ds_read_b128 v[36:39], v175 offset:144
	ds_read_b128 v[82:85], v175 offset:160
	ds_read_b128 v[86:89], v175 offset:176
	s_waitcnt lgkmcnt(3)
	v_pk_mul_f32 v[78:79], v[32:33], v[40:41] op_sel_hi:[0,1]
	v_pk_mul_f32 v[92:93], v[2:3], v[78:79]
	v_pk_fma_f32 v[90:91], v[2:3], v[78:79], v[90:91]
	s_waitcnt vmcnt(14)
	v_lshlrev_b32_e32 v40, 16, v42
	v_and_b32_e32 v41, 0xffff0000, v42
	v_pk_fma_f32 v[92:93], v[90:91], s[30:31], v[92:93] op_sel_hi:[1,0,1] neg_lo:[0,0,1] neg_hi:[0,0,1]
	v_pk_mul_f32 v[76:77], v[32:33], v[40:41] op_sel:[1,0]
	v_cvt_pk_bf16_f32 v5, v92, v93
	v_or3_b32 v92, s16, 16, v14
	v_mov_b32_e32 v93, v15
	v_pk_fma_f32 v[74:75], v[2:3], v[74:75], v[90:91] neg_lo:[1,0,0] neg_hi:[1,0,0]
	v_pk_mul_f32 v[94:95], v[2:3], v[76:77]
	v_lshlrev_b64 v[92:93], 9, v[92:93]
	v_pk_fma_f32 v[74:75], v[2:3], v[76:77], v[74:75]
	s_waitcnt vmcnt(13)
; __device__ __forceinline__ unsigned pk2(float lo, float hi) { f32x2 v = {lo, hi}; bf16x2_t b = __builtin_convertvector(v, bf16x2_t); return __builtin_bit_cast(unsigned, b); }
; template <int W> __device__ __forceinline__ void pool_unit(const bf16_t* x, const LAS float* rs, f32x2 gn, bf16_t* Ag, size_t rb, int t0, int c, int g) {
;     ...
;         for (int i = 0; i < 16; ++i) { const int t = t0 + bt * 16 + i;
;             win += hn_[i]; const float inv = 1.f / (float)((t + 1) < W ? (t + 1) : W);
;             const f32x2 a = win * inv - hn_[i];
;             *(unsigned*)(Ag + ((size_t)g * MT + rb + t) * 256 + (c & 255)) = pk2(a.x, a.y);
;             win -= (i - W + 1 >= 0) ? hn_[(i - W + 1 >= 0) ? (i - W + 1) : 0] : ring[(i - W + 17) & 15]; }
	v_lshlrev_b32_e32 v32, 16, v43
	v_and_b32_e32 v33, 0xffff0000, v43
	v_lshl_add_u64 v[92:93], v[8:9], 0, v[92:93]
	v_pk_fma_f32 v[90:91], v[74:75], s[30:31], v[94:95] op_sel_hi:[1,0,1] neg_lo:[0,0,1] neg_hi:[0,0,1]
	v_pk_mul_f32 v[70:71], v[34:35], v[32:33] op_sel_hi:[0,1]
	global_store_dword v[92:93], v5, off nt
	v_cvt_pk_bf16_f32 v5, v90, v91
	v_or3_b32 v90, s16, 17, v14
	v_mov_b32_e32 v91, v15
	v_pk_fma_f32 v[72:73], v[2:3], v[72:73], v[74:75] neg_lo:[1,0,0] neg_hi:[1,0,0]
	v_pk_mul_f32 v[96:97], v[2:3], v[70:71]
	v_lshlrev_b64 v[90:91], 9, v[90:91]
	v_pk_fma_f32 v[72:73], v[2:3], v[70:71], v[72:73]
	s_waitcnt vmcnt(13)
	v_lshlrev_b32_e32 v32, 16, v46
	v_and_b32_e32 v33, 0xffff0000, v46
	v_mov_b32_e32 v34, v35
	v_lshl_add_u64 v[90:91], v[8:9], 0, v[90:91]
	v_pk_fma_f32 v[74:75], v[72:73], s[30:31], v[96:97] op_sel_hi:[1,0,1] neg_lo:[0,0,1] neg_hi:[0,0,1]
	v_pk_mul_f32 v[68:69], v[34:35], v[32:33] op_sel_hi:[0,1]
	global_store_dword v[90:91], v5, off nt
	v_cvt_pk_bf16_f32 v5, v74, v75
	v_or3_b32 v74, s16, 18, v14
	v_mov_b32_e32 v75, v15
	v_pk_fma_f32 v[56:57], v[2:3], v[56:57], v[72:73] neg_lo:[1,0,0] neg_hi:[1,0,0]
	v_pk_mul_f32 v[98:99], v[2:3], v[68:69]
	v_lshlrev_b64 v[74:75], 9, v[74:75]
	v_pk_fma_f32 v[56:57], v[2:3], v[68:69], v[56:57]
	s_waitcnt vmcnt(13)
	v_lshlrev_b32_e32 v32, 16, v47
	v_and_b32_e32 v33, 0xffff0000, v47
	v_lshl_add_u64 v[74:75], v[8:9], 0, v[74:75]
	v_pk_fma_f32 v[72:73], v[56:57], s[30:31], v[98:99] op_sel_hi:[1,0,1] neg_lo:[0,0,1] neg_hi:[0,0,1]
	s_waitcnt lgkmcnt(2)
	v_pk_mul_f32 v[66:67], v[36:37], v[32:33] op_sel_hi:[0,1]
	global_store_dword v[74:75], v5, off nt
	v_cvt_pk_bf16_f32 v5, v72, v73
	v_or3_b32 v72, s16, 19, v14
	v_mov_b32_e32 v73, v15
	v_pk_fma_f32 v[54:55], v[2:3], v[54:55], v[56:57] neg_lo:[1,0,0] neg_hi:[1,0,0]
	v_pk_mul_f32 v[100:101], v[2:3], v[66:67]
	v_lshlrev_b64 v[72:73], 9, v[72:73]
	v_pk_fma_f32 v[54:55], v[2:3], v[66:67], v[54:55]
	s_waitcnt vmcnt(13)
	v_lshlrev_b32_e32 v32, 16, v58
	v_and_b32_e32 v33, 0xffff0000, v58
	v_lshl_add_u64 v[72:73], v[8:9], 0, v[72:73]
	v_pk_fma_f32 v[56:57], v[54:55], s[30:31], v[100:101] op_sel_hi:[1,0,1] neg_lo:[0,0,1] neg_hi:[0,0,1]
	v_pk_mul_f32 v[64:65], v[36:37], v[32:33] op_sel:[1,0]
	global_store_dword v[72:73], v5, off nt
	v_cvt_pk_bf16_f32 v5, v56, v57
	v_or3_b32 v56, s16, 20, v14
	v_mov_b32_e32 v57, v15
	v_pk_fma_f32 v[52:53], v[2:3], v[52:53], v[54:55] neg_lo:[1,0,0] neg_hi:[1,0,0]
	v_pk_mul_f32 v[104:105], v[2:3], v[64:65]
	v_lshlrev_b64 v[56:57], 9, v[56:57]
	v_pk_fma_f32 v[52:53], v[2:3], v[64:65], v[52:53]
	s_waitcnt vmcnt(13)
	v_lshlrev_b32_e32 v32, 16, v59
	v_and_b32_e32 v33, 0xffff0000, v59
	v_lshl_add_u64 v[56:57], v[8:9], 0, v[56:57]
	v_pk_fma_f32 v[54:55], v[52:53], s[30:31], v[104:105] op_sel_hi:[1,0,1] neg_lo:[0,0,1] neg_hi:[0,0,1]
	v_pk_mul_f32 v[62:63], v[38:39], v[32:33] op_sel_hi:[0,1]
	global_store_dword v[56:57], v5, off nt
	v_cvt_pk_bf16_f32 v5, v54, v55
	v_or3_b32 v54, s16, 21, v14
	v_mov_b32_e32 v55, v15
	v_pk_fma_f32 v[50:51], v[2:3], v[50:51], v[52:53] neg_lo:[1,0,0] neg_hi:[1,0,0]
	v_pk_mul_f32 v[106:107], v[2:3], v[62:63]
	v_lshlrev_b64 v[54:55], 9, v[54:55]
	v_pk_fma_f32 v[50:51], v[2:3], v[62:63], v[50:51]
	s_waitcnt vmcnt(13)
	v_lshlrev_b32_e32 v32, 16, v60
	v_and_b32_e32 v33, 0xffff0000, v60
	v_mov_b32_e32 v34, v39
	v_lshl_add_u64 v[54:55], v[8:9], 0, v[54:55]
	v_pk_fma_f32 v[52:53], v[50:51], s[30:31], v[106:107] op_sel_hi:[1,0,1] neg_lo:[0,0,1] neg_hi:[0,0,1]
	v_pk_mul_f32 v[60:61], v[34:35], v[32:33] op_sel_hi:[0,1]
	global_store_dword v[54:55], v5, off nt
	v_cvt_pk_bf16_f32 v5, v52, v53
	v_or3_b32 v52, s16, 22, v14
	v_mov_b32_e32 v53, v15
	v_pk_fma_f32 v[48:49], v[2:3], v[48:49], v[50:51] neg_lo:[1,0,0] neg_hi:[1,0,0]
	v_pk_mul_f32 v[108:109], v[2:3], v[60:61]
	v_lshlrev_b64 v[52:53], 9, v[52:53]
	v_pk_fma_f32 v[48:49], v[2:3], v[60:61], v[48:49]
	s_waitcnt vmcnt(13)
	v_lshlrev_b32_e32 v32, 16, v110
	v_and_b32_e32 v33, 0xffff0000, v110
	v_lshl_add_u64 v[52:53], v[8:9], 0, v[52:53]
	v_pk_fma_f32 v[50:51], v[48:49], s[30:31], v[108:109] op_sel_hi:[1,0,1] neg_lo:[0,0,1] neg_hi:[0,0,1]
	s_waitcnt lgkmcnt(1)
	v_pk_mul_f32 v[58:59], v[82:83], v[32:33] op_sel_hi:[0,1]
	global_store_dword v[52:53], v5, off nt
	v_cvt_pk_bf16_f32 v5, v50, v51
	v_or3_b32 v50, s16, 23, v14
	v_mov_b32_e32 v51, v15
	v_pk_fma_f32 v[44:45], v[2:3], v[44:45], v[48:49] neg_lo:[1,0,0] neg_hi:[1,0,0]
	v_pk_mul_f32 v[110:111], v[2:3], v[58:59]
	v_lshlrev_b64 v[50:51], 9, v[50:51]
	v_pk_fma_f32 v[44:45], v[2:3], v[58:59], v[44:45]
	s_waitcnt vmcnt(13)
	v_lshlrev_b32_e32 v32, 16, v112
	v_and_b32_e32 v33, 0xffff0000, v112
	v_lshl_add_u64 v[50:51], v[8:9], 0, v[50:51]
	v_pk_fma_f32 v[48:49], v[44:45], s[30:31], v[110:111] op_sel_hi:[1,0,1] neg_lo:[0,0,1] neg_hi:[0,0,1]
	v_pk_mul_f32 v[46:47], v[82:83], v[32:33] op_sel:[1,0]
	global_store_dword v[50:51], v5, off nt
	v_cvt_pk_bf16_f32 v5, v48, v49
	v_or3_b32 v48, s16, 24, v14
	v_mov_b32_e32 v49, v15
	v_pk_fma_f32 v[30:31], v[2:3], v[30:31], v[44:45] neg_lo:[1,0,0] neg_hi:[1,0,0]
	v_pk_mul_f32 v[82:83], v[2:3], v[46:47]
	v_lshlrev_b64 v[48:49], 9, v[48:49]
	v_pk_fma_f32 v[30:31], v[2:3], v[46:47], v[30:31]
	s_waitcnt vmcnt(13)
	v_lshlrev_b32_e32 v32, 16, v113
	v_and_b32_e32 v33, 0xffff0000, v113
	v_lshl_add_u64 v[48:49], v[8:9], 0, v[48:49]
	v_pk_fma_f32 v[44:45], v[30:31], s[30:31], v[82:83] op_sel_hi:[1,0,1] neg_lo:[0,0,1] neg_hi:[0,0,1]
	v_pk_mul_f32 v[42:43], v[84:85], v[32:33] op_sel_hi:[0,1]
	global_store_dword v[48:49], v5, off nt
	v_cvt_pk_bf16_f32 v5, v44, v45
	v_or3_b32 v44, s16, 25, v14
	v_mov_b32_e32 v45, v15
	v_pk_fma_f32 v[28:29], v[2:3], v[28:29], v[30:31] neg_lo:[1,0,0] neg_hi:[1,0,0]
	v_pk_mul_f32 v[112:113], v[2:3], v[42:43]
	v_lshlrev_b64 v[44:45], 9, v[44:45]
	v_pk_fma_f32 v[28:29], v[2:3], v[42:43], v[28:29]
	s_waitcnt vmcnt(13)
; __device__ __forceinline__ unsigned pk2(float lo, float hi) { f32x2 v = {lo, hi}; bf16x2_t b = __builtin_convertvector(v, bf16x2_t); return __builtin_bit_cast(unsigned, b); }
; __device__ __forceinline__ f32x2 ldx2(const bf16_t* p) { const unsigned w = *(const unsigned*)p; return (f32x2){__builtin_bit_cast(float, w << 16), __builtin_bit_cast(float, w & 0xffff0000u)}; }
; template <int W> __device__ __forceinline__ void pool_unit(const bf16_t* x, const LAS float* rs, f32x2 gn, bf16_t* Ag, size_t rb, int t0, int c, int g) {
;     ...
;         for (int i = 0; i < 16; ++i) hn_[i] = ldx2(x + (rb + t0 + bt * 16 + i) * 1024 + c) * rs[16 + bt * 16 + i] * gn;
; #pragma unroll
;         for (int i = 0; i < 16; ++i) { const int t = t0 + bt * 16 + i;
;             win += hn_[i]; const float inv = 1.f / (float)((t + 1) < W ? (t + 1) : W);
;             const f32x2 a = win * inv - hn_[i];
;             *(unsigned*)(Ag + ((size_t)g * MT + rb + t) * 256 + (c & 255)) = pk2(a.x, a.y);
;             win -= (i - W + 1 >= 0) ? hn_[(i - W + 1 >= 0) ? (i - W + 1) : 0] : ring[(i - W + 17) & 15]; }
; #pragma unroll
;         for (int i = 0; i < 16; ++i) ring[i] = hn_[i];
	v_lshlrev_b32_e32 v32, 16, v114
	v_and_b32_e32 v33, 0xffff0000, v114
	v_mov_b32_e32 v34, v85
	v_lshl_add_u64 v[44:45], v[8:9], 0, v[44:45]
	v_pk_fma_f32 v[30:31], v[28:29], s[30:31], v[112:113] op_sel_hi:[1,0,1] neg_lo:[0,0,1] neg_hi:[0,0,1]
	v_pk_mul_f32 v[40:41], v[34:35], v[32:33] op_sel_hi:[0,1]
	global_store_dword v[44:45], v5, off nt
	v_cvt_pk_bf16_f32 v5, v30, v31
	v_or3_b32 v30, s16, 26, v14
	v_mov_b32_e32 v31, v15
	v_pk_fma_f32 v[26:27], v[2:3], v[26:27], v[28:29] neg_lo:[1,0,0] neg_hi:[1,0,0]
	v_pk_mul_f32 v[84:85], v[2:3], v[40:41]
	v_lshlrev_b64 v[30:31], 9, v[30:31]
	v_pk_fma_f32 v[26:27], v[2:3], v[40:41], v[26:27]
	s_waitcnt vmcnt(13)
	v_lshlrev_b32_e32 v32, 16, v115
	v_and_b32_e32 v33, 0xffff0000, v115
	v_lshl_add_u64 v[30:31], v[8:9], 0, v[30:31]
	v_pk_fma_f32 v[28:29], v[26:27], s[30:31], v[84:85] op_sel_hi:[1,0,1] neg_lo:[0,0,1] neg_hi:[0,0,1]
	s_waitcnt lgkmcnt(0)
	v_pk_mul_f32 v[38:39], v[86:87], v[32:33] op_sel_hi:[0,1]
	global_store_dword v[30:31], v5, off nt
	v_cvt_pk_bf16_f32 v5, v28, v29
	v_or3_b32 v28, s16, 27, v14
	v_mov_b32_e32 v29, v15
	v_pk_fma_f32 v[24:25], v[2:3], v[24:25], v[26:27] neg_lo:[1,0,0] neg_hi:[1,0,0]
	v_pk_mul_f32 v[114:115], v[2:3], v[38:39]
	v_lshlrev_b64 v[28:29], 9, v[28:29]
	v_pk_fma_f32 v[24:25], v[2:3], v[38:39], v[24:25]
	s_waitcnt vmcnt(13)
	v_lshlrev_b32_e32 v32, 16, v116
	v_and_b32_e32 v33, 0xffff0000, v116
	v_lshl_add_u64 v[28:29], v[8:9], 0, v[28:29]
	v_pk_fma_f32 v[26:27], v[24:25], s[30:31], v[114:115] op_sel_hi:[1,0,1] neg_lo:[0,0,1] neg_hi:[0,0,1]
	v_pk_mul_f32 v[36:37], v[86:87], v[32:33] op_sel:[1,0]
	global_store_dword v[28:29], v5, off nt
	v_cvt_pk_bf16_f32 v5, v26, v27
	v_or3_b32 v26, s16, 28, v14
	v_mov_b32_e32 v27, v15
	v_pk_fma_f32 v[22:23], v[2:3], v[22:23], v[24:25] neg_lo:[1,0,0] neg_hi:[1,0,0]
	v_pk_mul_f32 v[86:87], v[2:3], v[36:37]
	v_lshlrev_b64 v[26:27], 9, v[26:27]
	v_pk_fma_f32 v[22:23], v[2:3], v[36:37], v[22:23]
	s_waitcnt vmcnt(13)
	v_lshlrev_b32_e32 v32, 16, v117
	v_and_b32_e32 v33, 0xffff0000, v117
	v_lshl_add_u64 v[26:27], v[8:9], 0, v[26:27]
	v_pk_fma_f32 v[24:25], v[22:23], s[30:31], v[86:87] op_sel_hi:[1,0,1] neg_lo:[0,0,1] neg_hi:[0,0,1]
	v_pk_mul_f32 v[34:35], v[88:89], v[32:33] op_sel_hi:[0,1]
	global_store_dword v[26:27], v5, off nt
	v_cvt_pk_bf16_f32 v5, v24, v25
	v_or3_b32 v24, s16, 29, v14
	v_mov_b32_e32 v25, v15
	v_pk_fma_f32 v[18:19], v[2:3], v[18:19], v[22:23] neg_lo:[1,0,0] neg_hi:[1,0,0]
	v_pk_mul_f32 v[116:117], v[2:3], v[34:35]
	v_lshlrev_b64 v[24:25], 9, v[24:25]
	v_pk_fma_f32 v[18:19], v[2:3], v[34:35], v[18:19]
	s_waitcnt vmcnt(13)
	v_lshlrev_b32_e32 v32, 16, v118
	v_and_b32_e32 v33, 0xffff0000, v118
	v_mov_b32_e32 v88, v89
	v_lshl_add_u64 v[24:25], v[8:9], 0, v[24:25]
	v_pk_fma_f32 v[22:23], v[18:19], s[30:31], v[116:117] op_sel_hi:[1,0,1] neg_lo:[0,0,1] neg_hi:[0,0,1]
	v_pk_mul_f32 v[32:33], v[88:89], v[32:33] op_sel_hi:[0,1]
	global_store_dword v[24:25], v5, off nt
	v_cvt_pk_bf16_f32 v5, v22, v23
	v_or3_b32 v22, s16, 30, v14
	v_mov_b32_e32 v23, v15
	v_pk_fma_f32 v[18:19], v[2:3], v[20:21], v[18:19] neg_lo:[1,0,0] neg_hi:[1,0,0]
	v_pk_mul_f32 v[88:89], v[2:3], v[32:33]
	v_lshlrev_b64 v[22:23], 9, v[22:23]
	v_pk_fma_f32 v[18:19], v[2:3], v[32:33], v[18:19]
	v_lshl_add_u64 v[22:23], v[8:9], 0, v[22:23]
	v_pk_fma_f32 v[20:21], v[18:19], s[30:31], v[88:89] op_sel_hi:[1,0,1] neg_lo:[0,0,1] neg_hi:[0,0,1]
	global_store_dword v[22:23], v5, off nt
	v_cvt_pk_bf16_f32 v5, v20, v21
	v_or3_b32 v20, s16, 31, v14
	v_mov_b32_e32 v21, v15
	v_lshlrev_b64 v[20:21], 9, v[20:21]
	v_lshl_add_u64 v[20:21], v[8:9], 0, v[20:21]
	global_store_dword v[20:21], v5, off nt
	global_load_dword v5, v[80:81], off
	s_nop 0
	global_load_dword v28, v[80:81], off offset:2048
	v_add_co_u32_e32 v20, vcc, s0, v16
	s_mov_b32 s0, 0x11000
	s_nop 0
	v_addc_co_u32_e32 v21, vcc, 0, v17, vcc
	global_load_dword v29, v[20:21], off offset:-4096
	v_add_co_u32_e32 v22, vcc, s0, v16
	s_mov_b32 s0, 0x14000
	s_nop 0
	v_addc_co_u32_e32 v23, vcc, 0, v17, vcc
	global_load_dword v30, v[22:23], off offset:2048
	global_load_dword v31, v[20:21], off
	global_load_dword v44, v[20:21], off offset:2048
	v_add_co_u32_e32 v20, vcc, s0, v16
	s_mov_b32 s0, 0x13000
	s_nop 0
	v_addc_co_u32_e32 v21, vcc, 0, v17, vcc
	global_load_dword v45, v[20:21], off offset:-4096
	v_add_co_u32_e32 v22, vcc, s0, v16
	s_mov_b32 s0, 0x16000
	s_nop 0
	v_addc_co_u32_e32 v23, vcc, 0, v17, vcc
	global_load_dword v48, v[22:23], off offset:2048
	global_load_dword v110, v[20:21], off
	global_load_dword v112, v[20:21], off offset:2048
	v_add_co_u32_e32 v20, vcc, s0, v16
	s_mov_b32 s0, 0x15000
	s_nop 0
	v_addc_co_u32_e32 v21, vcc, 0, v17, vcc
	global_load_dword v113, v[20:21], off offset:-4096
	v_add_co_u32_e32 v22, vcc, s0, v16
	s_mov_b32 s0, 0x18000
	s_nop 0
	v_addc_co_u32_e32 v23, vcc, 0, v17, vcc
	global_load_dword v114, v[22:23], off offset:2048
	global_load_dword v115, v[20:21], off
	global_load_dword v116, v[20:21], off offset:2048
	v_add_co_u32_e32 v80, vcc, s0, v16
	s_mov_b32 s0, 0x17000
	s_nop 0
	v_addc_co_u32_e32 v81, vcc, 0, v17, vcc
	global_load_dword v117, v[80:81], off offset:-4096
	v_add_co_u32_e32 v20, vcc, s0, v16
	v_pk_fma_f32 v[90:91], v[2:3], v[78:79], v[18:19] neg_lo:[1,0,0] neg_hi:[1,0,0]
	s_nop 0
	v_addc_co_u32_e32 v21, vcc, 0, v17, vcc
	global_load_dword v118, v[20:21], off offset:2048
	ds_read_b128 v[18:21], v175 offset:192
	ds_read_b128 v[22:25], v175 offset:208
	ds_read_b128 v[82:85], v175 offset:224
	ds_read_b128 v[86:89], v175 offset:240
	s_mov_b32 s0, 0x1a000
	s_waitcnt vmcnt(15)
	v_lshlrev_b32_e32 v26, 16, v5
	v_and_b32_e32 v27, 0xffff0000, v5
	s_waitcnt lgkmcnt(3)
; __device__ __forceinline__ unsigned pk2(float lo, float hi) { f32x2 v = {lo, hi}; bf16x2_t b = __builtin_convertvector(v, bf16x2_t); return __builtin_bit_cast(unsigned, b); }
; template <int W> __device__ __forceinline__ void pool_unit(const bf16_t* x, const LAS float* rs, f32x2 gn, bf16_t* Ag, size_t rb, int t0, int c, int g) {
;     ...
;         for (int i = 0; i < 16; ++i) { const int t = t0 + bt * 16 + i;
;             win += hn_[i]; const float inv = 1.f / (float)((t + 1) < W ? (t + 1) : W);
;             const f32x2 a = win * inv - hn_[i];
;             *(unsigned*)(Ag + ((size_t)g * MT + rb + t) * 256 + (c & 255)) = pk2(a.x, a.y);
;             win -= (i - W + 1 >= 0) ? hn_[(i - W + 1 >= 0) ? (i - W + 1) : 0] : ring[(i - W + 17) & 15]; }
	v_pk_mul_f32 v[78:79], v[18:19], v[26:27] op_sel_hi:[0,1]
	v_pk_mul_f32 v[92:93], v[2:3], v[78:79]
	v_pk_fma_f32 v[90:91], v[2:3], v[78:79], v[90:91]
	s_waitcnt vmcnt(14)
	v_lshlrev_b32_e32 v26, 16, v28
	v_and_b32_e32 v27, 0xffff0000, v28
	v_pk_fma_f32 v[92:93], v[90:91], s[30:31], v[92:93] op_sel_hi:[1,0,1] neg_lo:[0,0,1] neg_hi:[0,0,1]
	v_pk_mul_f32 v[74:75], v[18:19], v[26:27] op_sel:[1,0]
	v_cvt_pk_bf16_f32 v5, v92, v93
	v_or3_b32 v92, s16, 32, v14
	v_mov_b32_e32 v93, v15
	v_pk_fma_f32 v[76:77], v[2:3], v[76:77], v[90:91] neg_lo:[1,0,0] neg_hi:[1,0,0]
	v_pk_mul_f32 v[94:95], v[2:3], v[74:75]
	v_lshlrev_b64 v[92:93], 9, v[92:93]
	v_pk_fma_f32 v[76:77], v[2:3], v[74:75], v[76:77]
	s_waitcnt vmcnt(13)
	v_lshlrev_b32_e32 v18, 16, v29
	v_and_b32_e32 v19, 0xffff0000, v29
	v_lshl_add_u64 v[92:93], v[8:9], 0, v[92:93]
	v_pk_fma_f32 v[90:91], v[76:77], s[30:31], v[94:95] op_sel_hi:[1,0,1] neg_lo:[0,0,1] neg_hi:[0,0,1]
	v_pk_mul_f32 v[72:73], v[20:21], v[18:19] op_sel_hi:[0,1]
	global_store_dword v[92:93], v5, off nt
	v_cvt_pk_bf16_f32 v5, v90, v91
	v_or3_b32 v90, s16, 33, v14
	v_mov_b32_e32 v91, v15
	v_pk_fma_f32 v[70:71], v[2:3], v[70:71], v[76:77] neg_lo:[1,0,0] neg_hi:[1,0,0]
	v_pk_mul_f32 v[96:97], v[2:3], v[72:73]
	v_lshlrev_b64 v[90:91], 9, v[90:91]
	v_pk_fma_f32 v[70:71], v[2:3], v[72:73], v[70:71]
	s_waitcnt vmcnt(13)
	v_lshlrev_b32_e32 v18, 16, v30
	v_and_b32_e32 v19, 0xffff0000, v30
	v_mov_b32_e32 v20, v21
	v_lshl_add_u64 v[90:91], v[8:9], 0, v[90:91]
	v_pk_fma_f32 v[76:77], v[70:71], s[30:31], v[96:97] op_sel_hi:[1,0,1] neg_lo:[0,0,1] neg_hi:[0,0,1]
	v_pk_mul_f32 v[56:57], v[20:21], v[18:19] op_sel_hi:[0,1]
	global_store_dword v[90:91], v5, off nt
	v_cvt_pk_bf16_f32 v5, v76, v77
	v_or3_b32 v76, s16, 34, v14
	v_mov_b32_e32 v77, v15
	v_pk_fma_f32 v[68:69], v[2:3], v[68:69], v[70:71] neg_lo:[1,0,0] neg_hi:[1,0,0]
	v_pk_mul_f32 v[98:99], v[2:3], v[56:57]
	v_lshlrev_b64 v[76:77], 9, v[76:77]
	v_pk_fma_f32 v[68:69], v[2:3], v[56:57], v[68:69]
	s_waitcnt vmcnt(13)
	v_lshlrev_b32_e32 v18, 16, v31
	v_and_b32_e32 v19, 0xffff0000, v31
	v_lshl_add_u64 v[76:77], v[8:9], 0, v[76:77]
	v_pk_fma_f32 v[70:71], v[68:69], s[30:31], v[98:99] op_sel_hi:[1,0,1] neg_lo:[0,0,1] neg_hi:[0,0,1]
	s_waitcnt lgkmcnt(2)
	v_pk_mul_f32 v[54:55], v[22:23], v[18:19] op_sel_hi:[0,1]
	global_store_dword v[76:77], v5, off nt
	v_cvt_pk_bf16_f32 v5, v70, v71
	v_or3_b32 v70, s16, 35, v14
	v_mov_b32_e32 v71, v15
	v_pk_fma_f32 v[66:67], v[2:3], v[66:67], v[68:69] neg_lo:[1,0,0] neg_hi:[1,0,0]
	v_pk_mul_f32 v[100:101], v[2:3], v[54:55]
	v_lshlrev_b64 v[70:71], 9, v[70:71]
	v_pk_fma_f32 v[66:67], v[2:3], v[54:55], v[66:67]
	s_waitcnt vmcnt(13)
	v_lshlrev_b32_e32 v18, 16, v44
	v_and_b32_e32 v19, 0xffff0000, v44
	v_lshl_add_u64 v[70:71], v[8:9], 0, v[70:71]
	v_pk_fma_f32 v[68:69], v[66:67], s[30:31], v[100:101] op_sel_hi:[1,0,1] neg_lo:[0,0,1] neg_hi:[0,0,1]
	v_pk_mul_f32 v[52:53], v[22:23], v[18:19] op_sel:[1,0]
	global_store_dword v[70:71], v5, off nt
	v_cvt_pk_bf16_f32 v5, v68, v69
	v_or3_b32 v68, s16, 36, v14
	v_mov_b32_e32 v69, v15
	v_pk_fma_f32 v[64:65], v[2:3], v[64:65], v[66:67] neg_lo:[1,0,0] neg_hi:[1,0,0]
	v_pk_mul_f32 v[104:105], v[2:3], v[52:53]
	v_lshlrev_b64 v[68:69], 9, v[68:69]
	v_pk_fma_f32 v[64:65], v[2:3], v[52:53], v[64:65]
	s_waitcnt vmcnt(13)
	v_lshlrev_b32_e32 v18, 16, v45
	v_and_b32_e32 v19, 0xffff0000, v45
	v_lshl_add_u64 v[68:69], v[8:9], 0, v[68:69]
	v_pk_fma_f32 v[66:67], v[64:65], s[30:31], v[104:105] op_sel_hi:[1,0,1] neg_lo:[0,0,1] neg_hi:[0,0,1]
	v_pk_mul_f32 v[50:51], v[24:25], v[18:19] op_sel_hi:[0,1]
	global_store_dword v[68:69], v5, off nt
	v_cvt_pk_bf16_f32 v5, v66, v67
	v_or3_b32 v66, s16, 37, v14
	v_mov_b32_e32 v67, v15
	v_pk_fma_f32 v[62:63], v[2:3], v[62:63], v[64:65] neg_lo:[1,0,0] neg_hi:[1,0,0]
	v_pk_mul_f32 v[106:107], v[2:3], v[50:51]
	v_lshlrev_b64 v[66:67], 9, v[66:67]
	v_pk_fma_f32 v[62:63], v[2:3], v[50:51], v[62:63]
	s_waitcnt vmcnt(13)
	v_lshlrev_b32_e32 v18, 16, v48
	v_and_b32_e32 v19, 0xffff0000, v48
	v_mov_b32_e32 v20, v25
	v_lshl_add_u64 v[66:67], v[8:9], 0, v[66:67]
	v_pk_fma_f32 v[64:65], v[62:63], s[30:31], v[106:107] op_sel_hi:[1,0,1] neg_lo:[0,0,1] neg_hi:[0,0,1]
	v_pk_mul_f32 v[48:49], v[20:21], v[18:19] op_sel_hi:[0,1]
	global_store_dword v[66:67], v5, off nt
	v_cvt_pk_bf16_f32 v5, v64, v65
	v_or3_b32 v64, s16, 38, v14
	v_mov_b32_e32 v65, v15
	v_pk_fma_f32 v[60:61], v[2:3], v[60:61], v[62:63] neg_lo:[1,0,0] neg_hi:[1,0,0]
	v_pk_mul_f32 v[108:109], v[2:3], v[48:49]
	v_lshlrev_b64 v[64:65], 9, v[64:65]
	v_pk_fma_f32 v[60:61], v[2:3], v[48:49], v[60:61]
	s_waitcnt vmcnt(13)
	v_lshlrev_b32_e32 v18, 16, v110
	v_and_b32_e32 v19, 0xffff0000, v110
	v_lshl_add_u64 v[64:65], v[8:9], 0, v[64:65]
	v_pk_fma_f32 v[62:63], v[60:61], s[30:31], v[108:109] op_sel_hi:[1,0,1] neg_lo:[0,0,1] neg_hi:[0,0,1]
	s_waitcnt lgkmcnt(1)
	v_pk_mul_f32 v[44:45], v[82:83], v[18:19] op_sel_hi:[0,1]
	global_store_dword v[64:65], v5, off nt
	v_cvt_pk_bf16_f32 v5, v62, v63
	v_or3_b32 v62, s16, 39, v14
	v_mov_b32_e32 v63, v15
	v_pk_fma_f32 v[58:59], v[2:3], v[58:59], v[60:61] neg_lo:[1,0,0] neg_hi:[1,0,0]
	v_pk_mul_f32 v[110:111], v[2:3], v[44:45]
	v_lshlrev_b64 v[62:63], 9, v[62:63]
	v_pk_fma_f32 v[58:59], v[2:3], v[44:45], v[58:59]
	s_waitcnt vmcnt(13)
	v_lshlrev_b32_e32 v18, 16, v112
	v_and_b32_e32 v19, 0xffff0000, v112
	v_lshl_add_u64 v[62:63], v[8:9], 0, v[62:63]
	v_pk_fma_f32 v[60:61], v[58:59], s[30:31], v[110:111] op_sel_hi:[1,0,1] neg_lo:[0,0,1] neg_hi:[0,0,1]
	v_pk_mul_f32 v[30:31], v[82:83], v[18:19] op_sel:[1,0]
	global_store_dword v[62:63], v5, off nt
	v_cvt_pk_bf16_f32 v5, v60, v61
	v_or3_b32 v60, s16, 40, v14
	v_mov_b32_e32 v61, v15
	v_pk_fma_f32 v[46:47], v[2:3], v[46:47], v[58:59] neg_lo:[1,0,0] neg_hi:[1,0,0]
	v_pk_mul_f32 v[82:83], v[2:3], v[30:31]
	v_lshlrev_b64 v[60:61], 9, v[60:61]
	v_pk_fma_f32 v[46:47], v[2:3], v[30:31], v[46:47]
	s_waitcnt vmcnt(13)
; __device__ __forceinline__ unsigned pk2(float lo, float hi) { f32x2 v = {lo, hi}; bf16x2_t b = __builtin_convertvector(v, bf16x2_t); return __builtin_bit_cast(unsigned, b); }
; __device__ __forceinline__ f32x2 ldx2(const bf16_t* p) { const unsigned w = *(const unsigned*)p; return (f32x2){__builtin_bit_cast(float, w << 16), __builtin_bit_cast(float, w & 0xffff0000u)}; }
; template <int W> __device__ __forceinline__ void pool_unit(const bf16_t* x, const LAS float* rs, f32x2 gn, bf16_t* Ag, size_t rb, int t0, int c, int g) {
;     ...
;         for (int i = 0; i < 16; ++i) hn_[i] = ldx2(x + (rb + t0 + bt * 16 + i) * 1024 + c) * rs[16 + bt * 16 + i] * gn;
; #pragma unroll
;         for (int i = 0; i < 16; ++i) { const int t = t0 + bt * 16 + i;
;             win += hn_[i]; const float inv = 1.f / (float)((t + 1) < W ? (t + 1) : W);
;             const f32x2 a = win * inv - hn_[i];
;             *(unsigned*)(Ag + ((size_t)g * MT + rb + t) * 256 + (c & 255)) = pk2(a.x, a.y);
;             win -= (i - W + 1 >= 0) ? hn_[(i - W + 1 >= 0) ? (i - W + 1) : 0] : ring[(i - W + 17) & 15]; }
; #pragma unroll
;         for (int i = 0; i < 16; ++i) ring[i] = hn_[i];
	v_lshlrev_b32_e32 v18, 16, v113
	v_and_b32_e32 v19, 0xffff0000, v113
	v_lshl_add_u64 v[60:61], v[8:9], 0, v[60:61]
	v_pk_fma_f32 v[58:59], v[46:47], s[30:31], v[82:83] op_sel_hi:[1,0,1] neg_lo:[0,0,1] neg_hi:[0,0,1]
	v_pk_mul_f32 v[28:29], v[84:85], v[18:19] op_sel_hi:[0,1]
	global_store_dword v[60:61], v5, off nt
	v_cvt_pk_bf16_f32 v5, v58, v59
	v_or3_b32 v58, s16, 41, v14
	v_mov_b32_e32 v59, v15
	v_pk_fma_f32 v[42:43], v[2:3], v[42:43], v[46:47] neg_lo:[1,0,0] neg_hi:[1,0,0]
	v_pk_mul_f32 v[112:113], v[2:3], v[28:29]
	v_lshlrev_b64 v[58:59], 9, v[58:59]
	v_pk_fma_f32 v[42:43], v[2:3], v[28:29], v[42:43]
	s_waitcnt vmcnt(13)
	v_lshlrev_b32_e32 v18, 16, v114
	v_and_b32_e32 v19, 0xffff0000, v114
	v_mov_b32_e32 v20, v85
	v_lshl_add_u64 v[58:59], v[8:9], 0, v[58:59]
	v_pk_fma_f32 v[46:47], v[42:43], s[30:31], v[112:113] op_sel_hi:[1,0,1] neg_lo:[0,0,1] neg_hi:[0,0,1]
	v_pk_mul_f32 v[26:27], v[20:21], v[18:19] op_sel_hi:[0,1]
	global_store_dword v[58:59], v5, off nt
	v_cvt_pk_bf16_f32 v5, v46, v47
	v_or3_b32 v46, s16, 42, v14
	v_mov_b32_e32 v47, v15
	v_pk_fma_f32 v[40:41], v[2:3], v[40:41], v[42:43] neg_lo:[1,0,0] neg_hi:[1,0,0]
	v_pk_mul_f32 v[84:85], v[2:3], v[26:27]
	v_lshlrev_b64 v[46:47], 9, v[46:47]
	v_pk_fma_f32 v[40:41], v[2:3], v[26:27], v[40:41]
	s_waitcnt vmcnt(13)
	v_lshlrev_b32_e32 v18, 16, v115
	v_and_b32_e32 v19, 0xffff0000, v115
	v_lshl_add_u64 v[46:47], v[8:9], 0, v[46:47]
	v_pk_fma_f32 v[42:43], v[40:41], s[30:31], v[84:85] op_sel_hi:[1,0,1] neg_lo:[0,0,1] neg_hi:[0,0,1]
	s_waitcnt lgkmcnt(0)
	v_pk_mul_f32 v[24:25], v[86:87], v[18:19] op_sel_hi:[0,1]
	global_store_dword v[46:47], v5, off nt
	v_cvt_pk_bf16_f32 v5, v42, v43
	v_or3_b32 v42, s16, 43, v14
	v_mov_b32_e32 v43, v15
	v_pk_fma_f32 v[38:39], v[2:3], v[38:39], v[40:41] neg_lo:[1,0,0] neg_hi:[1,0,0]
	v_pk_mul_f32 v[114:115], v[2:3], v[24:25]
	v_lshlrev_b64 v[42:43], 9, v[42:43]
	v_pk_fma_f32 v[38:39], v[2:3], v[24:25], v[38:39]
	s_waitcnt vmcnt(13)
	v_lshlrev_b32_e32 v18, 16, v116
	v_and_b32_e32 v19, 0xffff0000, v116
	v_lshl_add_u64 v[42:43], v[8:9], 0, v[42:43]
	v_pk_fma_f32 v[40:41], v[38:39], s[30:31], v[114:115] op_sel_hi:[1,0,1] neg_lo:[0,0,1] neg_hi:[0,0,1]
	v_pk_mul_f32 v[22:23], v[86:87], v[18:19] op_sel:[1,0]
	global_store_dword v[42:43], v5, off nt
	v_cvt_pk_bf16_f32 v5, v40, v41
	v_or3_b32 v40, s16, 44, v14
	v_mov_b32_e32 v41, v15
	v_pk_fma_f32 v[36:37], v[2:3], v[36:37], v[38:39] neg_lo:[1,0,0] neg_hi:[1,0,0]
	v_pk_mul_f32 v[86:87], v[2:3], v[22:23]
	v_lshlrev_b64 v[40:41], 9, v[40:41]
	v_pk_fma_f32 v[36:37], v[2:3], v[22:23], v[36:37]
	s_waitcnt vmcnt(13)
	v_lshlrev_b32_e32 v18, 16, v117
	v_and_b32_e32 v19, 0xffff0000, v117
	v_lshl_add_u64 v[40:41], v[8:9], 0, v[40:41]
	v_pk_fma_f32 v[38:39], v[36:37], s[30:31], v[86:87] op_sel_hi:[1,0,1] neg_lo:[0,0,1] neg_hi:[0,0,1]
	v_pk_mul_f32 v[20:21], v[88:89], v[18:19] op_sel_hi:[0,1]
	global_store_dword v[40:41], v5, off nt
	v_cvt_pk_bf16_f32 v5, v38, v39
	v_or3_b32 v38, s16, 45, v14
	v_mov_b32_e32 v39, v15
	v_pk_fma_f32 v[34:35], v[2:3], v[34:35], v[36:37] neg_lo:[1,0,0] neg_hi:[1,0,0]
	v_pk_mul_f32 v[116:117], v[2:3], v[20:21]
	v_lshlrev_b64 v[38:39], 9, v[38:39]
	v_pk_fma_f32 v[34:35], v[2:3], v[20:21], v[34:35]
	s_waitcnt vmcnt(13)
	v_lshlrev_b32_e32 v18, 16, v118
	v_and_b32_e32 v19, 0xffff0000, v118
	v_mov_b32_e32 v88, v89
	v_lshl_add_u64 v[38:39], v[8:9], 0, v[38:39]
	v_pk_fma_f32 v[36:37], v[34:35], s[30:31], v[116:117] op_sel_hi:[1,0,1] neg_lo:[0,0,1] neg_hi:[0,0,1]
	v_pk_mul_f32 v[18:19], v[88:89], v[18:19] op_sel_hi:[0,1]
	global_store_dword v[38:39], v5, off nt
	v_cvt_pk_bf16_f32 v5, v36, v37
	v_or3_b32 v36, s16, 46, v14
	v_mov_b32_e32 v37, v15
	v_pk_fma_f32 v[32:33], v[2:3], v[32:33], v[34:35] neg_lo:[1,0,0] neg_hi:[1,0,0]
	v_pk_mul_f32 v[88:89], v[2:3], v[18:19]
	v_lshlrev_b64 v[36:37], 9, v[36:37]
	v_pk_fma_f32 v[32:33], v[2:3], v[18:19], v[32:33]
	v_lshl_add_u64 v[36:37], v[8:9], 0, v[36:37]
	v_pk_fma_f32 v[34:35], v[32:33], s[30:31], v[88:89] op_sel_hi:[1,0,1] neg_lo:[0,0,1] neg_hi:[0,0,1]
	global_store_dword v[36:37], v5, off nt
	v_cvt_pk_bf16_f32 v5, v34, v35
	v_or3_b32 v34, s16, 47, v14
	v_mov_b32_e32 v35, v15
	v_lshlrev_b64 v[34:35], 9, v[34:35]
	v_lshl_add_u64 v[34:35], v[8:9], 0, v[34:35]
	global_store_dword v[34:35], v5, off nt
	global_load_dword v5, v[80:81], off
	s_nop 0
	global_load_dword v65, v[80:81], off offset:2048
	v_add_co_u32_e32 v34, vcc, s0, v16
	s_mov_b32 s0, 0x19000
	s_nop 0
	v_addc_co_u32_e32 v35, vcc, 0, v17, vcc
	global_load_dword v67, v[34:35], off offset:-4096
	v_add_co_u32_e32 v36, vcc, s0, v16
	s_mov_b32 s0, 0x1c000
	s_nop 0
	v_addc_co_u32_e32 v37, vcc, 0, v17, vcc
	global_load_dword v71, v[36:37], off offset:2048
	global_load_dword v77, v[34:35], off
	global_load_dword v81, v[34:35], off offset:2048
	v_add_co_u32_e32 v34, vcc, s0, v16
	s_mov_b32 s0, 0x1b000
	s_nop 0
	v_addc_co_u32_e32 v35, vcc, 0, v17, vcc
	global_load_dword v83, v[34:35], off offset:-4096
	v_add_co_u32_e32 v36, vcc, s0, v16
	s_mov_b32 s0, 0x1e000
	s_nop 0
	v_addc_co_u32_e32 v37, vcc, 0, v17, vcc
	global_load_dword v87, v[36:37], off offset:2048
	global_load_dword v89, v[34:35], off
	global_load_dword v93, v[34:35], off offset:2048
	v_add_co_u32_e32 v34, vcc, s0, v16
	s_mov_b32 s0, 0x1d000
	s_nop 0
	v_addc_co_u32_e32 v35, vcc, 0, v17, vcc
	global_load_dword v95, v[34:35], off offset:-4096
	v_add_co_u32_e32 v36, vcc, s0, v16
	s_mov_b32 s0, 0x1f000
	s_nop 0
	v_addc_co_u32_e32 v37, vcc, 0, v17, vcc
	global_load_dword v99, v[36:37], off offset:2048
	global_load_dword v101, v[34:35], off
	global_load_dword v107, v[34:35], off offset:2048
	v_add_co_u32_e32 v16, vcc, s0, v16
	s_waitcnt vmcnt(13)
; __device__ __forceinline__ unsigned pk2(float lo, float hi) { f32x2 v = {lo, hi}; bf16x2_t b = __builtin_convertvector(v, bf16x2_t); return __builtin_bit_cast(unsigned, b); }
; __device__ __forceinline__ f32x2 ldx2(const bf16_t* p) { const unsigned w = *(const unsigned*)p; return (f32x2){__builtin_bit_cast(float, w << 16), __builtin_bit_cast(float, w & 0xffff0000u)}; }
; template <int W> __device__ __forceinline__ void pool_unit(const bf16_t* x, const LAS float* rs, f32x2 gn, bf16_t* Ag, size_t rb, int t0, int c, int g) {
;     ...
;         for (int i = 0; i < 16; ++i) hn_[i] = ldx2(x + (rb + t0 + bt * 16 + i) * 1024 + c) * rs[16 + bt * 16 + i] * gn;
; #pragma unroll
;         for (int i = 0; i < 16; ++i) { const int t = t0 + bt * 16 + i;
;             win += hn_[i]; const float inv = 1.f / (float)((t + 1) < W ? (t + 1) : W);
;             const f32x2 a = win * inv - hn_[i];
;             *(unsigned*)(Ag + ((size_t)g * MT + rb + t) * 256 + (c & 255)) = pk2(a.x, a.y);
;             win -= (i - W + 1 >= 0) ? hn_[(i - W + 1 >= 0) ? (i - W + 1) : 0] : ring[(i - W + 17) & 15]; }
	v_lshlrev_b32_e32 v46, 16, v5
	v_addc_co_u32_e32 v17, vcc, 0, v17, vcc
	global_load_dword v109, v[16:17], off
	global_load_dword v113, v[16:17], off offset:2048
	v_pk_fma_f32 v[16:17], v[2:3], v[78:79], v[32:33] neg_lo:[1,0,0] neg_hi:[1,0,0]
	ds_read_b128 v[32:35], v175 offset:256
	v_and_b32_e32 v47, 0xffff0000, v5
	s_waitcnt vmcnt(14)
	v_lshlrev_b32_e32 v64, 16, v65
	v_and_b32_e32 v65, 0xffff0000, v65
	ds_read_b128 v[36:39], v175 offset:272
	ds_read_b128 v[40:43], v175 offset:288
	ds_read_b128 v[58:61], v175 offset:304
	s_waitcnt lgkmcnt(3)
	v_pk_mul_f32 v[46:47], v[32:33], v[46:47] op_sel_hi:[0,1]
	v_pk_mul_f32 v[62:63], v[2:3], v[46:47]
	v_pk_fma_f32 v[16:17], v[2:3], v[46:47], v[16:17]
	v_pk_mul_f32 v[32:33], v[32:33], v[64:65] op_sel:[1,0]
	v_pk_fma_f32 v[46:47], v[16:17], s[30:31], v[62:63] op_sel_hi:[1,0,1] neg_lo:[0,0,1] neg_hi:[0,0,1]
	v_pk_fma_f32 v[16:17], v[2:3], v[74:75], v[16:17] neg_lo:[1,0,0] neg_hi:[1,0,0]
	v_cvt_pk_bf16_f32 v5, v46, v47
	v_or3_b32 v46, s16, 48, v14
	v_mov_b32_e32 v47, v15
	v_pk_mul_f32 v[64:65], v[2:3], v[32:33]
	v_lshlrev_b64 v[46:47], 9, v[46:47]
	v_pk_fma_f32 v[16:17], v[2:3], v[32:33], v[16:17]
	v_lshl_add_u64 v[46:47], v[8:9], 0, v[46:47]
	v_pk_fma_f32 v[32:33], v[16:17], s[30:31], v[64:65] op_sel_hi:[1,0,1] neg_lo:[0,0,1] neg_hi:[0,0,1]
	s_waitcnt vmcnt(13)
	v_lshlrev_b32_e32 v66, 16, v67
	v_and_b32_e32 v67, 0xffff0000, v67
	global_store_dword v[46:47], v5, off nt
	v_cvt_pk_bf16_f32 v5, v32, v33
	v_or3_b32 v32, s16, 49, v14
	v_mov_b32_e32 v33, v15
	v_pk_mul_f32 v[66:67], v[34:35], v[66:67] op_sel_hi:[0,1]
	v_lshlrev_b64 v[32:33], 9, v[32:33]
	v_pk_fma_f32 v[16:17], v[2:3], v[72:73], v[16:17] neg_lo:[1,0,0] neg_hi:[1,0,0]
	v_pk_mul_f32 v[68:69], v[2:3], v[66:67]
	v_lshl_add_u64 v[32:33], v[8:9], 0, v[32:33]
	v_pk_fma_f32 v[16:17], v[2:3], v[66:67], v[16:17]
	global_store_dword v[32:33], v5, off nt
	v_pk_fma_f32 v[32:33], v[16:17], s[30:31], v[68:69] op_sel_hi:[1,0,1] neg_lo:[0,0,1] neg_hi:[0,0,1]
	s_waitcnt vmcnt(14)
	v_lshlrev_b32_e32 v70, 16, v71
	v_and_b32_e32 v71, 0xffff0000, v71
	v_mov_b32_e32 v34, v35
	v_cvt_pk_bf16_f32 v5, v32, v33
	v_or3_b32 v32, s16, 50, v14
	v_mov_b32_e32 v33, v15
	v_pk_mul_f32 v[34:35], v[34:35], v[70:71] op_sel_hi:[0,1]
	v_lshlrev_b64 v[32:33], 9, v[32:33]
	v_pk_fma_f32 v[16:17], v[2:3], v[56:57], v[16:17] neg_lo:[1,0,0] neg_hi:[1,0,0]
	v_pk_mul_f32 v[70:71], v[2:3], v[34:35]
	v_lshl_add_u64 v[32:33], v[8:9], 0, v[32:33]
	v_pk_fma_f32 v[16:17], v[2:3], v[34:35], v[16:17]
	global_store_dword v[32:33], v5, off nt
	v_pk_fma_f32 v[32:33], v[16:17], s[30:31], v[70:71] op_sel_hi:[1,0,1] neg_lo:[0,0,1] neg_hi:[0,0,1]
	s_waitcnt vmcnt(14)
	v_lshlrev_b32_e32 v76, 16, v77
	v_and_b32_e32 v77, 0xffff0000, v77
	v_cvt_pk_bf16_f32 v5, v32, v33
	v_or3_b32 v32, s16, 51, v14
	v_mov_b32_e32 v33, v15
	s_waitcnt lgkmcnt(2)
	v_pk_mul_f32 v[76:77], v[36:37], v[76:77] op_sel_hi:[0,1]
	v_lshlrev_b64 v[32:33], 9, v[32:33]
	v_pk_fma_f32 v[16:17], v[2:3], v[54:55], v[16:17] neg_lo:[1,0,0] neg_hi:[1,0,0]
	v_pk_mul_f32 v[78:79], v[2:3], v[76:77]
	v_lshl_add_u64 v[32:33], v[8:9], 0, v[32:33]
	v_pk_fma_f32 v[16:17], v[2:3], v[76:77], v[16:17]
	global_store_dword v[32:33], v5, off nt
	v_pk_fma_f32 v[32:33], v[16:17], s[30:31], v[78:79] op_sel_hi:[1,0,1] neg_lo:[0,0,1] neg_hi:[0,0,1]
	s_waitcnt vmcnt(14)
	v_lshlrev_b32_e32 v80, 16, v81
	v_and_b32_e32 v81, 0xffff0000, v81
	v_cvt_pk_bf16_f32 v5, v32, v33
	v_or3_b32 v32, s16, 52, v14
	v_mov_b32_e32 v33, v15
	v_pk_mul_f32 v[36:37], v[36:37], v[80:81] op_sel:[1,0]
	v_lshlrev_b64 v[32:33], 9, v[32:33]
	v_pk_fma_f32 v[16:17], v[2:3], v[52:53], v[16:17] neg_lo:[1,0,0] neg_hi:[1,0,0]
	v_pk_mul_f32 v[80:81], v[2:3], v[36:37]
	v_lshl_add_u64 v[32:33], v[8:9], 0, v[32:33]
	v_pk_fma_f32 v[16:17], v[2:3], v[36:37], v[16:17]
	global_store_dword v[32:33], v5, off nt
	v_pk_fma_f32 v[32:33], v[16:17], s[30:31], v[80:81] op_sel_hi:[1,0,1] neg_lo:[0,0,1] neg_hi:[0,0,1]
	s_waitcnt vmcnt(14)
	v_lshlrev_b32_e32 v82, 16, v83
	v_and_b32_e32 v83, 0xffff0000, v83
	v_cvt_pk_bf16_f32 v5, v32, v33
	v_or3_b32 v32, s16, 53, v14
	v_mov_b32_e32 v33, v15
	v_pk_mul_f32 v[82:83], v[38:39], v[82:83] op_sel_hi:[0,1]
	v_lshlrev_b64 v[32:33], 9, v[32:33]
	v_pk_fma_f32 v[16:17], v[2:3], v[50:51], v[16:17] neg_lo:[1,0,0] neg_hi:[1,0,0]
	v_pk_mul_f32 v[84:85], v[2:3], v[82:83]
	v_lshl_add_u64 v[32:33], v[8:9], 0, v[32:33]
	v_pk_fma_f32 v[16:17], v[2:3], v[82:83], v[16:17]
	global_store_dword v[32:33], v5, off nt
	v_pk_fma_f32 v[32:33], v[16:17], s[30:31], v[84:85] op_sel_hi:[1,0,1] neg_lo:[0,0,1] neg_hi:[0,0,1]
	s_waitcnt vmcnt(14)
	v_lshlrev_b32_e32 v86, 16, v87
	v_and_b32_e32 v87, 0xffff0000, v87
	v_mov_b32_e32 v38, v39
	v_cvt_pk_bf16_f32 v5, v32, v33
	v_or3_b32 v32, s16, 54, v14
	v_mov_b32_e32 v33, v15
	v_pk_mul_f32 v[38:39], v[38:39], v[86:87] op_sel_hi:[0,1]
	v_lshlrev_b64 v[32:33], 9, v[32:33]
	v_pk_fma_f32 v[16:17], v[2:3], v[48:49], v[16:17] neg_lo:[1,0,0] neg_hi:[1,0,0]
	v_pk_mul_f32 v[86:87], v[2:3], v[38:39]
	v_lshl_add_u64 v[32:33], v[8:9], 0, v[32:33]
	v_pk_fma_f32 v[16:17], v[2:3], v[38:39], v[16:17]
	global_store_dword v[32:33], v5, off nt
	v_pk_fma_f32 v[32:33], v[16:17], s[30:31], v[86:87] op_sel_hi:[1,0,1] neg_lo:[0,0,1] neg_hi:[0,0,1]
	s_waitcnt vmcnt(14)
; __device__ __forceinline__ unsigned pk2(float lo, float hi) { f32x2 v = {lo, hi}; bf16x2_t b = __builtin_convertvector(v, bf16x2_t); return __builtin_bit_cast(unsigned, b); }
; template <int W> __device__ __forceinline__ void pool_unit(const bf16_t* x, const LAS float* rs, f32x2 gn, bf16_t* Ag, size_t rb, int t0, int c, int g) {
;     ...
;         for (int i = 0; i < 16; ++i) { const int t = t0 + bt * 16 + i;
;             win += hn_[i]; const float inv = 1.f / (float)((t + 1) < W ? (t + 1) : W);
;             const f32x2 a = win * inv - hn_[i];
;             *(unsigned*)(Ag + ((size_t)g * MT + rb + t) * 256 + (c & 255)) = pk2(a.x, a.y);
;             win -= (i - W + 1 >= 0) ? hn_[(i - W + 1 >= 0) ? (i - W + 1) : 0] : ring[(i - W + 17) & 15]; }
; #pragma unroll
;         for (int i = 0; i < 16; ++i) ring[i] = hn_[i];
;     }
	v_lshlrev_b32_e32 v88, 16, v89
	v_and_b32_e32 v89, 0xffff0000, v89
	v_cvt_pk_bf16_f32 v5, v32, v33
	v_or3_b32 v32, s16, 55, v14
	v_mov_b32_e32 v33, v15
	s_waitcnt lgkmcnt(1)
	v_pk_mul_f32 v[88:89], v[40:41], v[88:89] op_sel_hi:[0,1]
	v_lshlrev_b64 v[32:33], 9, v[32:33]
	v_pk_fma_f32 v[16:17], v[2:3], v[44:45], v[16:17] neg_lo:[1,0,0] neg_hi:[1,0,0]
	v_pk_mul_f32 v[90:91], v[2:3], v[88:89]
	v_lshl_add_u64 v[32:33], v[8:9], 0, v[32:33]
	v_pk_fma_f32 v[16:17], v[2:3], v[88:89], v[16:17]
	s_waitcnt vmcnt(13)
	v_lshlrev_b32_e32 v92, 16, v93
	v_and_b32_e32 v93, 0xffff0000, v93
	global_store_dword v[32:33], v5, off nt
	v_pk_fma_f32 v[32:33], v[16:17], s[30:31], v[90:91] op_sel_hi:[1,0,1] neg_lo:[0,0,1] neg_hi:[0,0,1]
	v_pk_mul_f32 v[40:41], v[40:41], v[92:93] op_sel:[1,0]
	v_cvt_pk_bf16_f32 v5, v32, v33
	v_or3_b32 v32, s16, 56, v14
	v_mov_b32_e32 v33, v15
	v_pk_fma_f32 v[16:17], v[2:3], v[30:31], v[16:17] neg_lo:[1,0,0] neg_hi:[1,0,0]
	v_pk_mul_f32 v[92:93], v[2:3], v[40:41]
	v_lshlrev_b64 v[32:33], 9, v[32:33]
	v_pk_fma_f32 v[16:17], v[2:3], v[40:41], v[16:17]
	s_waitcnt vmcnt(13)
	v_lshlrev_b32_e32 v94, 16, v95
	v_and_b32_e32 v95, 0xffff0000, v95
	v_lshl_add_u64 v[32:33], v[8:9], 0, v[32:33]
	v_pk_fma_f32 v[30:31], v[16:17], s[30:31], v[92:93] op_sel_hi:[1,0,1] neg_lo:[0,0,1] neg_hi:[0,0,1]
	v_pk_mul_f32 v[94:95], v[42:43], v[94:95] op_sel_hi:[0,1]
	global_store_dword v[32:33], v5, off nt
	v_cvt_pk_bf16_f32 v5, v30, v31
	v_or3_b32 v30, s16, 57, v14
	v_mov_b32_e32 v31, v15
	v_pk_fma_f32 v[16:17], v[2:3], v[28:29], v[16:17] neg_lo:[1,0,0] neg_hi:[1,0,0]
	v_pk_mul_f32 v[96:97], v[2:3], v[94:95]
	v_lshlrev_b64 v[30:31], 9, v[30:31]
	v_pk_fma_f32 v[16:17], v[2:3], v[94:95], v[16:17]
	s_waitcnt vmcnt(13)
	v_lshlrev_b32_e32 v98, 16, v99
	v_and_b32_e32 v99, 0xffff0000, v99
	v_mov_b32_e32 v42, v43
	v_lshl_add_u64 v[30:31], v[8:9], 0, v[30:31]
	v_pk_fma_f32 v[28:29], v[16:17], s[30:31], v[96:97] op_sel_hi:[1,0,1] neg_lo:[0,0,1] neg_hi:[0,0,1]
	v_pk_mul_f32 v[42:43], v[42:43], v[98:99] op_sel_hi:[0,1]
	global_store_dword v[30:31], v5, off nt
	v_cvt_pk_bf16_f32 v5, v28, v29
	v_or3_b32 v28, s16, 58, v14
	v_mov_b32_e32 v29, v15
	v_pk_fma_f32 v[16:17], v[2:3], v[26:27], v[16:17] neg_lo:[1,0,0] neg_hi:[1,0,0]
	v_pk_mul_f32 v[98:99], v[2:3], v[42:43]
	v_lshlrev_b64 v[28:29], 9, v[28:29]
	v_pk_fma_f32 v[16:17], v[2:3], v[42:43], v[16:17]
	s_waitcnt vmcnt(13)
	v_lshlrev_b32_e32 v100, 16, v101
	v_and_b32_e32 v101, 0xffff0000, v101
	v_lshl_add_u64 v[28:29], v[8:9], 0, v[28:29]
	v_pk_fma_f32 v[26:27], v[16:17], s[30:31], v[98:99] op_sel_hi:[1,0,1] neg_lo:[0,0,1] neg_hi:[0,0,1]
	s_waitcnt lgkmcnt(0)
	v_pk_mul_f32 v[100:101], v[58:59], v[100:101] op_sel_hi:[0,1]
	global_store_dword v[28:29], v5, off nt
	v_cvt_pk_bf16_f32 v5, v26, v27
	v_or3_b32 v26, s16, 59, v14
	v_mov_b32_e32 v27, v15
	v_pk_fma_f32 v[16:17], v[2:3], v[24:25], v[16:17] neg_lo:[1,0,0] neg_hi:[1,0,0]
	v_pk_mul_f32 v[104:105], v[2:3], v[100:101]
	v_lshlrev_b64 v[26:27], 9, v[26:27]
	v_pk_fma_f32 v[16:17], v[2:3], v[100:101], v[16:17]
	s_waitcnt vmcnt(13)
	v_lshlrev_b32_e32 v106, 16, v107
	v_and_b32_e32 v107, 0xffff0000, v107
	v_lshl_add_u64 v[26:27], v[8:9], 0, v[26:27]
	v_pk_fma_f32 v[24:25], v[16:17], s[30:31], v[104:105] op_sel_hi:[1,0,1] neg_lo:[0,0,1] neg_hi:[0,0,1]
	v_pk_mul_f32 v[58:59], v[58:59], v[106:107] op_sel:[1,0]
	global_store_dword v[26:27], v5, off nt
	v_cvt_pk_bf16_f32 v5, v24, v25
	v_or3_b32 v24, s16, 60, v14
	v_mov_b32_e32 v25, v15
	v_pk_fma_f32 v[16:17], v[2:3], v[22:23], v[16:17] neg_lo:[1,0,0] neg_hi:[1,0,0]
	v_pk_mul_f32 v[106:107], v[2:3], v[58:59]
	v_lshlrev_b64 v[24:25], 9, v[24:25]
	v_pk_fma_f32 v[16:17], v[2:3], v[58:59], v[16:17]
	s_waitcnt vmcnt(13)
	v_lshlrev_b32_e32 v108, 16, v109
	v_and_b32_e32 v109, 0xffff0000, v109
	v_lshl_add_u64 v[24:25], v[8:9], 0, v[24:25]
	v_pk_fma_f32 v[22:23], v[16:17], s[30:31], v[106:107] op_sel_hi:[1,0,1] neg_lo:[0,0,1] neg_hi:[0,0,1]
	v_pk_mul_f32 v[108:109], v[60:61], v[108:109] op_sel_hi:[0,1]
	global_store_dword v[24:25], v5, off nt
	v_cvt_pk_bf16_f32 v5, v22, v23
	v_or3_b32 v22, s16, 61, v14
	v_mov_b32_e32 v23, v15
	v_pk_fma_f32 v[16:17], v[2:3], v[20:21], v[16:17] neg_lo:[1,0,0] neg_hi:[1,0,0]
	v_pk_mul_f32 v[110:111], v[2:3], v[108:109]
	v_lshlrev_b64 v[22:23], 9, v[22:23]
	v_pk_fma_f32 v[16:17], v[2:3], v[108:109], v[16:17]
	v_lshl_add_u64 v[22:23], v[8:9], 0, v[22:23]
	v_pk_fma_f32 v[20:21], v[16:17], s[30:31], v[110:111] op_sel_hi:[1,0,1] neg_lo:[0,0,1] neg_hi:[0,0,1]
	s_waitcnt vmcnt(13)
	v_lshlrev_b32_e32 v112, 16, v113
	v_and_b32_e32 v113, 0xffff0000, v113
	v_mov_b32_e32 v60, v61
	global_store_dword v[22:23], v5, off nt
	v_cvt_pk_bf16_f32 v5, v20, v21
	v_or3_b32 v20, s16, 62, v14
	v_mov_b32_e32 v21, v15
	v_pk_mul_f32 v[60:61], v[60:61], v[112:113] op_sel_hi:[0,1]
	v_lshlrev_b64 v[20:21], 9, v[20:21]
	v_pk_fma_f32 v[16:17], v[2:3], v[18:19], v[16:17] neg_lo:[1,0,0] neg_hi:[1,0,0]
	v_pk_mul_f32 v[112:113], v[2:3], v[60:61]
	v_lshl_add_u64 v[20:21], v[8:9], 0, v[20:21]
	v_pk_fma_f32 v[16:17], v[2:3], v[60:61], v[16:17]
	global_store_dword v[20:21], v5, off nt
	v_pk_fma_f32 v[16:17], v[16:17], s[30:31], v[112:113] op_sel_hi:[1,0,1] neg_lo:[0,0,1] neg_hi:[0,0,1]
	s_or_b64 exec, exec, s[38:39]
	s_and_saveexec_b64 s[0:1], s[54:55]
	s_xor_b64 s[0:1], exec, s[0:1]
	s_cbranch_execnz .LBB0_1197
